# peer_topk layer-0: second-half fragment loads also issued up front (staged, counted vmcnt) instead of 12 load->vmcnt(0)->MFMA round trips
# speedup vs baseline: 1.0168x; 1.0060x over previous
; #define MFMA(a, b, c) __builtin_amdgcn_mfma_f32_32x32x16_bf16((a), (b), (c), 0, 0, 0)
; DI unsigned f2ord(float f) { const unsigned u = __float_as_uint(f); return (u & 0x80000000u) ? ~u : (u | 0x80000000u); }
; DI void peer_topk_phase(const bf16_t* __restrict__ qpk, const bf16_t* __restrict__ subk, int* __restrict__ eidx, float* __restrict__ gout) {
;     ...
;         for (int c = 0; c < 2; ++c) {
;             f32x16 acc[4];
; #pragma unroll
;             for (int nb = 0; nb < 4; ++nb)
; #pragma unroll
;                 for (int i = 0; i < 16; ++i) acc[nb][i] = 0.f;
;             const bf16_t* qp = qpk + (size_t)(t0 + r) * 1024 + hh * 128 + c * 64 + h * 8;
;             const bf16_t* kp = subk + ((size_t)(hh * 2 + c) * 128 + r) * 64 + h * 8;
; #pragma unroll
;             for (int ks = 0; ks < 4; ++ks) {
;                 const bf16x8 qfr = *(const bf16x8*)(qp + ks * 16);
; #pragma unroll
;                 for (int nb = 0; nb < 4; ++nb) {
;                     const bf16x8 kf = *(const bf16x8*)(kp + nb * 32 * 64 + ks * 16);
;                     acc[nb] = MFMA(kf, qfr, acc[nb]);
;                 }
;             }
;             unsigned key[64];
; #pragma unroll
;             for (int nb = 0; nb < 4; ++nb)
; #pragma unroll
;                 for (int i = 0; i < 16; ++i) {
;                     const int n = nb * 32 + (i & 3) + 8 * (i >> 2) + 4 * h;
;                     key[nb * 16 + i] = (f2ord(acc[nb][i]) & ~127u) | (unsigned)(127 - n);
;                 }
.LBB0_466:
	v_and_or_b32 v80, v154, s21, v84
	v_ashrrev_i32_e32 v81, 31, v80
	v_and_b32_e32 v156, 7, v1
	v_lshlrev_b64 v[2:3], 11, v[80:81]
	v_lshl_add_u64 v[2:3], s[40:41], 0, v[2:3]
	v_lshlrev_b32_e32 v74, 8, v156
	v_lshl_add_u64 v[2:3], v[2:3], 0, v[74:75]
	v_mov_b32_e32 v79, v75
	v_lshl_add_u64 v[66:67], v[2:3], 0, v[78:79]
	v_lshl_or_b32 v74, v156, 15, v155
	v_lshl_add_u64 v[68:69], v[76:77], 0, v[74:75]
	v_add_co_u32_e32 v72, vcc, s24, v68
	s_nop 1
	v_addc_co_u32_e32 v73, vcc, 0, v69, vcc
	v_add_co_u32_e32 v82, vcc, s25, v68
	s_nop 1
	v_addc_co_u32_e32 v83, vcc, 0, v69, vcc
	v_add_co_u32_e32 v166, vcc, s27, v68
	s_nop 1
	v_addc_co_u32_e32 v167, vcc, 0, v69, vcc
	v_add_co_u32_e32 v70, vcc, s4, v68
	s_nop 1
	v_addc_co_u32_e32 v71, vcc, 0, v69, vcc
	global_load_dwordx4 v[2:5], v[66:67], off
	global_load_dwordx4 v[6:9], v[68:69], off
	global_load_dwordx4 v[162:165], v[72:73], off
	global_load_dwordx4 v[198:201], v[82:83], off
	global_load_dwordx4 v[210:213], v[166:167], off
	global_load_dwordx4 v[158:161], v[66:67], off offset:32
	global_load_dwordx4 v[214:217], v[68:69], off offset:32
	global_load_dwordx4 v[218:221], v[72:73], off offset:32
	global_load_dwordx4 v[222:225], v[82:83], off offset:32
	global_load_dwordx4 v[226:229], v[166:167], off offset:32
	global_load_dwordx4 v[182:185], v[66:67], off offset:64
	global_load_dwordx4 v[232:235], v[68:69], off offset:64
	global_load_dwordx4 v[236:239], v[72:73], off offset:64
	global_load_dwordx4 v[240:243], v[82:83], off offset:64
	global_load_dwordx4 v[244:247], v[166:167], off offset:64
	global_load_dwordx4 v[186:189], v[66:67], off offset:96
	global_load_dwordx4 v[248:251], v[68:69], off offset:96
	s_waitcnt vmcnt(15)
	v_mfma_f32_32x32x16_bf16 v[50:65], v[6:9], v[2:5], 0
	s_waitcnt vmcnt(14)
	v_mfma_f32_32x32x16_bf16 v[34:49], v[162:165], v[2:5], 0
	s_waitcnt vmcnt(13)
	v_mfma_f32_32x32x16_bf16 v[18:33], v[198:201], v[2:5], 0
	s_waitcnt vmcnt(12)
	v_mfma_f32_32x32x16_bf16 v[2:17], v[210:213], v[2:5], 0
	global_load_dwordx4 v[162:165], v[72:73], off offset:96
	global_load_dwordx4 v[198:201], v[82:83], off offset:96
	global_load_dwordx4 v[210:213], v[166:167], off offset:96
	s_waitcnt vmcnt(13)
	v_mfma_f32_32x32x16_bf16 v[50:65], v[214:217], v[158:161], v[50:65]
	s_waitcnt vmcnt(12)
	v_mfma_f32_32x32x16_bf16 v[34:49], v[218:221], v[158:161], v[34:49]
	s_waitcnt vmcnt(11)
	v_mfma_f32_32x32x16_bf16 v[18:33], v[222:225], v[158:161], v[18:33]
	s_waitcnt vmcnt(10)
	v_mfma_f32_32x32x16_bf16 v[2:17], v[226:229], v[158:161], v[2:17]
	s_waitcnt vmcnt(8)
	v_mfma_f32_32x32x16_bf16 v[50:65], v[232:235], v[182:185], v[50:65]
	s_waitcnt vmcnt(7)
	v_mfma_f32_32x32x16_bf16 v[34:49], v[236:239], v[182:185], v[34:49]
	s_waitcnt vmcnt(6)
	v_mfma_f32_32x32x16_bf16 v[18:33], v[240:243], v[182:185], v[18:33]
	s_waitcnt vmcnt(5)
	v_mfma_f32_32x32x16_bf16 v[2:17], v[244:247], v[182:185], v[2:17]
	s_waitcnt vmcnt(3)
	v_mfma_f32_32x32x16_bf16 v[50:65], v[248:251], v[186:189], v[50:65]
	s_nop 11
	v_not_b32_e32 v72, v50
	v_or_b32_e32 v73, 0x80000000, v50
	v_cmp_gt_i32_e32 vcc, 0, v50
	s_waitcnt vmcnt(2)
	v_mfma_f32_32x32x16_bf16 v[34:49], v[162:165], v[186:189], v[34:49]
	v_cndmask_b32_e32 v50, v73, v72, vcc
	v_not_b32_e32 v72, v51
	v_or_b32_e32 v73, 0x80000000, v51
	v_cmp_gt_i32_e32 vcc, 0, v51
	v_and_or_b32 v50, v50, s42, v85
	s_nop 0
	v_cndmask_b32_e32 v51, v73, v72, vcc
	v_not_b32_e32 v72, v52
	v_or_b32_e32 v73, 0x80000000, v52
	v_cmp_gt_i32_e32 vcc, 0, v52
	v_and_or_b32 v51, v51, s42, v86
	s_waitcnt vmcnt(1)
	v_mfma_f32_32x32x16_bf16 v[18:33], v[198:201], v[186:189], v[18:33]
	v_cndmask_b32_e32 v52, v73, v72, vcc
	v_not_b32_e32 v72, v53
	v_or_b32_e32 v73, 0x80000000, v53
	v_cmp_gt_i32_e32 vcc, 0, v53
	v_and_or_b32 v52, v52, s42, v87
	s_nop 0
	v_cndmask_b32_e32 v53, v73, v72, vcc
	v_not_b32_e32 v72, v54
	v_or_b32_e32 v73, 0x80000000, v54
	v_cmp_gt_i32_e32 vcc, 0, v54
	v_and_or_b32 v53, v53, s42, v88
	s_waitcnt vmcnt(0)
	v_mfma_f32_32x32x16_bf16 v[2:17], v[210:213], v[186:189], v[2:17]
	v_cndmask_b32_e32 v54, v73, v72, vcc
	v_not_b32_e32 v72, v55
	v_or_b32_e32 v73, 0x80000000, v55
	v_cmp_gt_i32_e32 vcc, 0, v55
	v_and_or_b32 v54, v54, s42, v89
	s_nop 0
	v_cndmask_b32_e32 v55, v73, v72, vcc
	v_not_b32_e32 v72, v56
	v_or_b32_e32 v73, 0x80000000, v56
	v_cmp_gt_i32_e32 vcc, 0, v56
	v_and_or_b32 v55, v55, s42, v90
	s_nop 0
	v_cndmask_b32_e32 v56, v73, v72, vcc
	v_not_b32_e32 v72, v57
	v_or_b32_e32 v73, 0x80000000, v57
	v_cmp_gt_i32_e32 vcc, 0, v57
	v_and_or_b32 v56, v56, s42, v91
	s_nop 0
	v_cndmask_b32_e32 v57, v73, v72, vcc
	v_not_b32_e32 v72, v58
	v_or_b32_e32 v73, 0x80000000, v58
	v_cmp_gt_i32_e32 vcc, 0, v58
	v_and_or_b32 v57, v57, s42, v92
	s_nop 0
	v_cndmask_b32_e32 v58, v73, v72, vcc
	v_not_b32_e32 v72, v59
	v_or_b32_e32 v73, 0x80000000, v59
	v_cmp_gt_i32_e32 vcc, 0, v59
	v_and_or_b32 v58, v58, s42, v93
	s_nop 0
	v_cndmask_b32_e32 v59, v73, v72, vcc
	v_not_b32_e32 v72, v60
	v_or_b32_e32 v73, 0x80000000, v60
	v_cmp_gt_i32_e32 vcc, 0, v60
	v_and_or_b32 v59, v59, s42, v94
	s_nop 0
	v_cndmask_b32_e32 v60, v73, v72, vcc
	v_not_b32_e32 v72, v61
	v_or_b32_e32 v73, 0x80000000, v61
	v_cmp_gt_i32_e32 vcc, 0, v61
	v_and_or_b32 v60, v60, s42, v95
	s_nop 0
	v_cndmask_b32_e32 v61, v73, v72, vcc
	v_not_b32_e32 v72, v62
	v_or_b32_e32 v73, 0x80000000, v62
	v_cmp_gt_i32_e32 vcc, 0, v62
	v_and_or_b32 v61, v61, s42, v96
	s_nop 0
	v_cndmask_b32_e32 v62, v73, v72, vcc
	v_not_b32_e32 v72, v63
	v_or_b32_e32 v73, 0x80000000, v63
	v_cmp_gt_i32_e32 vcc, 0, v63
	v_and_or_b32 v62, v62, s42, v97
	s_nop 0
	v_cndmask_b32_e32 v63, v73, v72, vcc
	v_not_b32_e32 v72, v64
	v_or_b32_e32 v73, 0x80000000, v64
	v_cmp_gt_i32_e32 vcc, 0, v64
; DI unsigned f2ord(float f) { const unsigned u = __float_as_uint(f); return (u & 0x80000000u) ? ~u : (u | 0x80000000u); }
; DI void peer_topk_phase(const bf16_t* __restrict__ qpk, const bf16_t* __restrict__ subk, int* __restrict__ eidx, float* __restrict__ gout) {
;     ...
; #pragma unroll
;             for (int nb = 0; nb < 4; ++nb)
; #pragma unroll
;                 for (int i = 0; i < 16; ++i) {
;                     const int n = nb * 32 + (i & 3) + 8 * (i >> 2) + 4 * h;
;                     key[nb * 16 + i] = (f2ord(acc[nb][i]) & ~127u) | (unsigned)(127 - n);
;                 }
	v_and_or_b32 v63, v63, s42, v98
	s_nop 0
	v_cndmask_b32_e32 v64, v73, v72, vcc
	v_not_b32_e32 v72, v65
	v_or_b32_e32 v73, 0x80000000, v65
	v_cmp_gt_i32_e32 vcc, 0, v65
	v_and_or_b32 v64, v64, s42, v99
	s_nop 0
	v_cndmask_b32_e32 v65, v73, v72, vcc
	v_not_b32_e32 v72, v34
	v_or_b32_e32 v73, 0x80000000, v34
	v_cmp_gt_i32_e32 vcc, 0, v34
	v_and_or_b32 v65, v65, s42, v100
	s_nop 0
	v_cndmask_b32_e32 v34, v73, v72, vcc
	v_not_b32_e32 v72, v35
	v_or_b32_e32 v73, 0x80000000, v35
	v_cmp_gt_i32_e32 vcc, 0, v35
	v_and_or_b32 v34, v34, s42, v101
	s_nop 0
	v_cndmask_b32_e32 v35, v73, v72, vcc
	v_not_b32_e32 v72, v36
	v_or_b32_e32 v73, 0x80000000, v36
	v_cmp_gt_i32_e32 vcc, 0, v36
	v_and_or_b32 v35, v35, s42, v102
	s_nop 0
	v_cndmask_b32_e32 v36, v73, v72, vcc
	v_not_b32_e32 v72, v37
	v_or_b32_e32 v73, 0x80000000, v37
	v_cmp_gt_i32_e32 vcc, 0, v37
	v_and_or_b32 v36, v36, s42, v103
	s_nop 0
	v_cndmask_b32_e32 v37, v73, v72, vcc
	v_not_b32_e32 v72, v38
	v_or_b32_e32 v73, 0x80000000, v38
	v_cmp_gt_i32_e32 vcc, 0, v38
	v_and_or_b32 v37, v37, s42, v104
	s_nop 0
	v_cndmask_b32_e32 v38, v73, v72, vcc
	v_not_b32_e32 v72, v39
	v_or_b32_e32 v73, 0x80000000, v39
	v_cmp_gt_i32_e32 vcc, 0, v39
	v_and_or_b32 v38, v38, s42, v105
	s_nop 0
	v_cndmask_b32_e32 v39, v73, v72, vcc
	v_not_b32_e32 v72, v40
	v_or_b32_e32 v73, 0x80000000, v40
	v_cmp_gt_i32_e32 vcc, 0, v40
	v_and_or_b32 v39, v39, s42, v106
	s_nop 0
	v_cndmask_b32_e32 v40, v73, v72, vcc
	v_not_b32_e32 v72, v41
	v_or_b32_e32 v73, 0x80000000, v41
	v_cmp_gt_i32_e32 vcc, 0, v41
	v_and_or_b32 v40, v40, s42, v107
	s_nop 0
	v_cndmask_b32_e32 v41, v73, v72, vcc
	v_not_b32_e32 v72, v42
	v_or_b32_e32 v73, 0x80000000, v42
	v_cmp_gt_i32_e32 vcc, 0, v42
	v_and_or_b32 v41, v41, s42, v108
	s_nop 0
	v_cndmask_b32_e32 v42, v73, v72, vcc
	v_not_b32_e32 v72, v43
	v_or_b32_e32 v73, 0x80000000, v43
	v_cmp_gt_i32_e32 vcc, 0, v43
	v_and_or_b32 v42, v42, s42, v109
	s_nop 0
	v_cndmask_b32_e32 v43, v73, v72, vcc
	v_not_b32_e32 v72, v44
	v_or_b32_e32 v73, 0x80000000, v44
	v_cmp_gt_i32_e32 vcc, 0, v44
	v_and_or_b32 v43, v43, s42, v110
	s_nop 0
	v_cndmask_b32_e32 v44, v73, v72, vcc
	v_not_b32_e32 v72, v45
	v_or_b32_e32 v73, 0x80000000, v45
	v_cmp_gt_i32_e32 vcc, 0, v45
	v_and_or_b32 v44, v44, s42, v111
	s_nop 0
	v_cndmask_b32_e32 v45, v73, v72, vcc
	v_not_b32_e32 v72, v46
	v_or_b32_e32 v73, 0x80000000, v46
	v_cmp_gt_i32_e32 vcc, 0, v46
	v_and_or_b32 v45, v45, s42, v112
	s_nop 0
	v_cndmask_b32_e32 v46, v73, v72, vcc
	v_not_b32_e32 v72, v47
	v_or_b32_e32 v73, 0x80000000, v47
	v_cmp_gt_i32_e32 vcc, 0, v47
	v_and_or_b32 v46, v46, s42, v113
	s_nop 0
	v_cndmask_b32_e32 v47, v73, v72, vcc
	v_not_b32_e32 v72, v48
	v_or_b32_e32 v73, 0x80000000, v48
	v_cmp_gt_i32_e32 vcc, 0, v48
	v_and_or_b32 v47, v47, s42, v114
	s_nop 0
	v_cndmask_b32_e32 v48, v73, v72, vcc
	v_not_b32_e32 v72, v49
	v_or_b32_e32 v73, 0x80000000, v49
	v_cmp_gt_i32_e32 vcc, 0, v49
	v_and_or_b32 v48, v48, s42, v115
	s_nop 0
	v_cndmask_b32_e32 v49, v73, v72, vcc
	v_not_b32_e32 v72, v18
	v_or_b32_e32 v73, 0x80000000, v18
	v_cmp_gt_i32_e32 vcc, 0, v18
	v_and_or_b32 v49, v49, s42, v116
	s_nop 0
	v_cndmask_b32_e32 v18, v73, v72, vcc
	v_not_b32_e32 v72, v19
	v_or_b32_e32 v73, 0x80000000, v19
	v_cmp_gt_i32_e32 vcc, 0, v19
	v_and_or_b32 v18, v18, s42, v117
	s_nop 0
	v_cndmask_b32_e32 v19, v73, v72, vcc
	v_not_b32_e32 v72, v20
	v_or_b32_e32 v73, 0x80000000, v20
	v_cmp_gt_i32_e32 vcc, 0, v20
	v_and_or_b32 v19, v19, s42, v118
	s_nop 0
	v_cndmask_b32_e32 v20, v73, v72, vcc
	v_not_b32_e32 v72, v21
	v_or_b32_e32 v73, 0x80000000, v21
	v_cmp_gt_i32_e32 vcc, 0, v21
	v_and_or_b32 v20, v20, s42, v119
	s_nop 0
	v_cndmask_b32_e32 v21, v73, v72, vcc
	v_not_b32_e32 v72, v22
	v_or_b32_e32 v73, 0x80000000, v22
	v_cmp_gt_i32_e32 vcc, 0, v22
	v_and_or_b32 v21, v21, s42, v120
	s_nop 0
	v_cndmask_b32_e32 v22, v73, v72, vcc
	v_not_b32_e32 v72, v23
	v_or_b32_e32 v73, 0x80000000, v23
	v_cmp_gt_i32_e32 vcc, 0, v23
	v_and_or_b32 v22, v22, s42, v121
	s_nop 0
	v_cndmask_b32_e32 v23, v73, v72, vcc
	v_not_b32_e32 v72, v24
	v_or_b32_e32 v73, 0x80000000, v24
	v_cmp_gt_i32_e32 vcc, 0, v24
	v_and_or_b32 v23, v23, s42, v122
	s_nop 0
	v_cndmask_b32_e32 v24, v73, v72, vcc
	v_not_b32_e32 v72, v25
	v_or_b32_e32 v73, 0x80000000, v25
	v_cmp_gt_i32_e32 vcc, 0, v25
	v_and_or_b32 v24, v24, s42, v123
	s_nop 0
	v_cndmask_b32_e32 v25, v73, v72, vcc
	v_not_b32_e32 v72, v26
	v_or_b32_e32 v73, 0x80000000, v26
	v_cmp_gt_i32_e32 vcc, 0, v26
	v_and_or_b32 v25, v25, s42, v124
	s_nop 0
	v_cndmask_b32_e32 v26, v73, v72, vcc
	v_not_b32_e32 v72, v27
	v_or_b32_e32 v73, 0x80000000, v27
	v_cmp_gt_i32_e32 vcc, 0, v27
	v_and_or_b32 v26, v26, s42, v125
	s_nop 0
	v_cndmask_b32_e32 v27, v73, v72, vcc
	v_not_b32_e32 v72, v28
	v_or_b32_e32 v73, 0x80000000, v28
	v_cmp_gt_i32_e32 vcc, 0, v28
	v_and_or_b32 v27, v27, s42, v126
	s_nop 0
	v_cndmask_b32_e32 v28, v73, v72, vcc
	v_not_b32_e32 v72, v29
	v_or_b32_e32 v73, 0x80000000, v29
	v_cmp_gt_i32_e32 vcc, 0, v29
	v_and_or_b32 v28, v28, s42, v127
	s_nop 0
	v_cndmask_b32_e32 v29, v73, v72, vcc
	v_not_b32_e32 v72, v30
	v_or_b32_e32 v73, 0x80000000, v30
	v_cmp_gt_i32_e32 vcc, 0, v30
	v_and_or_b32 v29, v29, s42, v128
	s_nop 0
	v_cndmask_b32_e32 v30, v73, v72, vcc
	v_not_b32_e32 v72, v31
	v_or_b32_e32 v73, 0x80000000, v31
	v_cmp_gt_i32_e32 vcc, 0, v31
	v_and_or_b32 v30, v30, s42, v129
	s_nop 0
	v_cndmask_b32_e32 v31, v73, v72, vcc
	v_not_b32_e32 v72, v32
	v_or_b32_e32 v73, 0x80000000, v32
	v_cmp_gt_i32_e32 vcc, 0, v32
	v_and_or_b32 v31, v31, s42, v130
	s_nop 0
	v_cndmask_b32_e32 v32, v73, v72, vcc
	v_not_b32_e32 v72, v33
	v_or_b32_e32 v73, 0x80000000, v33
	v_cmp_gt_i32_e32 vcc, 0, v33
	v_and_or_b32 v32, v32, s42, v131
; DI unsigned f2ord(float f) { const unsigned u = __float_as_uint(f); return (u & 0x80000000u) ? ~u : (u | 0x80000000u); }
; DI void peer_topk_phase(const bf16_t* __restrict__ qpk, const bf16_t* __restrict__ subk, int* __restrict__ eidx, float* __restrict__ gout) {
;     ...
;                     const int n = nb * 32 + (i & 3) + 8 * (i >> 2) + 4 * h;
;                     key[nb * 16 + i] = (f2ord(acc[nb][i]) & ~127u) | (unsigned)(127 - n);
;                 }
;             unsigned g0[16], g1[16], g2[16], g3[16];
; #pragma unroll
;             for (int i = 0; i < 16; ++i) { g0[i] = key[i]; g1[i] = key[16 + i]; g2[i] = key[32 + i]; g3[i] = key[48 + i]; }
; #pragma unroll
;             for (int n = 0; n < 63; ++n) { cex(g0[SORT16[n][0]], g0[SORT16[n][1]]); cex(g1[SORT16[n][0]], g1[SORT16[n][1]]); cex(g2[SORT16[n][0]], g2[SORT16[n][1]]); cex(g3[SORT16[n][0]], g3[SORT16[n][1]]); }
	s_nop 0
	v_cndmask_b32_e32 v33, v73, v72, vcc
	v_not_b32_e32 v72, v2
	v_or_b32_e32 v73, 0x80000000, v2
	v_cmp_gt_i32_e32 vcc, 0, v2
	v_and_or_b32 v33, v33, s42, v132
	s_nop 0
	v_cndmask_b32_e32 v2, v73, v72, vcc
	v_not_b32_e32 v72, v3
	v_or_b32_e32 v73, 0x80000000, v3
	v_cmp_gt_i32_e32 vcc, 0, v3
	v_and_or_b32 v2, v2, s42, v133
	s_nop 0
	v_cndmask_b32_e32 v3, v73, v72, vcc
	v_not_b32_e32 v72, v4
	v_or_b32_e32 v73, 0x80000000, v4
	v_cmp_gt_i32_e32 vcc, 0, v4
	v_and_or_b32 v3, v3, s42, v134
	s_nop 0
	v_cndmask_b32_e32 v4, v73, v72, vcc
	v_not_b32_e32 v72, v5
	v_or_b32_e32 v73, 0x80000000, v5
	v_cmp_gt_i32_e32 vcc, 0, v5
	v_and_or_b32 v4, v4, s42, v135
	s_nop 0
	v_cndmask_b32_e32 v5, v73, v72, vcc
	v_not_b32_e32 v72, v6
	v_or_b32_e32 v73, 0x80000000, v6
	v_cmp_gt_i32_e32 vcc, 0, v6
	v_and_or_b32 v5, v5, s42, v136
	s_nop 0
	v_cndmask_b32_e32 v6, v73, v72, vcc
	v_not_b32_e32 v72, v7
	v_or_b32_e32 v73, 0x80000000, v7
	v_cmp_gt_i32_e32 vcc, 0, v7
	v_and_or_b32 v6, v6, s42, v137
	s_nop 0
	v_cndmask_b32_e32 v7, v73, v72, vcc
	v_not_b32_e32 v72, v8
	v_or_b32_e32 v73, 0x80000000, v8
	v_cmp_gt_i32_e32 vcc, 0, v8
	v_and_or_b32 v7, v7, s42, v138
	s_nop 0
	v_cndmask_b32_e32 v8, v73, v72, vcc
	v_not_b32_e32 v72, v9
	v_or_b32_e32 v73, 0x80000000, v9
	v_cmp_gt_i32_e32 vcc, 0, v9
	v_and_or_b32 v8, v8, s42, v139
	s_nop 0
	v_cndmask_b32_e32 v9, v73, v72, vcc
	v_not_b32_e32 v72, v10
	v_or_b32_e32 v73, 0x80000000, v10
	v_cmp_gt_i32_e32 vcc, 0, v10
	v_and_or_b32 v9, v9, s42, v140
	s_nop 0
	v_cndmask_b32_e32 v10, v73, v72, vcc
	v_not_b32_e32 v72, v11
	v_or_b32_e32 v73, 0x80000000, v11
	v_cmp_gt_i32_e32 vcc, 0, v11
	v_and_or_b32 v10, v10, s42, v141
	s_nop 0
	v_cndmask_b32_e32 v11, v73, v72, vcc
	v_not_b32_e32 v72, v12
	v_or_b32_e32 v73, 0x80000000, v12
	v_cmp_gt_i32_e32 vcc, 0, v12
	v_and_or_b32 v11, v11, s42, v142
	s_nop 0
	v_cndmask_b32_e32 v12, v73, v72, vcc
	v_not_b32_e32 v72, v13
	v_or_b32_e32 v73, 0x80000000, v13
	v_cmp_gt_i32_e32 vcc, 0, v13
	v_and_or_b32 v12, v12, s42, v143
	s_nop 0
	v_cndmask_b32_e32 v13, v73, v72, vcc
	v_not_b32_e32 v72, v14
	v_or_b32_e32 v73, 0x80000000, v14
	v_cmp_gt_i32_e32 vcc, 0, v14
	v_and_or_b32 v13, v13, s42, v144
	s_nop 0
	v_cndmask_b32_e32 v14, v73, v72, vcc
	v_not_b32_e32 v72, v15
	v_or_b32_e32 v73, 0x80000000, v15
	v_cmp_gt_i32_e32 vcc, 0, v15
	v_and_or_b32 v14, v14, s42, v145
	s_nop 0
	v_cndmask_b32_e32 v15, v73, v72, vcc
	v_not_b32_e32 v72, v16
	v_or_b32_e32 v73, 0x80000000, v16
	v_cmp_gt_i32_e32 vcc, 0, v16
	v_and_or_b32 v15, v15, s42, v149
	s_nop 0
	v_cndmask_b32_e32 v16, v73, v72, vcc
	v_not_b32_e32 v72, v17
	v_or_b32_e32 v73, 0x80000000, v17
	v_cmp_gt_i32_e32 vcc, 0, v17
	v_and_or_b32 v16, v16, s42, v152
	s_nop 0
	v_cndmask_b32_e32 v17, v73, v72, vcc
	v_max_u32_e32 v72, v50, v51
	v_min_u32_e32 v50, v50, v51
	v_max_u32_e32 v51, v34, v35
	v_min_u32_e32 v34, v34, v35
	v_max_u32_e32 v35, v18, v19
	v_min_u32_e32 v18, v18, v19
	v_max_u32_e32 v19, v2, v3
	v_min_u32_e32 v2, v2, v3
	v_max_u32_e32 v3, v52, v53
	v_min_u32_e32 v52, v52, v53
	v_max_u32_e32 v53, v36, v37
	v_min_u32_e32 v36, v36, v37
	v_max_u32_e32 v37, v20, v21
	v_min_u32_e32 v20, v20, v21
	v_max_u32_e32 v21, v4, v5
	v_min_u32_e32 v4, v4, v5
	v_max_u32_e32 v5, v72, v3
	v_min_u32_e32 v3, v72, v3
	v_max_u32_e32 v72, v51, v53
	v_min_u32_e32 v51, v51, v53
	v_max_u32_e32 v53, v35, v37
	v_min_u32_e32 v35, v35, v37
	v_max_u32_e32 v37, v19, v21
	v_min_u32_e32 v19, v19, v21
	v_max_u32_e32 v21, v50, v52
	v_min_u32_e32 v50, v50, v52
	v_max_u32_e32 v52, v34, v36
	v_min_u32_e32 v34, v34, v36
	v_max_u32_e32 v36, v18, v20
	v_min_u32_e32 v18, v18, v20
	v_max_u32_e32 v20, v2, v4
	v_min_u32_e32 v2, v2, v4
	v_max_u32_e32 v4, v21, v3
	v_min_u32_e32 v3, v21, v3
	v_max_u32_e32 v21, v52, v51
	v_min_u32_e32 v51, v52, v51
	v_max_u32_e32 v52, v36, v35
	v_min_u32_e32 v35, v36, v35
	v_max_u32_e32 v36, v20, v19
	v_min_u32_e32 v19, v20, v19
	v_max_u32_e32 v20, v54, v55
	v_min_u32_e32 v54, v54, v55
	v_max_u32_e32 v55, v38, v39
	v_min_u32_e32 v38, v38, v39
	v_max_u32_e32 v39, v22, v23
	v_min_u32_e32 v22, v22, v23
	v_max_u32_e32 v23, v6, v7
	v_min_u32_e32 v6, v6, v7
	v_max_u32_e32 v7, v56, v57
	v_min_u32_e32 v56, v56, v57
	v_max_u32_e32 v57, v40, v41
	v_min_u32_e32 v40, v40, v41
	v_max_u32_e32 v41, v24, v25
	v_min_u32_e32 v24, v24, v25
	v_max_u32_e32 v25, v8, v9
	v_min_u32_e32 v8, v8, v9
	v_max_u32_e32 v9, v20, v7
	v_min_u32_e32 v7, v20, v7
	v_max_u32_e32 v20, v55, v57
	v_min_u32_e32 v55, v55, v57
	v_max_u32_e32 v57, v39, v41
	v_min_u32_e32 v39, v39, v41
	v_max_u32_e32 v41, v23, v25
	v_min_u32_e32 v23, v23, v25
	v_max_u32_e32 v25, v54, v56
	v_min_u32_e32 v54, v54, v56
	v_max_u32_e32 v56, v38, v40
	v_min_u32_e32 v38, v38, v40
	v_max_u32_e32 v40, v22, v24
	v_min_u32_e32 v22, v22, v24
	v_max_u32_e32 v24, v6, v8
	v_min_u32_e32 v6, v6, v8
	v_max_u32_e32 v8, v25, v7
	v_min_u32_e32 v7, v25, v7
	v_max_u32_e32 v25, v56, v55
	v_min_u32_e32 v55, v56, v55
	v_max_u32_e32 v56, v40, v39
	v_min_u32_e32 v39, v40, v39
	v_max_u32_e32 v40, v24, v23
	v_min_u32_e32 v23, v24, v23
	v_max_u32_e32 v24, v5, v9
	v_min_u32_e32 v5, v5, v9
	v_max_u32_e32 v9, v72, v20
	v_min_u32_e32 v20, v72, v20
	v_max_u32_e32 v72, v53, v57
	v_min_u32_e32 v53, v53, v57
	v_max_u32_e32 v57, v37, v41
	v_min_u32_e32 v37, v37, v41
	v_max_u32_e32 v41, v3, v7
	v_min_u32_e32 v3, v3, v7
	v_max_u32_e32 v7, v51, v55
	v_min_u32_e32 v51, v51, v55
	v_max_u32_e32 v55, v35, v39
	v_min_u32_e32 v35, v35, v39
	v_max_u32_e32 v39, v19, v23
	v_min_u32_e32 v19, v19, v23
	v_max_u32_e32 v23, v41, v5
	v_min_u32_e32 v5, v41, v5
	v_max_u32_e32 v41, v7, v20
	v_min_u32_e32 v7, v7, v20
	v_max_u32_e32 v20, v55, v53
	v_min_u32_e32 v53, v55, v53
	v_max_u32_e32 v55, v39, v37
; DI void peer_topk_phase(const bf16_t* __restrict__ qpk, const bf16_t* __restrict__ subk, int* __restrict__ eidx, float* __restrict__ gout) {
;     ...
;             for (int n = 0; n < 63; ++n) { cex(g0[SORT16[n][0]], g0[SORT16[n][1]]); cex(g1[SORT16[n][0]], g1[SORT16[n][1]]); cex(g2[SORT16[n][0]], g2[SORT16[n][1]]); cex(g3[SORT16[n][0]], g3[SORT16[n][1]]); }
	v_min_u32_e32 v37, v39, v37
	v_max_u32_e32 v39, v4, v8
	v_min_u32_e32 v4, v4, v8
	v_max_u32_e32 v8, v21, v25
	v_min_u32_e32 v21, v21, v25
	v_max_u32_e32 v25, v52, v56
	v_min_u32_e32 v52, v52, v56
	v_max_u32_e32 v56, v36, v40
	v_min_u32_e32 v36, v36, v40
	v_max_u32_e32 v40, v50, v54
	v_min_u32_e32 v50, v50, v54
	v_max_u32_e32 v54, v34, v38
	v_min_u32_e32 v34, v34, v38
	v_max_u32_e32 v38, v18, v22
	v_min_u32_e32 v18, v18, v22
	v_max_u32_e32 v22, v2, v6
	v_min_u32_e32 v2, v2, v6
	v_max_u32_e32 v6, v40, v4
	v_min_u32_e32 v4, v40, v4
	v_max_u32_e32 v40, v54, v21
	v_min_u32_e32 v21, v54, v21
	v_max_u32_e32 v54, v38, v52
	v_min_u32_e32 v38, v38, v52
	v_max_u32_e32 v52, v22, v36
	v_min_u32_e32 v22, v22, v36
	v_max_u32_e32 v36, v39, v23
	v_min_u32_e32 v23, v39, v23
	v_max_u32_e32 v39, v8, v41
	v_min_u32_e32 v8, v8, v41
	v_max_u32_e32 v41, v25, v20
	v_min_u32_e32 v20, v25, v20
	v_max_u32_e32 v25, v56, v55
	v_min_u32_e32 v55, v56, v55
	v_max_u32_e32 v56, v6, v5
	v_min_u32_e32 v5, v6, v5
	v_max_u32_e32 v6, v40, v7
	v_min_u32_e32 v7, v40, v7
	v_max_u32_e32 v40, v54, v53
	v_min_u32_e32 v53, v54, v53
	v_max_u32_e32 v54, v52, v37
	v_min_u32_e32 v37, v52, v37
	v_max_u32_e32 v52, v4, v3
	v_min_u32_e32 v3, v4, v3
	v_max_u32_e32 v4, v21, v51
	v_min_u32_e32 v21, v21, v51
	v_max_u32_e32 v51, v38, v35
	v_min_u32_e32 v35, v38, v35
	v_max_u32_e32 v38, v22, v19
	v_min_u32_e32 v19, v22, v19
	v_max_u32_e32 v22, v58, v59
	v_min_u32_e32 v58, v58, v59
	v_max_u32_e32 v59, v42, v43
	v_min_u32_e32 v42, v42, v43
	v_max_u32_e32 v43, v26, v27
	v_min_u32_e32 v26, v26, v27
	v_max_u32_e32 v27, v10, v11
	v_min_u32_e32 v10, v10, v11
	v_max_u32_e32 v11, v60, v61
	v_min_u32_e32 v60, v60, v61
	v_max_u32_e32 v61, v44, v45
	v_min_u32_e32 v44, v44, v45
	v_max_u32_e32 v45, v28, v29
	v_min_u32_e32 v28, v28, v29
	v_max_u32_e32 v29, v12, v13
	v_min_u32_e32 v12, v12, v13
	v_and_or_b32 v17, v17, s42, v153
	v_max_u32_e32 v13, v22, v11
	v_min_u32_e32 v11, v22, v11
	v_max_u32_e32 v22, v59, v61
	v_min_u32_e32 v59, v59, v61
	v_max_u32_e32 v61, v43, v45
	v_min_u32_e32 v43, v43, v45
	v_max_u32_e32 v45, v27, v29
	v_min_u32_e32 v27, v27, v29
	v_max_u32_e32 v29, v58, v60
	v_min_u32_e32 v58, v58, v60
	v_max_u32_e32 v60, v42, v44
	v_min_u32_e32 v42, v42, v44
	v_max_u32_e32 v44, v26, v28
	v_min_u32_e32 v26, v26, v28
	v_max_u32_e32 v28, v10, v12
	v_min_u32_e32 v10, v10, v12
	v_max_u32_e32 v12, v29, v11
	v_min_u32_e32 v11, v29, v11
	v_max_u32_e32 v29, v60, v59
	v_min_u32_e32 v59, v60, v59
	v_max_u32_e32 v60, v44, v43
	v_min_u32_e32 v43, v44, v43
	v_max_u32_e32 v44, v28, v27
	v_min_u32_e32 v27, v28, v27
	v_max_u32_e32 v28, v62, v63
	v_min_u32_e32 v62, v62, v63
	v_max_u32_e32 v63, v46, v47
	v_min_u32_e32 v46, v46, v47
	v_max_u32_e32 v47, v30, v31
	v_min_u32_e32 v30, v30, v31
	v_max_u32_e32 v31, v14, v15
	v_min_u32_e32 v14, v14, v15
	v_max_u32_e32 v15, v64, v65
	v_min_u32_e32 v64, v64, v65
	v_max_u32_e32 v65, v48, v49
	v_min_u32_e32 v48, v48, v49
	v_max_u32_e32 v49, v32, v33
	v_min_u32_e32 v32, v32, v33
	v_max_u32_e32 v33, v16, v17
	v_min_u32_e32 v16, v16, v17
	v_max_u32_e32 v17, v28, v15
	v_min_u32_e32 v15, v28, v15
	v_max_u32_e32 v28, v63, v65
	v_min_u32_e32 v63, v63, v65
	v_max_u32_e32 v65, v47, v49
	v_min_u32_e32 v47, v47, v49
	v_max_u32_e32 v49, v31, v33
	v_min_u32_e32 v31, v31, v33
	v_max_u32_e32 v33, v62, v64
	v_min_u32_e32 v62, v62, v64
	v_max_u32_e32 v64, v46, v48
	v_min_u32_e32 v46, v46, v48
	v_max_u32_e32 v48, v30, v32
	v_min_u32_e32 v30, v30, v32
	v_max_u32_e32 v32, v14, v16
	v_min_u32_e32 v14, v14, v16
	v_max_u32_e32 v16, v33, v15
	v_min_u32_e32 v15, v33, v15
	v_max_u32_e32 v33, v64, v63
	v_min_u32_e32 v63, v64, v63
	v_max_u32_e32 v64, v48, v47
	v_min_u32_e32 v47, v48, v47
	v_max_u32_e32 v48, v32, v31
	v_min_u32_e32 v31, v32, v31
	v_max_u32_e32 v32, v13, v17
	v_min_u32_e32 v13, v13, v17
	v_max_u32_e32 v17, v22, v28
	v_min_u32_e32 v22, v22, v28
	v_max_u32_e32 v28, v61, v65
	v_min_u32_e32 v61, v61, v65
	v_max_u32_e32 v65, v45, v49
	v_min_u32_e32 v45, v45, v49
	v_max_u32_e32 v49, v11, v15
	v_min_u32_e32 v11, v11, v15
	v_max_u32_e32 v15, v59, v63
	v_min_u32_e32 v59, v59, v63
	v_max_u32_e32 v63, v43, v47
	v_min_u32_e32 v43, v43, v47
	v_max_u32_e32 v47, v27, v31
	v_min_u32_e32 v27, v27, v31
	v_max_u32_e32 v31, v49, v13
	v_min_u32_e32 v13, v49, v13
	v_max_u32_e32 v49, v15, v22
	v_min_u32_e32 v15, v15, v22
	v_max_u32_e32 v22, v63, v61
	v_min_u32_e32 v61, v63, v61
	v_max_u32_e32 v63, v47, v45
	v_min_u32_e32 v45, v47, v45
	v_max_u32_e32 v47, v12, v16
	v_min_u32_e32 v12, v12, v16
	v_max_u32_e32 v16, v29, v33
	v_min_u32_e32 v29, v29, v33
	v_max_u32_e32 v33, v60, v64
	v_min_u32_e32 v60, v60, v64
	v_max_u32_e32 v64, v44, v48
	v_min_u32_e32 v44, v44, v48
	v_max_u32_e32 v48, v58, v62
	v_min_u32_e32 v58, v58, v62
	v_max_u32_e32 v62, v42, v46
	v_min_u32_e32 v42, v42, v46
	v_max_u32_e32 v46, v26, v30
	v_min_u32_e32 v26, v26, v30
	v_max_u32_e32 v30, v10, v14
	v_min_u32_e32 v10, v10, v14
	v_max_u32_e32 v14, v48, v12
	v_min_u32_e32 v12, v48, v12
	v_max_u32_e32 v48, v62, v29
	v_min_u32_e32 v29, v62, v29
	v_max_u32_e32 v62, v46, v60
	v_min_u32_e32 v46, v46, v60
	v_max_u32_e32 v60, v30, v44
	v_min_u32_e32 v30, v30, v44
	v_max_u32_e32 v44, v47, v31
	v_min_u32_e32 v31, v47, v31
	v_max_u32_e32 v47, v16, v49
	v_min_u32_e32 v16, v16, v49
	v_max_u32_e32 v49, v33, v22
	v_min_u32_e32 v22, v33, v22
	v_max_u32_e32 v33, v64, v63
	v_min_u32_e32 v63, v64, v63
	v_max_u32_e32 v64, v14, v13
	v_min_u32_e32 v13, v14, v13
	v_max_u32_e32 v14, v48, v15
	v_min_u32_e32 v15, v48, v15
	v_max_u32_e32 v48, v62, v61
	v_min_u32_e32 v61, v62, v61
	v_max_u32_e32 v62, v60, v45
	v_min_u32_e32 v45, v60, v45
	v_max_u32_e32 v60, v12, v11
; DI void merge_top16(unsigned (&A)[16], const unsigned (&B)[16]) {
; #pragma unroll
;     for (int i = 0; i < 16; ++i) A[i] = max(A[i], B[15 - i]);
; #pragma unroll
;     for (int n = 0; n < 32; ++n) cex(A[BMERGE16[n][0]], A[BMERGE16[n][1]]);
; }
; DI void peer_topk_phase(const bf16_t* __restrict__ qpk, const bf16_t* __restrict__ subk, int* __restrict__ eidx, float* __restrict__ gout) {
;     ...
;             for (int n = 0; n < 63; ++n) { cex(g0[SORT16[n][0]], g0[SORT16[n][1]]); cex(g1[SORT16[n][0]], g1[SORT16[n][1]]); cex(g2[SORT16[n][0]], g2[SORT16[n][1]]); cex(g3[SORT16[n][0]], g3[SORT16[n][1]]); }
;             merge_top16(g0, g1); merge_top16(g2, g3); merge_top16(g0, g2);
	v_min_u32_e32 v11, v12, v11
	v_max_u32_e32 v12, v29, v59
	v_min_u32_e32 v29, v29, v59
	v_max_u32_e32 v59, v46, v43
	v_min_u32_e32 v43, v46, v43
	v_max_u32_e32 v46, v30, v27
	v_min_u32_e32 v27, v30, v27
	v_min_u32_e32 v30, v24, v32
	v_min_u32_e32 v73, v9, v17
	v_min_u32_e32 v74, v72, v28
	v_min_u32_e32 v79, v57, v65
	v_max_u32_e32 v82, v5, v13
	v_min_u32_e32 v5, v5, v13
	v_max_u32_e32 v13, v7, v15
	v_min_u32_e32 v7, v7, v15
	v_max_u32_e32 v15, v53, v61
	v_min_u32_e32 v53, v53, v61
	v_max_u32_e32 v61, v37, v45
	v_min_u32_e32 v37, v37, v45
	v_max_u32_e32 v45, v82, v30
	v_min_u32_e32 v30, v82, v30
	v_max_u32_e32 v82, v13, v73
	v_min_u32_e32 v13, v13, v73
	v_max_u32_e32 v73, v15, v74
	v_min_u32_e32 v15, v15, v74
	v_max_u32_e32 v74, v61, v79
	v_min_u32_e32 v61, v61, v79
	v_max_u32_e32 v79, v23, v31
	v_min_u32_e32 v23, v23, v31
	v_max_u32_e32 v31, v8, v16
	v_min_u32_e32 v8, v8, v16
	v_max_u32_e32 v16, v20, v22
	v_min_u32_e32 v20, v20, v22
	v_max_u32_e32 v22, v55, v63
	v_min_u32_e32 v55, v55, v63
	v_max_u32_e32 v63, v3, v11
	v_min_u32_e32 v3, v3, v11
	v_max_u32_e32 v11, v21, v29
	v_min_u32_e32 v21, v21, v29
	v_max_u32_e32 v29, v35, v43
	v_min_u32_e32 v35, v35, v43
	v_max_u32_e32 v43, v19, v27
	v_min_u32_e32 v19, v19, v27
	v_max_u32_e32 v27, v63, v23
	v_min_u32_e32 v23, v63, v23
	v_max_u32_e32 v63, v11, v8
	v_min_u32_e32 v8, v11, v8
	v_max_u32_e32 v11, v29, v20
	v_min_u32_e32 v20, v29, v20
	v_max_u32_e32 v29, v43, v55
	v_min_u32_e32 v43, v43, v55
	v_max_u32_e32 v55, v79, v45
	v_min_u32_e32 v45, v79, v45
	v_max_u32_e32 v79, v31, v82
	v_min_u32_e32 v31, v31, v82
	v_max_u32_e32 v82, v16, v73
	v_min_u32_e32 v16, v16, v73
	v_max_u32_e32 v73, v22, v74
	v_min_u32_e32 v22, v22, v74
	v_max_u32_e32 v74, v27, v30
	v_min_u32_e32 v27, v27, v30
	v_max_u32_e32 v30, v63, v13
	v_min_u32_e32 v13, v63, v13
	v_max_u32_e32 v63, v11, v15
	v_min_u32_e32 v11, v11, v15
	v_max_u32_e32 v15, v29, v61
	v_min_u32_e32 v29, v29, v61
	v_max_u32_e32 v61, v23, v5
	v_min_u32_e32 v5, v23, v5
	v_max_u32_e32 v23, v8, v7
	v_min_u32_e32 v7, v8, v7
	v_max_u32_e32 v8, v20, v53
	v_min_u32_e32 v20, v20, v53
	v_max_u32_e32 v53, v43, v37
	v_min_u32_e32 v37, v43, v37
	v_max_u32_e32 v43, v36, v44
	v_min_u32_e32 v36, v36, v44
	v_max_u32_e32 v44, v39, v47
	v_min_u32_e32 v39, v39, v47
	v_max_u32_e32 v47, v41, v49
	v_min_u32_e32 v41, v41, v49
	v_max_u32_e32 v49, v25, v33
	v_min_u32_e32 v25, v25, v33
	v_max_u32_e32 v33, v52, v60
	v_min_u32_e32 v52, v52, v60
	v_max_u32_e32 v60, v4, v12
	v_min_u32_e32 v4, v4, v12
	v_max_u32_e32 v12, v51, v59
	v_min_u32_e32 v51, v51, v59
	v_max_u32_e32 v59, v38, v46
	v_min_u32_e32 v38, v38, v46
	v_max_u32_e32 v46, v33, v36
	v_min_u32_e32 v33, v33, v36
	v_max_u32_e32 v36, v60, v39
	v_min_u32_e32 v39, v60, v39
	v_max_u32_e32 v60, v12, v41
	v_min_u32_e32 v12, v12, v41
	v_max_u32_e32 v41, v59, v25
	v_min_u32_e32 v25, v59, v25
	v_max_u32_e32 v59, v56, v64
	v_min_u32_e32 v56, v56, v64
	v_max_u32_e32 v64, v6, v14
	v_min_u32_e32 v6, v6, v14
	v_max_u32_e32 v14, v40, v48
	v_min_u32_e32 v40, v40, v48
	v_max_u32_e32 v48, v54, v62
	v_min_u32_e32 v54, v54, v62
	v_max_u32_e32 v62, v50, v58
	v_min_u32_e32 v50, v50, v58
	v_max_u32_e32 v58, v34, v42
	v_min_u32_e32 v34, v34, v42
	v_max_u32_e32 v42, v18, v26
	v_min_u32_e32 v18, v18, v26
	v_max_u32_e32 v26, v2, v10
	v_min_u32_e32 v2, v2, v10
	v_max_u32_e32 v10, v62, v56
	v_min_u32_e32 v56, v62, v56
	v_max_u32_e32 v62, v58, v6
	v_min_u32_e32 v6, v58, v6
	v_max_u32_e32 v58, v42, v40
	v_min_u32_e32 v40, v42, v40
	v_max_u32_e32 v42, v26, v54
	v_min_u32_e32 v26, v26, v54
	v_max_u32_e32 v54, v59, v46
	v_min_u32_e32 v46, v59, v46
	v_max_u32_e32 v59, v64, v36
	v_min_u32_e32 v36, v64, v36
	v_max_u32_e32 v64, v14, v60
	v_min_u32_e32 v14, v14, v60
	v_max_u32_e32 v60, v48, v41
	v_min_u32_e32 v41, v48, v41
	v_max_u32_e32 v48, v10, v33
	v_min_u32_e32 v10, v10, v33
	v_max_u32_e32 v33, v62, v39
	v_min_u32_e32 v39, v62, v39
	v_max_u32_e32 v62, v58, v12
	v_min_u32_e32 v12, v58, v12
	v_max_u32_e32 v58, v42, v25
	v_min_u32_e32 v25, v42, v25
	v_max_u32_e32 v42, v56, v52
	v_min_u32_e32 v52, v56, v52
	v_max_u32_e32 v56, v6, v4
	v_min_u32_e32 v4, v6, v4
	v_max_u32_e32 v6, v40, v51
	v_min_u32_e32 v40, v40, v51
	v_max_u32_e32 v51, v26, v38
	v_min_u32_e32 v26, v26, v38
	v_min_u32_e32 v38, v43, v55
	v_min_u32_e32 v83, v44, v79
	v_min_u32_e32 v157, v47, v82
	v_min_u32_e32 v158, v49, v73
	v_min_u32_e32 v159, v54, v45
	v_min_u32_e32 v160, v59, v31
	v_min_u32_e32 v161, v64, v16
	v_min_u32_e32 v162, v60, v22
	v_min_u32_e32 v163, v46, v74
	v_min_u32_e32 v164, v36, v30
	v_min_u32_e32 v165, v14, v63
	v_min_u32_e32 v166, v41, v15
	v_min_u32_e32 v167, v48, v27
	v_min_u32_e32 v168, v33, v13
	v_min_u32_e32 v169, v62, v11
	v_min_u32_e32 v182, v58, v29
	v_min_u32_e32 v183, v10, v61
	v_min_u32_e32 v184, v39, v23
	v_min_u32_e32 v185, v12, v8
	v_min_u32_e32 v186, v25, v53
	v_min_u32_e32 v187, v42, v5
	v_min_u32_e32 v188, v56, v7
	v_min_u32_e32 v189, v6, v20
	v_min_u32_e32 v190, v51, v37
	v_min_u32_e32 v191, v52, v3
	v_min_u32_e32 v198, v4, v21
	v_min_u32_e32 v199, v40, v35
	v_min_u32_e32 v200, v26, v19
	v_max3_u32 v24, v24, v32, v34
	v_max3_u32 v32, v43, v55, v198
	v_max3_u32 v4, v38, v4, v21
	v_max3_u32 v21, v54, v45, v188
	v_max3_u32 v7, v159, v56, v7
	v_max3_u32 v34, v46, v74, v184
	v_max3_u32 v23, v163, v39, v23
	v_max3_u32 v27, v48, v27, v168
	v_max3_u32 v13, v167, v33, v13
	v_max3_u32 v10, v10, v61, v164
	v_max3_u32 v30, v183, v36, v30
	v_max3_u32 v5, v42, v5, v160
	v_max3_u32 v31, v187, v59, v31
	v_max3_u32 v3, v52, v3, v83
	v_max3_u32 v33, v191, v44, v79
	v_max3_u32 v9, v50, v9, v17
	v_max3_u32 v2, v72, v28, v2
	v_max3_u32 v28, v47, v82, v200
	v_max3_u32 v19, v157, v26, v19
; DI void merge_top16(unsigned (&A)[16], const unsigned (&B)[16]) {
; #pragma unroll
;     for (int i = 0; i < 16; ++i) A[i] = max(A[i], B[15 - i]);
; #pragma unroll
;     for (int n = 0; n < 32; ++n) cex(A[BMERGE16[n][0]], A[BMERGE16[n][1]]);
; }
; DI void peer_topk_phase(const bf16_t* __restrict__ qpk, const bf16_t* __restrict__ subk, int* __restrict__ eidx, float* __restrict__ gout) {
;     ...
;             merge_top16(g0, g1); merge_top16(g2, g3); merge_top16(g0, g2);
;             unsigned pb[16];
; #pragma unroll
;             for (int i = 0; i < 16; ++i) pb[i] = (unsigned)__shfl_xor((int)g0[i], 32);
;             merge_top16(g0, pb);
; #pragma unroll
;             for (int i = 0; i < 16; ++i) top[c][i] = g0[i];
	v_max3_u32 v16, v64, v16, v190
	v_max3_u32 v26, v161, v51, v37
	v_max3_u32 v14, v14, v63, v186
	v_max3_u32 v25, v165, v25, v53
	v_max3_u32 v11, v62, v11, v182
	v_max3_u32 v29, v169, v58, v29
	v_max3_u32 v8, v12, v8, v166
	v_max3_u32 v12, v185, v41, v15
	v_max3_u32 v6, v6, v20, v162
	v_max3_u32 v15, v189, v60, v22
	v_max3_u32 v20, v40, v35, v158
	v_max3_u32 v22, v199, v49, v73
	v_max3_u32 v18, v18, v57, v65
	v_max_u32_e32 v17, v24, v13
	v_min_u32_e32 v13, v24, v13
	v_max_u32_e32 v24, v32, v10
	v_min_u32_e32 v10, v32, v10
	v_max_u32_e32 v32, v4, v30
	v_min_u32_e32 v4, v4, v30
	v_max_u32_e32 v30, v21, v5
	v_min_u32_e32 v5, v21, v5
	v_max_u32_e32 v21, v7, v31
	v_min_u32_e32 v7, v7, v31
	v_max_u32_e32 v31, v34, v3
	v_min_u32_e32 v3, v34, v3
	v_max_u32_e32 v34, v23, v33
	v_min_u32_e32 v23, v23, v33
	v_max_u32_e32 v33, v27, v9
	v_min_u32_e32 v9, v27, v9
	v_max_u32_e32 v35, v2, v29
	v_min_u32_e32 v2, v2, v29
	v_max_u32_e32 v29, v28, v8
	v_min_u32_e32 v8, v28, v8
	v_max_u32_e32 v28, v19, v12
	v_min_u32_e32 v12, v19, v12
	v_max_u32_e32 v19, v16, v6
	v_min_u32_e32 v6, v16, v6
	v_max_u32_e32 v16, v26, v15
	v_min_u32_e32 v15, v26, v15
	v_max_u32_e32 v26, v14, v20
	v_min_u32_e32 v14, v14, v20
	v_max_u32_e32 v20, v25, v22
	v_min_u32_e32 v22, v25, v22
	v_max_u32_e32 v25, v11, v18
	v_min_u32_e32 v11, v11, v18
	v_max_u32_e32 v27, v17, v21
	v_min_u32_e32 v17, v17, v21
	v_max_u32_e32 v21, v24, v31
	v_min_u32_e32 v24, v24, v31
	v_max_u32_e32 v31, v32, v34
	v_min_u32_e32 v32, v32, v34
	v_max_u32_e32 v34, v30, v33
	v_min_u32_e32 v30, v30, v33
	v_max_u32_e32 v33, v13, v7
	v_min_u32_e32 v7, v13, v7
	v_max_u32_e32 v13, v10, v3
	v_min_u32_e32 v3, v10, v3
	v_max_u32_e32 v10, v4, v23
	v_min_u32_e32 v4, v4, v23
	v_max_u32_e32 v23, v5, v9
	v_min_u32_e32 v5, v5, v9
	v_max_u32_e32 v18, v35, v16
	v_min_u32_e32 v16, v35, v16
	v_max_u32_e32 v35, v29, v26
	v_min_u32_e32 v26, v29, v26
	v_max_u32_e32 v29, v28, v20
	v_min_u32_e32 v20, v28, v20
	v_max_u32_e32 v28, v19, v25
	v_min_u32_e32 v19, v19, v25
	v_max_u32_e32 v25, v2, v15
	v_min_u32_e32 v2, v2, v15
	v_max_u32_e32 v15, v8, v14
	v_min_u32_e32 v8, v8, v14
	v_max_u32_e32 v14, v12, v22
	v_min_u32_e32 v12, v12, v22
	v_max_u32_e32 v22, v6, v11
	v_min_u32_e32 v6, v6, v11
	v_max_u32_e32 v9, v27, v31
	v_min_u32_e32 v27, v27, v31
	v_max_u32_e32 v31, v21, v34
	v_min_u32_e32 v21, v21, v34
	v_max_u32_e32 v34, v17, v32
	v_min_u32_e32 v17, v17, v32
	v_max_u32_e32 v32, v24, v30
	v_min_u32_e32 v24, v24, v30
	v_max_u32_e32 v30, v33, v10
	v_min_u32_e32 v10, v33, v10
	v_max_u32_e32 v33, v13, v23
	v_min_u32_e32 v13, v13, v23
	v_max_u32_e32 v23, v7, v4
	v_min_u32_e32 v4, v7, v4
	v_max_u32_e32 v7, v3, v5
	v_min_u32_e32 v3, v3, v5
	v_max_u32_e32 v11, v18, v29
	v_min_u32_e32 v18, v18, v29
	v_max_u32_e32 v29, v35, v28
	v_min_u32_e32 v28, v35, v28
	v_max_u32_e32 v35, v16, v20
	v_min_u32_e32 v16, v16, v20
	v_max_u32_e32 v20, v26, v19
	v_min_u32_e32 v19, v26, v19
	v_max_u32_e32 v26, v25, v14
	v_min_u32_e32 v14, v25, v14
	v_max_u32_e32 v25, v15, v22
	v_min_u32_e32 v15, v15, v22
	v_max_u32_e32 v22, v2, v12
	v_min_u32_e32 v2, v2, v12
	v_max_u32_e32 v12, v8, v6
	v_min_u32_e32 v6, v8, v6
	v_min_u32_e32 v5, v9, v31
	v_min_u32_e32 v36, v27, v21
	v_min_u32_e32 v38, v34, v32
	v_min_u32_e32 v39, v17, v24
	v_min_u32_e32 v42, v30, v33
	v_min_u32_e32 v43, v10, v13
	v_min_u32_e32 v44, v23, v7
	v_min_u32_e32 v45, v4, v3
	v_min_u32_e32 v8, v11, v29
	v_min_u32_e32 v37, v18, v28
	v_min_u32_e32 v40, v35, v20
	v_min_u32_e32 v41, v16, v19
	v_min_u32_e32 v46, v26, v25
	v_min_u32_e32 v47, v14, v15
	v_min_u32_e32 v48, v22, v12
	v_min_u32_e32 v49, v2, v6
	v_max3_u32 v9, v9, v31, v49
	v_max3_u32 v2, v5, v2, v6
	v_max3_u32 v5, v27, v21, v48
	v_max3_u32 v6, v36, v22, v12
	v_max3_u32 v12, v34, v32, v47
	v_max3_u32 v14, v38, v14, v15
	v_max3_u32 v15, v17, v24, v46
	v_max3_u32 v17, v39, v26, v25
	v_max3_u32 v21, v30, v33, v41
	v_max3_u32 v16, v42, v16, v19
	v_max3_u32 v10, v10, v13, v40
	v_max3_u32 v13, v43, v35, v20
	v_max3_u32 v7, v23, v7, v37
	v_max3_u32 v18, v44, v18, v28
	v_max3_u32 v3, v4, v3, v8
	v_max3_u32 v4, v45, v11, v29
	v_max_u32_e32 v8, v9, v21
	v_min_u32_e32 v9, v9, v21
	v_max_u32_e32 v11, v2, v16
	v_min_u32_e32 v2, v2, v16
	v_max_u32_e32 v16, v5, v10
	v_min_u32_e32 v5, v5, v10
	v_max_u32_e32 v10, v6, v13
	v_min_u32_e32 v6, v6, v13
	v_max_u32_e32 v13, v12, v7
	v_min_u32_e32 v7, v12, v7
	v_max_u32_e32 v12, v14, v18
	v_min_u32_e32 v14, v14, v18
	v_max_u32_e32 v18, v15, v3
	v_min_u32_e32 v3, v15, v3
	v_max_u32_e32 v15, v17, v4
	v_min_u32_e32 v4, v17, v4
	v_max_u32_e32 v17, v8, v13
	v_min_u32_e32 v8, v8, v13
	v_max_u32_e32 v13, v11, v12
	v_min_u32_e32 v11, v11, v12
	v_max_u32_e32 v12, v16, v18
	v_min_u32_e32 v16, v16, v18
	v_max_u32_e32 v18, v10, v15
	v_min_u32_e32 v10, v10, v15
	v_max_u32_e32 v15, v9, v7
	v_min_u32_e32 v7, v9, v7
	v_max_u32_e32 v9, v2, v14
	v_min_u32_e32 v2, v2, v14
	v_max_u32_e32 v14, v5, v3
	v_min_u32_e32 v3, v5, v3
	v_max_u32_e32 v5, v6, v4
	v_min_u32_e32 v4, v6, v4
	v_max_u32_e32 v6, v17, v12
	v_min_u32_e32 v12, v17, v12
	v_max_u32_e32 v17, v13, v18
	v_min_u32_e32 v13, v13, v18
	v_max_u32_e32 v18, v8, v16
	v_min_u32_e32 v8, v8, v16
	v_max_u32_e32 v16, v11, v10
	v_min_u32_e32 v10, v11, v10
	v_max_u32_e32 v11, v15, v14
	v_min_u32_e32 v14, v15, v14
	v_max_u32_e32 v15, v9, v5
	v_min_u32_e32 v5, v9, v5
	v_max_u32_e32 v9, v7, v3
	v_min_u32_e32 v3, v7, v3
	v_max_u32_e32 v7, v2, v4
	v_min_u32_e32 v2, v2, v4
	v_max_u32_e32 v4, v6, v17
	v_min_u32_e32 v6, v6, v17
	v_max_u32_e32 v17, v12, v13
	v_min_u32_e32 v12, v12, v13
	v_max_u32_e32 v13, v18, v16
	v_min_u32_e32 v16, v18, v16
	v_max_u32_e32 v18, v8, v10
	v_min_u32_e32 v8, v8, v10
	v_max_u32_e32 v10, v11, v15
	v_min_u32_e32 v11, v11, v15
	v_max_u32_e32 v15, v14, v5
	v_min_u32_e32 v5, v14, v5
	v_max_u32_e32 v14, v9, v7
	v_min_u32_e32 v7, v9, v7
	v_max_u32_e32 v9, v3, v2
	v_min_u32_e32 v2, v3, v2
	ds_bpermute_b32 v3, v173, v4
	ds_bpermute_b32 v19, v173, v6
	ds_bpermute_b32 v20, v173, v17
	ds_bpermute_b32 v21, v173, v12
	ds_bpermute_b32 v22, v173, v13
	ds_bpermute_b32 v23, v173, v16
	ds_bpermute_b32 v24, v173, v18
	ds_bpermute_b32 v25, v173, v8
	ds_bpermute_b32 v26, v173, v10
	ds_bpermute_b32 v27, v173, v11
	ds_bpermute_b32 v28, v173, v15
	ds_bpermute_b32 v29, v173, v5
	ds_bpermute_b32 v30, v173, v14
	ds_bpermute_b32 v31, v173, v7
	ds_bpermute_b32 v32, v173, v9
	ds_bpermute_b32 v33, v173, v2
	s_waitcnt lgkmcnt(4)
; #define MFMA(a, b, c) __builtin_amdgcn_mfma_f32_32x32x16_bf16((a), (b), (c), 0, 0, 0)
; DI void peer_topk_phase(const bf16_t* __restrict__ qpk, const bf16_t* __restrict__ subk, int* __restrict__ eidx, float* __restrict__ gout) {
;     ...
;         for (int c = 0; c < 2; ++c) {
;             f32x16 acc[4];
; #pragma unroll
;             for (int nb = 0; nb < 4; ++nb)
; #pragma unroll
;                 for (int i = 0; i < 16; ++i) acc[nb][i] = 0.f;
;             const bf16_t* qp = qpk + (size_t)(t0 + r) * 1024 + hh * 128 + c * 64 + h * 8;
;             const bf16_t* kp = subk + ((size_t)(hh * 2 + c) * 128 + r) * 64 + h * 8;
; #pragma unroll
;             for (int ks = 0; ks < 4; ++ks) {
;                 const bf16x8 qfr = *(const bf16x8*)(qp + ks * 16);
; #pragma unroll
;                 for (int nb = 0; nb < 4; ++nb) {
;                     const bf16x8 kf = *(const bf16x8*)(kp + nb * 32 * 64 + ks * 16);
;                     acc[nb] = MFMA(kf, qfr, acc[nb]);
;                 }
;             }
;     ...
;             merge_top16(g0, pb);
; #pragma unroll
;             for (int i = 0; i < 16; ++i) top[c][i] = g0[i];
	v_max_u32_e32 v13, v13, v29
	s_waitcnt lgkmcnt(3)
	v_max_u32_e32 v12, v12, v30
	s_waitcnt lgkmcnt(2)
	v_max_u32_e32 v17, v17, v31
	s_waitcnt lgkmcnt(1)
	v_max_u32_e32 v6, v6, v32
	s_waitcnt lgkmcnt(0)
	v_max_u32_e32 v4, v4, v33
	v_max_u32_e32 v16, v16, v28
	v_max_u32_e32 v18, v18, v27
	v_max_u32_e32 v8, v8, v26
	v_max_u32_e32 v10, v10, v25
	v_max_u32_e32 v11, v11, v24
	v_max_u32_e32 v15, v15, v23
	v_max_u32_e32 v5, v5, v22
	v_max_u32_e32 v14, v14, v21
	v_max_u32_e32 v7, v7, v20
	v_max_u32_e32 v9, v9, v19
	v_max_u32_e32 v2, v2, v3
	v_max_u32_e32 v3, v4, v10
	v_min_u32_e32 v4, v4, v10
	v_max_u32_e32 v10, v6, v11
	v_min_u32_e32 v6, v6, v11
	v_max_u32_e32 v11, v17, v15
	v_min_u32_e32 v15, v17, v15
	v_max_u32_e32 v17, v12, v5
	v_min_u32_e32 v5, v12, v5
	v_max_u32_e32 v12, v13, v14
	v_min_u32_e32 v13, v13, v14
	v_max_u32_e32 v14, v16, v7
	v_min_u32_e32 v7, v16, v7
	v_max_u32_e32 v16, v18, v9
	v_min_u32_e32 v9, v18, v9
	v_max_u32_e32 v18, v8, v2
	v_min_u32_e32 v2, v8, v2
	v_max_u32_e32 v8, v3, v12
	v_min_u32_e32 v3, v3, v12
	v_max_u32_e32 v12, v10, v14
	v_min_u32_e32 v10, v10, v14
	v_max_u32_e32 v14, v11, v16
	v_min_u32_e32 v11, v11, v16
	v_max_u32_e32 v16, v17, v18
	v_min_u32_e32 v17, v17, v18
	v_max_u32_e32 v18, v4, v13
	v_min_u32_e32 v4, v4, v13
	v_max_u32_e32 v13, v6, v7
	v_min_u32_e32 v6, v6, v7
	v_max_u32_e32 v7, v15, v9
	v_min_u32_e32 v9, v15, v9
	v_max_u32_e32 v15, v5, v2
	v_min_u32_e32 v2, v5, v2
	v_max_u32_e32 v5, v8, v14
	v_min_u32_e32 v8, v8, v14
	v_max_u32_e32 v14, v12, v16
	v_min_u32_e32 v12, v12, v16
	v_max_u32_e32 v16, v3, v11
	v_min_u32_e32 v3, v3, v11
	v_max_u32_e32 v11, v10, v17
	v_min_u32_e32 v10, v10, v17
	v_max_u32_e32 v17, v18, v7
	v_min_u32_e32 v7, v18, v7
	v_max_u32_e32 v18, v13, v15
	v_min_u32_e32 v13, v13, v15
	v_max_u32_e32 v15, v4, v9
	v_min_u32_e32 v4, v4, v9
	v_max_u32_e32 v9, v6, v2
	v_min_u32_e32 v2, v6, v2
	v_max_u32_e32 v168, v5, v14
	v_min_u32_e32 v182, v5, v14
	v_max_u32_e32 v164, v3, v10
	v_min_u32_e32 v163, v3, v10
	v_max_u32_e32 v79, v4, v2
	v_min_u32_e32 v74, v4, v2
	v_max_u32_e32 v162, v17, v18
	v_min_u32_e32 v161, v17, v18
	v_max_u32_e32 v169, v8, v12
	v_min_u32_e32 v167, v8, v12
	v_max_u32_e32 v166, v16, v11
	v_min_u32_e32 v165, v16, v11
	v_max_u32_e32 v160, v7, v13
	v_min_u32_e32 v159, v7, v13
	v_max_u32_e32 v158, v15, v9
	v_min_u32_e32 v157, v15, v9
	v_add_co_u32_e32 v72, vcc, s43, v68
	s_nop 1
	v_addc_co_u32_e32 v73, vcc, 0, v69, vcc
	v_add_co_u32_e32 v82, vcc, s52, v68
	s_nop 1
	v_addc_co_u32_e32 v83, vcc, 0, v69, vcc
	v_add_co_u32_e32 v198, vcc, s53, v68
	s_nop 1
	v_addc_co_u32_e32 v199, vcc, 0, v69, vcc
	global_load_dwordx4 v[50:53], v[66:67], off offset:128
	global_load_dwordx4 v[214:217], v[70:71], off
	global_load_dwordx4 v[218:221], v[82:83], off offset:-4096
	global_load_dwordx4 v[2:5], v[82:83], off
	global_load_dwordx4 v[54:57], v[198:199], off
	global_load_dwordx4 v[184:187], v[66:67], off offset:160
	global_load_dwordx4 v[222:225], v[70:71], off offset:32
	global_load_dwordx4 v[226:229], v[72:73], off offset:32
	global_load_dwordx4 v[232:235], v[82:83], off offset:32
	global_load_dwordx4 v[236:239], v[198:199], off offset:32
	global_load_dwordx4 v[188:191], v[66:67], off offset:192
	global_load_dwordx4 v[240:243], v[70:71], off offset:64
	global_load_dwordx4 v[244:247], v[72:73], off offset:64
	global_load_dwordx4 v[248:251], v[82:83], off offset:64
	global_load_dwordx4 v[210:213], v[66:67], off offset:224
	s_waitcnt vmcnt(13)
	v_mfma_f32_32x32x16_bf16 v[34:49], v[214:217], v[50:53], 0
	s_waitcnt vmcnt(12)
	v_mfma_f32_32x32x16_bf16 v[18:33], v[218:221], v[50:53], 0
	s_waitcnt vmcnt(11)
	v_mfma_f32_32x32x16_bf16 v[2:17], v[2:5], v[50:53], 0
	s_waitcnt vmcnt(10)
	v_mfma_f32_32x32x16_bf16 v[50:65], v[54:57], v[50:53], 0
	global_load_dwordx4 v[214:217], v[198:199], off offset:64
	global_load_dwordx4 v[218:221], v[70:71], off offset:96
	s_waitcnt vmcnt(10)
	v_mfma_f32_32x32x16_bf16 v[34:49], v[222:225], v[184:187], v[34:49]
	s_waitcnt vmcnt(9)
	v_mfma_f32_32x32x16_bf16 v[18:33], v[226:229], v[184:187], v[18:33]
	s_waitcnt vmcnt(8)
	v_mfma_f32_32x32x16_bf16 v[2:17], v[232:235], v[184:187], v[2:17]
	s_waitcnt vmcnt(7)
	v_mfma_f32_32x32x16_bf16 v[50:65], v[236:239], v[184:187], v[50:65]
	global_load_dwordx4 v[222:225], v[72:73], off offset:96
	global_load_dwordx4 v[226:229], v[82:83], off offset:96
	global_load_dwordx4 v[232:235], v[198:199], off offset:96
	s_waitcnt vmcnt(8)
	v_mfma_f32_32x32x16_bf16 v[34:49], v[240:243], v[188:191], v[34:49]
	s_waitcnt vmcnt(7)
	v_mfma_f32_32x32x16_bf16 v[18:33], v[244:247], v[188:191], v[18:33]
	s_waitcnt vmcnt(6)
	v_mfma_f32_32x32x16_bf16 v[2:17], v[248:251], v[188:191], v[2:17]
	s_waitcnt vmcnt(4)
	v_mfma_f32_32x32x16_bf16 v[50:65], v[214:217], v[188:191], v[50:65]
	s_waitcnt vmcnt(3)
	v_mfma_f32_32x32x16_bf16 v[34:49], v[218:221], v[210:213], v[34:49]
	s_waitcnt vmcnt(2)
	v_mfma_f32_32x32x16_bf16 v[18:33], v[222:225], v[210:213], v[18:33]
	s_waitcnt vmcnt(1)
	v_mfma_f32_32x32x16_bf16 v[2:17], v[226:229], v[210:213], v[2:17]
	s_waitcnt vmcnt(0)
; #define MFMA(a, b, c) __builtin_amdgcn_mfma_f32_32x32x16_bf16((a), (b), (c), 0, 0, 0)
; DI unsigned f2ord(float f) { const unsigned u = __float_as_uint(f); return (u & 0x80000000u) ? ~u : (u | 0x80000000u); }
; DI void peer_topk_phase(const bf16_t* __restrict__ qpk, const bf16_t* __restrict__ subk, int* __restrict__ eidx, float* __restrict__ gout) {
;     ...
;                     const bf16x8 kf = *(const bf16x8*)(kp + nb * 32 * 64 + ks * 16);
;                     acc[nb] = MFMA(kf, qfr, acc[nb]);
;                 }
;             }
;             unsigned key[64];
; #pragma unroll
;             for (int nb = 0; nb < 4; ++nb)
; #pragma unroll
;                 for (int i = 0; i < 16; ++i) {
;                     const int n = nb * 32 + (i & 3) + 8 * (i >> 2) + 4 * h;
;                     key[nb * 16 + i] = (f2ord(acc[nb][i]) & ~127u) | (unsigned)(127 - n);
;                 }
	v_mfma_f32_32x32x16_bf16 v[50:65], v[232:235], v[210:213], v[50:65]
	s_nop 9
	v_not_b32_e32 v66, v34
	v_or_b32_e32 v67, 0x80000000, v34
	v_cmp_gt_i32_e32 vcc, 0, v34
	s_nop 1
	v_cndmask_b32_e32 v34, v67, v66, vcc
	v_not_b32_e32 v66, v35
	v_or_b32_e32 v67, 0x80000000, v35
	v_cmp_gt_i32_e32 vcc, 0, v35
	v_and_or_b32 v34, v34, s42, v85
	s_nop 0
	v_cndmask_b32_e32 v35, v67, v66, vcc
	v_not_b32_e32 v66, v36
	v_or_b32_e32 v67, 0x80000000, v36
	v_cmp_gt_i32_e32 vcc, 0, v36
	v_and_or_b32 v35, v35, s42, v86
	s_nop 0
	v_cndmask_b32_e32 v36, v67, v66, vcc
	v_not_b32_e32 v66, v37
	v_or_b32_e32 v67, 0x80000000, v37
	v_cmp_gt_i32_e32 vcc, 0, v37
	v_and_or_b32 v36, v36, s42, v87
	s_nop 0
	v_cndmask_b32_e32 v37, v67, v66, vcc
	v_not_b32_e32 v66, v38
	v_or_b32_e32 v67, 0x80000000, v38
	v_cmp_gt_i32_e32 vcc, 0, v38
	v_and_or_b32 v37, v37, s42, v88
	s_nop 0
	v_cndmask_b32_e32 v38, v67, v66, vcc
	v_not_b32_e32 v66, v39
	v_or_b32_e32 v67, 0x80000000, v39
	v_cmp_gt_i32_e32 vcc, 0, v39
	v_and_or_b32 v38, v38, s42, v89
	s_nop 0
	v_cndmask_b32_e32 v39, v67, v66, vcc
	v_not_b32_e32 v66, v40
	v_or_b32_e32 v67, 0x80000000, v40
	v_cmp_gt_i32_e32 vcc, 0, v40
	v_and_or_b32 v39, v39, s42, v90
	s_nop 0
	v_cndmask_b32_e32 v40, v67, v66, vcc
	v_not_b32_e32 v66, v41
	v_or_b32_e32 v67, 0x80000000, v41
	v_cmp_gt_i32_e32 vcc, 0, v41
	v_and_or_b32 v40, v40, s42, v91
	s_nop 0
	v_cndmask_b32_e32 v41, v67, v66, vcc
	v_not_b32_e32 v66, v42
	v_or_b32_e32 v67, 0x80000000, v42
	v_cmp_gt_i32_e32 vcc, 0, v42
	v_and_or_b32 v41, v41, s42, v92
	s_nop 0
	v_cndmask_b32_e32 v42, v67, v66, vcc
	v_not_b32_e32 v66, v43
	v_or_b32_e32 v67, 0x80000000, v43
	v_cmp_gt_i32_e32 vcc, 0, v43
	v_and_or_b32 v42, v42, s42, v93
	s_nop 0
	v_cndmask_b32_e32 v43, v67, v66, vcc
	v_not_b32_e32 v66, v44
	v_or_b32_e32 v67, 0x80000000, v44
	v_cmp_gt_i32_e32 vcc, 0, v44
	v_and_or_b32 v43, v43, s42, v94
	s_nop 0
	v_cndmask_b32_e32 v44, v67, v66, vcc
	v_not_b32_e32 v66, v45
	v_or_b32_e32 v67, 0x80000000, v45
	v_cmp_gt_i32_e32 vcc, 0, v45
	v_and_or_b32 v44, v44, s42, v95
	s_nop 0
	v_cndmask_b32_e32 v45, v67, v66, vcc
	v_not_b32_e32 v66, v46
	v_or_b32_e32 v67, 0x80000000, v46
	v_cmp_gt_i32_e32 vcc, 0, v46
	v_and_or_b32 v45, v45, s42, v96
	s_nop 0
	v_cndmask_b32_e32 v46, v67, v66, vcc
	v_not_b32_e32 v66, v47
	v_or_b32_e32 v67, 0x80000000, v47
	v_cmp_gt_i32_e32 vcc, 0, v47
	v_and_or_b32 v46, v46, s42, v97
	s_nop 0
	v_cndmask_b32_e32 v47, v67, v66, vcc
	v_not_b32_e32 v66, v48
	v_or_b32_e32 v67, 0x80000000, v48
	v_cmp_gt_i32_e32 vcc, 0, v48
	v_and_or_b32 v47, v47, s42, v98
	s_nop 0
	v_cndmask_b32_e32 v48, v67, v66, vcc
	v_not_b32_e32 v66, v49
	v_or_b32_e32 v67, 0x80000000, v49
	v_cmp_gt_i32_e32 vcc, 0, v49
	v_and_or_b32 v48, v48, s42, v99
	s_nop 0
	v_cndmask_b32_e32 v49, v67, v66, vcc
	v_not_b32_e32 v66, v18
	v_or_b32_e32 v67, 0x80000000, v18
	v_cmp_gt_i32_e32 vcc, 0, v18
	v_and_or_b32 v49, v49, s42, v100
	s_nop 0
	v_cndmask_b32_e32 v18, v67, v66, vcc
	v_not_b32_e32 v66, v19
	v_or_b32_e32 v67, 0x80000000, v19
	v_cmp_gt_i32_e32 vcc, 0, v19
	v_and_or_b32 v18, v18, s42, v101
	s_nop 0
	v_cndmask_b32_e32 v19, v67, v66, vcc
	v_not_b32_e32 v66, v20
	v_or_b32_e32 v67, 0x80000000, v20
	v_cmp_gt_i32_e32 vcc, 0, v20
	v_and_or_b32 v19, v19, s42, v102
	s_nop 0
	v_cndmask_b32_e32 v20, v67, v66, vcc
	v_not_b32_e32 v66, v21
	v_or_b32_e32 v67, 0x80000000, v21
	v_cmp_gt_i32_e32 vcc, 0, v21
	v_and_or_b32 v20, v20, s42, v103
	s_nop 0
	v_cndmask_b32_e32 v21, v67, v66, vcc
	v_not_b32_e32 v66, v22
	v_or_b32_e32 v67, 0x80000000, v22
	v_cmp_gt_i32_e32 vcc, 0, v22
	v_and_or_b32 v21, v21, s42, v104
	s_nop 0
	v_cndmask_b32_e32 v22, v67, v66, vcc
	v_not_b32_e32 v66, v23
	v_or_b32_e32 v67, 0x80000000, v23
	v_cmp_gt_i32_e32 vcc, 0, v23
	v_and_or_b32 v22, v22, s42, v105
	s_nop 0
	v_cndmask_b32_e32 v23, v67, v66, vcc
	v_not_b32_e32 v66, v24
	v_or_b32_e32 v67, 0x80000000, v24
	v_cmp_gt_i32_e32 vcc, 0, v24
	v_and_or_b32 v23, v23, s42, v106
	s_nop 0
	v_cndmask_b32_e32 v24, v67, v66, vcc
	v_not_b32_e32 v66, v25
	v_or_b32_e32 v67, 0x80000000, v25
	v_cmp_gt_i32_e32 vcc, 0, v25
	v_and_or_b32 v24, v24, s42, v107
	s_nop 0
	v_cndmask_b32_e32 v25, v67, v66, vcc
	v_not_b32_e32 v66, v26
	v_or_b32_e32 v67, 0x80000000, v26
	v_cmp_gt_i32_e32 vcc, 0, v26
	v_and_or_b32 v25, v25, s42, v108
	s_nop 0
	v_cndmask_b32_e32 v26, v67, v66, vcc
	v_not_b32_e32 v66, v27
	v_or_b32_e32 v67, 0x80000000, v27
	v_cmp_gt_i32_e32 vcc, 0, v27
	v_and_or_b32 v26, v26, s42, v109
	s_nop 0
	v_cndmask_b32_e32 v27, v67, v66, vcc
	v_not_b32_e32 v66, v28
	v_or_b32_e32 v67, 0x80000000, v28
	v_cmp_gt_i32_e32 vcc, 0, v28
	v_and_or_b32 v27, v27, s42, v110
	s_nop 0
	v_cndmask_b32_e32 v28, v67, v66, vcc
	v_not_b32_e32 v66, v29
	v_or_b32_e32 v67, 0x80000000, v29
	v_cmp_gt_i32_e32 vcc, 0, v29
	v_and_or_b32 v28, v28, s42, v111
	s_nop 0
	v_cndmask_b32_e32 v29, v67, v66, vcc
	v_not_b32_e32 v66, v30
	v_or_b32_e32 v67, 0x80000000, v30
	v_cmp_gt_i32_e32 vcc, 0, v30
	v_and_or_b32 v29, v29, s42, v112
	s_nop 0
	v_cndmask_b32_e32 v30, v67, v66, vcc
	v_not_b32_e32 v66, v31
	v_or_b32_e32 v67, 0x80000000, v31
	v_cmp_gt_i32_e32 vcc, 0, v31
	v_and_or_b32 v30, v30, s42, v113
	s_nop 0
	v_cndmask_b32_e32 v31, v67, v66, vcc
	v_not_b32_e32 v66, v32
	v_or_b32_e32 v67, 0x80000000, v32
	v_cmp_gt_i32_e32 vcc, 0, v32
	v_and_or_b32 v31, v31, s42, v114
	s_nop 0
	v_cndmask_b32_e32 v32, v67, v66, vcc
	v_not_b32_e32 v66, v33
	v_or_b32_e32 v67, 0x80000000, v33
	v_cmp_gt_i32_e32 vcc, 0, v33
	v_and_or_b32 v32, v32, s42, v115
	s_nop 0
	v_cndmask_b32_e32 v33, v67, v66, vcc
	v_not_b32_e32 v66, v2
	v_or_b32_e32 v67, 0x80000000, v2
	v_cmp_gt_i32_e32 vcc, 0, v2
	v_and_or_b32 v33, v33, s42, v116
	s_nop 0
	v_cndmask_b32_e32 v2, v67, v66, vcc
; DI unsigned f2ord(float f) { const unsigned u = __float_as_uint(f); return (u & 0x80000000u) ? ~u : (u | 0x80000000u); }
; DI void peer_topk_phase(const bf16_t* __restrict__ qpk, const bf16_t* __restrict__ subk, int* __restrict__ eidx, float* __restrict__ gout) {
;     ...
; #pragma unroll
;             for (int nb = 0; nb < 4; ++nb)
; #pragma unroll
;                 for (int i = 0; i < 16; ++i) {
;                     const int n = nb * 32 + (i & 3) + 8 * (i >> 2) + 4 * h;
;                     key[nb * 16 + i] = (f2ord(acc[nb][i]) & ~127u) | (unsigned)(127 - n);
;                 }
;             unsigned g0[16], g1[16], g2[16], g3[16];
; #pragma unroll
;             for (int i = 0; i < 16; ++i) { g0[i] = key[i]; g1[i] = key[16 + i]; g2[i] = key[32 + i]; g3[i] = key[48 + i]; }
; #pragma unroll
;             for (int n = 0; n < 63; ++n) { cex(g0[SORT16[n][0]], g0[SORT16[n][1]]); cex(g1[SORT16[n][0]], g1[SORT16[n][1]]); cex(g2[SORT16[n][0]], g2[SORT16[n][1]]); cex(g3[SORT16[n][0]], g3[SORT16[n][1]]); }
	v_not_b32_e32 v66, v3
	v_or_b32_e32 v67, 0x80000000, v3
	v_cmp_gt_i32_e32 vcc, 0, v3
	v_and_or_b32 v2, v2, s42, v117
	s_nop 0
	v_cndmask_b32_e32 v3, v67, v66, vcc
	v_not_b32_e32 v66, v4
	v_or_b32_e32 v67, 0x80000000, v4
	v_cmp_gt_i32_e32 vcc, 0, v4
	v_and_or_b32 v3, v3, s42, v118
	s_nop 0
	v_cndmask_b32_e32 v4, v67, v66, vcc
	v_not_b32_e32 v66, v5
	v_or_b32_e32 v67, 0x80000000, v5
	v_cmp_gt_i32_e32 vcc, 0, v5
	v_and_or_b32 v4, v4, s42, v119
	s_nop 0
	v_cndmask_b32_e32 v5, v67, v66, vcc
	v_not_b32_e32 v66, v6
	v_or_b32_e32 v67, 0x80000000, v6
	v_cmp_gt_i32_e32 vcc, 0, v6
	v_and_or_b32 v5, v5, s42, v120
	s_nop 0
	v_cndmask_b32_e32 v6, v67, v66, vcc
	v_not_b32_e32 v66, v7
	v_or_b32_e32 v67, 0x80000000, v7
	v_cmp_gt_i32_e32 vcc, 0, v7
	v_and_or_b32 v6, v6, s42, v121
	s_nop 0
	v_cndmask_b32_e32 v7, v67, v66, vcc
	v_not_b32_e32 v66, v8
	v_or_b32_e32 v67, 0x80000000, v8
	v_cmp_gt_i32_e32 vcc, 0, v8
	v_and_or_b32 v7, v7, s42, v122
	s_nop 0
	v_cndmask_b32_e32 v8, v67, v66, vcc
	v_not_b32_e32 v66, v9
	v_or_b32_e32 v67, 0x80000000, v9
	v_cmp_gt_i32_e32 vcc, 0, v9
	v_and_or_b32 v8, v8, s42, v123
	s_nop 0
	v_cndmask_b32_e32 v9, v67, v66, vcc
	v_not_b32_e32 v66, v10
	v_or_b32_e32 v67, 0x80000000, v10
	v_cmp_gt_i32_e32 vcc, 0, v10
	v_and_or_b32 v9, v9, s42, v124
	s_nop 0
	v_cndmask_b32_e32 v10, v67, v66, vcc
	v_not_b32_e32 v66, v11
	v_or_b32_e32 v67, 0x80000000, v11
	v_cmp_gt_i32_e32 vcc, 0, v11
	v_and_or_b32 v10, v10, s42, v125
	s_nop 0
	v_cndmask_b32_e32 v11, v67, v66, vcc
	v_not_b32_e32 v66, v12
	v_or_b32_e32 v67, 0x80000000, v12
	v_cmp_gt_i32_e32 vcc, 0, v12
	v_and_or_b32 v11, v11, s42, v126
	s_nop 0
	v_cndmask_b32_e32 v12, v67, v66, vcc
	v_not_b32_e32 v66, v13
	v_or_b32_e32 v67, 0x80000000, v13
	v_cmp_gt_i32_e32 vcc, 0, v13
	v_and_or_b32 v12, v12, s42, v127
	s_nop 0
	v_cndmask_b32_e32 v13, v67, v66, vcc
	v_not_b32_e32 v66, v14
	v_or_b32_e32 v67, 0x80000000, v14
	v_cmp_gt_i32_e32 vcc, 0, v14
	v_and_or_b32 v13, v13, s42, v128
	s_nop 0
	v_cndmask_b32_e32 v14, v67, v66, vcc
	v_not_b32_e32 v66, v15
	v_or_b32_e32 v67, 0x80000000, v15
	v_cmp_gt_i32_e32 vcc, 0, v15
	v_and_or_b32 v14, v14, s42, v129
	s_nop 0
	v_cndmask_b32_e32 v15, v67, v66, vcc
	v_not_b32_e32 v66, v16
	v_or_b32_e32 v67, 0x80000000, v16
	v_cmp_gt_i32_e32 vcc, 0, v16
	v_and_or_b32 v15, v15, s42, v130
	s_nop 0
	v_cndmask_b32_e32 v16, v67, v66, vcc
	v_not_b32_e32 v66, v17
	v_or_b32_e32 v67, 0x80000000, v17
	v_cmp_gt_i32_e32 vcc, 0, v17
	v_and_or_b32 v16, v16, s42, v131
	s_nop 0
	v_cndmask_b32_e32 v17, v67, v66, vcc
	v_not_b32_e32 v66, v50
	v_or_b32_e32 v67, 0x80000000, v50
	v_cmp_gt_i32_e32 vcc, 0, v50
	v_and_or_b32 v17, v17, s42, v132
	s_nop 0
	v_cndmask_b32_e32 v50, v67, v66, vcc
	v_not_b32_e32 v66, v51
	v_or_b32_e32 v67, 0x80000000, v51
	v_cmp_gt_i32_e32 vcc, 0, v51
	v_and_or_b32 v50, v50, s42, v133
	s_nop 0
	v_cndmask_b32_e32 v51, v67, v66, vcc
	v_not_b32_e32 v66, v52
	v_or_b32_e32 v67, 0x80000000, v52
	v_cmp_gt_i32_e32 vcc, 0, v52
	v_and_or_b32 v51, v51, s42, v134
	s_nop 0
	v_cndmask_b32_e32 v52, v67, v66, vcc
	v_not_b32_e32 v66, v53
	v_or_b32_e32 v67, 0x80000000, v53
	v_cmp_gt_i32_e32 vcc, 0, v53
	v_and_or_b32 v52, v52, s42, v135
	s_nop 0
	v_cndmask_b32_e32 v53, v67, v66, vcc
	v_not_b32_e32 v66, v54
	v_or_b32_e32 v67, 0x80000000, v54
	v_cmp_gt_i32_e32 vcc, 0, v54
	v_and_or_b32 v53, v53, s42, v136
	s_nop 0
	v_cndmask_b32_e32 v54, v67, v66, vcc
	v_not_b32_e32 v66, v55
	v_or_b32_e32 v67, 0x80000000, v55
	v_cmp_gt_i32_e32 vcc, 0, v55
	v_and_or_b32 v54, v54, s42, v137
	s_nop 0
	v_cndmask_b32_e32 v55, v67, v66, vcc
	v_not_b32_e32 v66, v56
	v_or_b32_e32 v67, 0x80000000, v56
	v_cmp_gt_i32_e32 vcc, 0, v56
	v_and_or_b32 v55, v55, s42, v138
	s_nop 0
	v_cndmask_b32_e32 v56, v67, v66, vcc
	v_not_b32_e32 v66, v57
	v_or_b32_e32 v67, 0x80000000, v57
	v_cmp_gt_i32_e32 vcc, 0, v57
	v_and_or_b32 v56, v56, s42, v139
	s_nop 0
	v_cndmask_b32_e32 v57, v67, v66, vcc
	v_not_b32_e32 v66, v58
	v_or_b32_e32 v67, 0x80000000, v58
	v_cmp_gt_i32_e32 vcc, 0, v58
	v_and_or_b32 v57, v57, s42, v140
	s_nop 0
	v_cndmask_b32_e32 v58, v67, v66, vcc
	v_not_b32_e32 v66, v59
	v_or_b32_e32 v67, 0x80000000, v59
	v_cmp_gt_i32_e32 vcc, 0, v59
	v_and_or_b32 v58, v58, s42, v141
	s_nop 0
	v_cndmask_b32_e32 v59, v67, v66, vcc
	v_not_b32_e32 v66, v60
	v_or_b32_e32 v67, 0x80000000, v60
	v_cmp_gt_i32_e32 vcc, 0, v60
	v_and_or_b32 v59, v59, s42, v142
	s_nop 0
	v_cndmask_b32_e32 v60, v67, v66, vcc
	v_not_b32_e32 v66, v61
	v_or_b32_e32 v67, 0x80000000, v61
	v_cmp_gt_i32_e32 vcc, 0, v61
	v_and_or_b32 v60, v60, s42, v143
	s_nop 0
	v_cndmask_b32_e32 v61, v67, v66, vcc
	v_not_b32_e32 v66, v62
	v_or_b32_e32 v67, 0x80000000, v62
	v_cmp_gt_i32_e32 vcc, 0, v62
	v_and_or_b32 v61, v61, s42, v144
	s_nop 0
	v_cndmask_b32_e32 v62, v67, v66, vcc
	v_not_b32_e32 v66, v63
	v_or_b32_e32 v67, 0x80000000, v63
	v_cmp_gt_i32_e32 vcc, 0, v63
	v_and_or_b32 v62, v62, s42, v145
	s_nop 0
	v_cndmask_b32_e32 v63, v67, v66, vcc
	v_not_b32_e32 v66, v64
	v_or_b32_e32 v67, 0x80000000, v64
	v_cmp_gt_i32_e32 vcc, 0, v64
	v_and_or_b32 v63, v63, s42, v149
	s_nop 0
	v_cndmask_b32_e32 v64, v67, v66, vcc
	v_not_b32_e32 v66, v65
	v_or_b32_e32 v67, 0x80000000, v65
	v_cmp_gt_i32_e32 vcc, 0, v65
	v_and_or_b32 v64, v64, s42, v152
	s_nop 0
	v_cndmask_b32_e32 v65, v67, v66, vcc
	v_max_u32_e32 v66, v34, v35
	v_min_u32_e32 v34, v34, v35
	v_max_u32_e32 v35, v18, v19
	v_min_u32_e32 v18, v18, v19
	v_max_u32_e32 v19, v2, v3
	v_min_u32_e32 v2, v2, v3
	v_max_u32_e32 v3, v50, v51
	v_min_u32_e32 v50, v50, v51
	v_max_u32_e32 v51, v36, v37
	v_min_u32_e32 v36, v36, v37
	v_max_u32_e32 v37, v20, v21
	v_min_u32_e32 v20, v20, v21
	v_max_u32_e32 v21, v4, v5
	v_min_u32_e32 v4, v4, v5
	v_max_u32_e32 v5, v52, v53
; DI void peer_topk_phase(const bf16_t* __restrict__ qpk, const bf16_t* __restrict__ subk, int* __restrict__ eidx, float* __restrict__ gout) {
;     ...
;             for (int n = 0; n < 63; ++n) { cex(g0[SORT16[n][0]], g0[SORT16[n][1]]); cex(g1[SORT16[n][0]], g1[SORT16[n][1]]); cex(g2[SORT16[n][0]], g2[SORT16[n][1]]); cex(g3[SORT16[n][0]], g3[SORT16[n][1]]); }
	v_min_u32_e32 v52, v52, v53
	v_max_u32_e32 v53, v66, v51
	v_min_u32_e32 v51, v66, v51
	v_max_u32_e32 v66, v35, v37
	v_min_u32_e32 v35, v35, v37
	v_max_u32_e32 v37, v19, v21
	v_min_u32_e32 v19, v19, v21
	v_max_u32_e32 v21, v3, v5
	v_min_u32_e32 v3, v3, v5
	v_max_u32_e32 v5, v34, v36
	v_min_u32_e32 v34, v34, v36
	v_max_u32_e32 v36, v18, v20
	v_min_u32_e32 v18, v18, v20
	v_max_u32_e32 v20, v2, v4
	v_min_u32_e32 v2, v2, v4
	v_max_u32_e32 v4, v50, v52
	v_min_u32_e32 v50, v50, v52
	v_max_u32_e32 v52, v5, v51
	v_min_u32_e32 v5, v5, v51
	v_max_u32_e32 v51, v36, v35
	v_min_u32_e32 v35, v36, v35
	v_max_u32_e32 v36, v20, v19
	v_min_u32_e32 v19, v20, v19
	v_max_u32_e32 v20, v4, v3
	v_min_u32_e32 v3, v4, v3
	v_max_u32_e32 v4, v38, v39
	v_min_u32_e32 v38, v38, v39
	v_max_u32_e32 v39, v22, v23
	v_min_u32_e32 v22, v22, v23
	v_max_u32_e32 v23, v6, v7
	v_min_u32_e32 v6, v6, v7
	v_max_u32_e32 v7, v54, v55
	v_min_u32_e32 v54, v54, v55
	v_max_u32_e32 v55, v40, v41
	v_min_u32_e32 v40, v40, v41
	v_max_u32_e32 v41, v24, v25
	v_min_u32_e32 v24, v24, v25
	v_max_u32_e32 v25, v8, v9
	v_min_u32_e32 v8, v8, v9
	v_max_u32_e32 v9, v56, v57
	v_min_u32_e32 v56, v56, v57
	v_max_u32_e32 v57, v4, v55
	v_min_u32_e32 v4, v4, v55
	v_max_u32_e32 v55, v39, v41
	v_min_u32_e32 v39, v39, v41
	v_max_u32_e32 v41, v23, v25
	v_min_u32_e32 v23, v23, v25
	v_max_u32_e32 v25, v7, v9
	v_min_u32_e32 v7, v7, v9
	v_max_u32_e32 v9, v38, v40
	v_min_u32_e32 v38, v38, v40
	v_max_u32_e32 v40, v22, v24
	v_min_u32_e32 v22, v22, v24
	v_max_u32_e32 v24, v6, v8
	v_min_u32_e32 v6, v6, v8
	v_max_u32_e32 v8, v54, v56
	v_min_u32_e32 v54, v54, v56
	v_max_u32_e32 v56, v9, v4
	v_min_u32_e32 v4, v9, v4
	v_max_u32_e32 v9, v40, v39
	v_min_u32_e32 v39, v40, v39
	v_max_u32_e32 v40, v24, v23
	v_min_u32_e32 v23, v24, v23
	v_max_u32_e32 v24, v8, v7
	v_min_u32_e32 v7, v8, v7
	v_max_u32_e32 v8, v53, v57
	v_min_u32_e32 v53, v53, v57
	v_max_u32_e32 v57, v66, v55
	v_min_u32_e32 v55, v66, v55
	v_max_u32_e32 v66, v37, v41
	v_min_u32_e32 v37, v37, v41
	v_max_u32_e32 v41, v21, v25
	v_min_u32_e32 v21, v21, v25
	v_max_u32_e32 v25, v5, v4
	v_min_u32_e32 v4, v5, v4
	v_max_u32_e32 v5, v35, v39
	v_min_u32_e32 v35, v35, v39
	v_max_u32_e32 v39, v19, v23
	v_min_u32_e32 v19, v19, v23
	v_max_u32_e32 v23, v3, v7
	v_min_u32_e32 v3, v3, v7
	v_max_u32_e32 v7, v25, v53
	v_min_u32_e32 v25, v25, v53
	v_max_u32_e32 v53, v5, v55
	v_min_u32_e32 v5, v5, v55
	v_max_u32_e32 v55, v39, v37
	v_min_u32_e32 v37, v39, v37
	v_max_u32_e32 v39, v23, v21
	v_min_u32_e32 v21, v23, v21
	v_max_u32_e32 v23, v52, v56
	v_min_u32_e32 v52, v52, v56
	v_max_u32_e32 v56, v51, v9
	v_min_u32_e32 v9, v51, v9
	v_max_u32_e32 v51, v36, v40
	v_min_u32_e32 v36, v36, v40
	v_max_u32_e32 v40, v20, v24
	v_min_u32_e32 v20, v20, v24
	v_max_u32_e32 v24, v34, v38
	v_min_u32_e32 v34, v34, v38
	v_max_u32_e32 v38, v18, v22
	v_min_u32_e32 v18, v18, v22
	v_max_u32_e32 v22, v2, v6
	v_min_u32_e32 v2, v2, v6
	v_max_u32_e32 v6, v50, v54
	v_min_u32_e32 v50, v50, v54
	v_max_u32_e32 v54, v24, v52
	v_min_u32_e32 v24, v24, v52
	v_max_u32_e32 v52, v38, v9
	v_min_u32_e32 v9, v38, v9
	v_max_u32_e32 v38, v22, v36
	v_min_u32_e32 v22, v22, v36
	v_max_u32_e32 v36, v6, v20
	v_min_u32_e32 v6, v6, v20
	v_max_u32_e32 v20, v23, v7
	v_min_u32_e32 v7, v23, v7
	v_max_u32_e32 v23, v56, v53
	v_min_u32_e32 v53, v56, v53
	v_max_u32_e32 v56, v51, v55
	v_min_u32_e32 v51, v51, v55
	v_max_u32_e32 v55, v40, v39
	v_min_u32_e32 v39, v40, v39
	v_max_u32_e32 v40, v54, v25
	v_min_u32_e32 v25, v54, v25
	v_max_u32_e32 v54, v52, v5
	v_min_u32_e32 v5, v52, v5
	v_max_u32_e32 v52, v38, v37
	v_min_u32_e32 v37, v38, v37
	v_max_u32_e32 v38, v36, v21
	v_min_u32_e32 v21, v36, v21
	v_max_u32_e32 v36, v24, v4
	v_min_u32_e32 v4, v24, v4
	v_max_u32_e32 v24, v9, v35
	v_min_u32_e32 v9, v9, v35
	v_max_u32_e32 v35, v22, v19
	v_min_u32_e32 v19, v22, v19
	v_max_u32_e32 v22, v6, v3
	v_min_u32_e32 v3, v6, v3
	v_max_u32_e32 v6, v42, v43
	v_min_u32_e32 v42, v42, v43
	v_max_u32_e32 v43, v26, v27
	v_min_u32_e32 v26, v26, v27
	v_max_u32_e32 v27, v10, v11
	v_min_u32_e32 v10, v10, v11
	v_max_u32_e32 v11, v58, v59
	v_min_u32_e32 v58, v58, v59
	v_max_u32_e32 v59, v44, v45
	v_min_u32_e32 v44, v44, v45
	v_max_u32_e32 v45, v28, v29
	v_min_u32_e32 v28, v28, v29
	v_max_u32_e32 v29, v12, v13
	v_min_u32_e32 v12, v12, v13
	v_max_u32_e32 v13, v60, v61
	v_min_u32_e32 v60, v60, v61
	v_and_or_b32 v65, v65, s42, v153
	v_max_u32_e32 v61, v6, v59
	v_min_u32_e32 v6, v6, v59
	v_max_u32_e32 v59, v43, v45
	v_min_u32_e32 v43, v43, v45
	v_max_u32_e32 v45, v27, v29
	v_min_u32_e32 v27, v27, v29
	v_max_u32_e32 v29, v11, v13
	v_min_u32_e32 v11, v11, v13
	v_max_u32_e32 v13, v42, v44
	v_min_u32_e32 v42, v42, v44
	v_max_u32_e32 v44, v26, v28
	v_min_u32_e32 v26, v26, v28
	v_max_u32_e32 v28, v10, v12
	v_min_u32_e32 v10, v10, v12
	v_max_u32_e32 v12, v58, v60
	v_min_u32_e32 v58, v58, v60
	v_max_u32_e32 v60, v13, v6
	v_min_u32_e32 v6, v13, v6
	v_max_u32_e32 v13, v44, v43
	v_min_u32_e32 v43, v44, v43
	v_max_u32_e32 v44, v28, v27
	v_min_u32_e32 v27, v28, v27
	v_max_u32_e32 v28, v12, v11
	v_min_u32_e32 v11, v12, v11
	v_max_u32_e32 v12, v46, v47
	v_min_u32_e32 v46, v46, v47
	v_max_u32_e32 v47, v30, v31
	v_min_u32_e32 v30, v30, v31
	v_max_u32_e32 v31, v14, v15
	v_min_u32_e32 v14, v14, v15
	v_max_u32_e32 v15, v62, v63
	v_min_u32_e32 v62, v62, v63
	v_max_u32_e32 v63, v48, v49
	v_min_u32_e32 v48, v48, v49
	v_max_u32_e32 v49, v32, v33
	v_min_u32_e32 v32, v32, v33
	v_max_u32_e32 v33, v16, v17
	v_min_u32_e32 v16, v16, v17
	v_max_u32_e32 v17, v64, v65
	v_min_u32_e32 v64, v64, v65
	v_max_u32_e32 v65, v12, v63
	v_min_u32_e32 v12, v12, v63
	v_max_u32_e32 v63, v47, v49
	v_min_u32_e32 v47, v47, v49
; DI void merge_top16(unsigned (&A)[16], const unsigned (&B)[16]) {
; #pragma unroll
;     for (int i = 0; i < 16; ++i) A[i] = max(A[i], B[15 - i]);
; #pragma unroll
;     for (int n = 0; n < 32; ++n) cex(A[BMERGE16[n][0]], A[BMERGE16[n][1]]);
; }
; DI void peer_topk_phase(const bf16_t* __restrict__ qpk, const bf16_t* __restrict__ subk, int* __restrict__ eidx, float* __restrict__ gout) {
;     ...
;             for (int n = 0; n < 63; ++n) { cex(g0[SORT16[n][0]], g0[SORT16[n][1]]); cex(g1[SORT16[n][0]], g1[SORT16[n][1]]); cex(g2[SORT16[n][0]], g2[SORT16[n][1]]); cex(g3[SORT16[n][0]], g3[SORT16[n][1]]); }
;             merge_top16(g0, g1); merge_top16(g2, g3); merge_top16(g0, g2);
	v_max_u32_e32 v49, v31, v33
	v_min_u32_e32 v31, v31, v33
	v_max_u32_e32 v33, v15, v17
	v_min_u32_e32 v15, v15, v17
	v_max_u32_e32 v17, v46, v48
	v_min_u32_e32 v46, v46, v48
	v_max_u32_e32 v48, v30, v32
	v_min_u32_e32 v30, v30, v32
	v_max_u32_e32 v32, v14, v16
	v_min_u32_e32 v14, v14, v16
	v_max_u32_e32 v16, v62, v64
	v_min_u32_e32 v62, v62, v64
	v_max_u32_e32 v64, v17, v12
	v_min_u32_e32 v12, v17, v12
	v_max_u32_e32 v17, v48, v47
	v_min_u32_e32 v47, v48, v47
	v_max_u32_e32 v48, v32, v31
	v_min_u32_e32 v31, v32, v31
	v_max_u32_e32 v32, v16, v15
	v_min_u32_e32 v15, v16, v15
	v_max_u32_e32 v16, v61, v65
	v_min_u32_e32 v61, v61, v65
	v_max_u32_e32 v65, v59, v63
	v_min_u32_e32 v59, v59, v63
	v_max_u32_e32 v63, v45, v49
	v_min_u32_e32 v45, v45, v49
	v_max_u32_e32 v49, v29, v33
	v_min_u32_e32 v29, v29, v33
	v_max_u32_e32 v33, v6, v12
	v_min_u32_e32 v6, v6, v12
	v_max_u32_e32 v12, v43, v47
	v_min_u32_e32 v43, v43, v47
	v_max_u32_e32 v47, v27, v31
	v_min_u32_e32 v27, v27, v31
	v_max_u32_e32 v31, v11, v15
	v_min_u32_e32 v11, v11, v15
	v_max_u32_e32 v15, v33, v61
	v_min_u32_e32 v33, v33, v61
	v_max_u32_e32 v61, v12, v59
	v_min_u32_e32 v12, v12, v59
	v_max_u32_e32 v59, v47, v45
	v_min_u32_e32 v45, v47, v45
	v_max_u32_e32 v47, v31, v29
	v_min_u32_e32 v29, v31, v29
	v_max_u32_e32 v31, v60, v64
	v_min_u32_e32 v60, v60, v64
	v_max_u32_e32 v64, v13, v17
	v_min_u32_e32 v13, v13, v17
	v_max_u32_e32 v17, v44, v48
	v_min_u32_e32 v44, v44, v48
	v_max_u32_e32 v48, v28, v32
	v_min_u32_e32 v28, v28, v32
	v_max_u32_e32 v32, v42, v46
	v_min_u32_e32 v42, v42, v46
	v_max_u32_e32 v46, v26, v30
	v_min_u32_e32 v26, v26, v30
	v_max_u32_e32 v30, v10, v14
	v_min_u32_e32 v10, v10, v14
	v_max_u32_e32 v14, v58, v62
	v_min_u32_e32 v58, v58, v62
	v_max_u32_e32 v62, v32, v60
	v_min_u32_e32 v32, v32, v60
	v_max_u32_e32 v60, v46, v13
	v_min_u32_e32 v13, v46, v13
	v_max_u32_e32 v46, v30, v44
	v_min_u32_e32 v30, v30, v44
	v_max_u32_e32 v44, v14, v28
	v_min_u32_e32 v14, v14, v28
	v_max_u32_e32 v28, v31, v15
	v_min_u32_e32 v15, v31, v15
	v_max_u32_e32 v31, v64, v61
	v_min_u32_e32 v61, v64, v61
	v_max_u32_e32 v64, v17, v59
	v_min_u32_e32 v17, v17, v59
	v_max_u32_e32 v59, v48, v47
	v_min_u32_e32 v47, v48, v47
	v_max_u32_e32 v48, v62, v33
	v_min_u32_e32 v33, v62, v33
	v_max_u32_e32 v62, v60, v12
	v_min_u32_e32 v12, v60, v12
	v_max_u32_e32 v60, v46, v45
	v_min_u32_e32 v45, v46, v45
	v_max_u32_e32 v46, v44, v29
	v_min_u32_e32 v29, v44, v29
	v_max_u32_e32 v44, v32, v6
	v_min_u32_e32 v6, v32, v6
	v_max_u32_e32 v32, v13, v43
	v_min_u32_e32 v13, v13, v43
	v_max_u32_e32 v43, v30, v27
	v_min_u32_e32 v27, v30, v27
	v_max_u32_e32 v30, v14, v11
	v_min_u32_e32 v11, v14, v11
	v_min_u32_e32 v14, v8, v16
	v_min_u32_e32 v67, v57, v65
	v_min_u32_e32 v68, v66, v63
	v_min_u32_e32 v69, v41, v49
	v_max_u32_e32 v70, v25, v33
	v_min_u32_e32 v25, v25, v33
	v_max_u32_e32 v33, v5, v12
	v_min_u32_e32 v5, v5, v12
	v_max_u32_e32 v12, v37, v45
	v_min_u32_e32 v37, v37, v45
	v_max_u32_e32 v45, v21, v29
	v_min_u32_e32 v21, v21, v29
	v_max_u32_e32 v29, v70, v14
	v_min_u32_e32 v14, v70, v14
	v_max_u32_e32 v70, v33, v67
	v_min_u32_e32 v33, v33, v67
	v_max_u32_e32 v67, v12, v68
	v_min_u32_e32 v12, v12, v68
	v_max_u32_e32 v68, v45, v69
	v_min_u32_e32 v45, v45, v69
	v_max_u32_e32 v69, v7, v15
	v_min_u32_e32 v7, v7, v15
	v_max_u32_e32 v15, v53, v61
	v_min_u32_e32 v53, v53, v61
	v_max_u32_e32 v61, v51, v17
	v_min_u32_e32 v17, v51, v17
	v_max_u32_e32 v51, v39, v47
	v_min_u32_e32 v39, v39, v47
	v_max_u32_e32 v47, v4, v6
	v_min_u32_e32 v4, v4, v6
	v_max_u32_e32 v6, v9, v13
	v_min_u32_e32 v9, v9, v13
	v_max_u32_e32 v13, v19, v27
	v_min_u32_e32 v19, v19, v27
	v_max_u32_e32 v27, v3, v11
	v_min_u32_e32 v3, v3, v11
	v_max_u32_e32 v11, v47, v7
	v_min_u32_e32 v7, v47, v7
	v_max_u32_e32 v47, v6, v53
	v_min_u32_e32 v6, v6, v53
	v_max_u32_e32 v53, v13, v17
	v_min_u32_e32 v13, v13, v17
	v_max_u32_e32 v17, v27, v39
	v_min_u32_e32 v27, v27, v39
	v_max_u32_e32 v39, v69, v29
	v_min_u32_e32 v29, v69, v29
	v_max_u32_e32 v69, v15, v70
	v_min_u32_e32 v15, v15, v70
	v_max_u32_e32 v70, v61, v67
	v_min_u32_e32 v61, v61, v67
	v_max_u32_e32 v67, v51, v68
	v_min_u32_e32 v51, v51, v68
	v_max_u32_e32 v68, v11, v14
	v_min_u32_e32 v11, v11, v14
	v_max_u32_e32 v14, v47, v33
	v_min_u32_e32 v33, v47, v33
	v_max_u32_e32 v47, v53, v12
	v_min_u32_e32 v12, v53, v12
	v_max_u32_e32 v53, v17, v45
	v_min_u32_e32 v17, v17, v45
	v_max_u32_e32 v45, v7, v25
	v_min_u32_e32 v7, v7, v25
	v_max_u32_e32 v25, v6, v5
	v_min_u32_e32 v5, v6, v5
	v_max_u32_e32 v6, v13, v37
	v_min_u32_e32 v13, v13, v37
	v_max_u32_e32 v37, v27, v21
	v_min_u32_e32 v21, v27, v21
	v_max_u32_e32 v27, v20, v28
	v_min_u32_e32 v20, v20, v28
	v_max_u32_e32 v28, v23, v31
	v_min_u32_e32 v23, v23, v31
	v_max_u32_e32 v31, v56, v64
	v_min_u32_e32 v56, v56, v64
	v_max_u32_e32 v64, v55, v59
	v_min_u32_e32 v55, v55, v59
	v_max_u32_e32 v59, v36, v44
	v_min_u32_e32 v36, v36, v44
	v_max_u32_e32 v44, v24, v32
	v_min_u32_e32 v24, v24, v32
	v_max_u32_e32 v32, v35, v43
	v_min_u32_e32 v35, v35, v43
	v_max_u32_e32 v43, v22, v30
	v_min_u32_e32 v22, v22, v30
	v_max_u32_e32 v30, v59, v20
	v_min_u32_e32 v20, v59, v20
	v_max_u32_e32 v59, v44, v23
	v_min_u32_e32 v23, v44, v23
	v_max_u32_e32 v44, v32, v56
	v_min_u32_e32 v32, v32, v56
	v_max_u32_e32 v56, v43, v55
	v_min_u32_e32 v43, v43, v55
	v_max_u32_e32 v55, v40, v48
	v_min_u32_e32 v40, v40, v48
	v_max_u32_e32 v48, v54, v62
	v_min_u32_e32 v54, v54, v62
	v_max_u32_e32 v62, v52, v60
	v_min_u32_e32 v52, v52, v60
	v_max_u32_e32 v60, v38, v46
	v_min_u32_e32 v38, v38, v46
	v_max_u32_e32 v46, v34, v42
	v_min_u32_e32 v34, v34, v42
	v_max_u32_e32 v42, v18, v26
	v_min_u32_e32 v18, v18, v26
; DI void merge_top16(unsigned (&A)[16], const unsigned (&B)[16]) {
; #pragma unroll
;     for (int i = 0; i < 16; ++i) A[i] = max(A[i], B[15 - i]);
; #pragma unroll
;     for (int n = 0; n < 32; ++n) cex(A[BMERGE16[n][0]], A[BMERGE16[n][1]]);
; }
; DI void peer_topk_phase(const bf16_t* __restrict__ qpk, const bf16_t* __restrict__ subk, int* __restrict__ eidx, float* __restrict__ gout) {
;     ...
;             merge_top16(g0, g1); merge_top16(g2, g3); merge_top16(g0, g2);
	v_max_u32_e32 v26, v2, v10
	v_min_u32_e32 v2, v2, v10
	v_max_u32_e32 v10, v50, v58
	v_min_u32_e32 v50, v50, v58
	v_max_u32_e32 v58, v46, v40
	v_min_u32_e32 v40, v46, v40
	v_max_u32_e32 v46, v42, v54
	v_min_u32_e32 v42, v42, v54
	v_max_u32_e32 v54, v26, v52
	v_min_u32_e32 v26, v26, v52
	v_max_u32_e32 v52, v10, v38
	v_min_u32_e32 v10, v10, v38
	v_max_u32_e32 v38, v55, v30
	v_min_u32_e32 v30, v55, v30
	v_max_u32_e32 v55, v48, v59
	v_min_u32_e32 v48, v48, v59
	v_max_u32_e32 v59, v62, v44
	v_min_u32_e32 v44, v62, v44
	v_max_u32_e32 v62, v60, v56
	v_min_u32_e32 v56, v60, v56
	v_max_u32_e32 v60, v58, v20
	v_min_u32_e32 v20, v58, v20
	v_max_u32_e32 v58, v46, v23
	v_min_u32_e32 v23, v46, v23
	v_max_u32_e32 v46, v54, v32
	v_min_u32_e32 v32, v54, v32
	v_max_u32_e32 v54, v52, v43
	v_min_u32_e32 v43, v52, v43
	v_max_u32_e32 v52, v40, v36
	v_min_u32_e32 v36, v40, v36
	v_max_u32_e32 v40, v42, v24
	v_min_u32_e32 v24, v42, v24
	v_max_u32_e32 v42, v26, v35
	v_min_u32_e32 v26, v26, v35
	v_max_u32_e32 v35, v10, v22
	v_min_u32_e32 v10, v10, v22
	v_min_u32_e32 v22, v27, v39
	v_min_u32_e32 v71, v28, v69
	v_min_u32_e32 v72, v31, v70
	v_min_u32_e32 v73, v64, v67
	v_min_u32_e32 v82, v38, v29
	v_min_u32_e32 v83, v55, v15
	v_min_u32_e32 v183, v59, v61
	v_min_u32_e32 v184, v62, v51
	v_min_u32_e32 v185, v30, v68
	v_min_u32_e32 v186, v48, v14
	v_min_u32_e32 v187, v44, v47
	v_min_u32_e32 v188, v56, v53
	v_min_u32_e32 v189, v60, v11
	v_min_u32_e32 v190, v58, v33
	v_min_u32_e32 v191, v46, v12
	v_min_u32_e32 v198, v54, v17
	v_min_u32_e32 v199, v20, v45
	v_min_u32_e32 v200, v23, v25
	v_min_u32_e32 v201, v32, v6
	v_min_u32_e32 v202, v43, v37
	v_min_u32_e32 v203, v52, v7
	v_min_u32_e32 v210, v40, v5
	v_min_u32_e32 v211, v42, v13
	v_min_u32_e32 v212, v35, v21
	v_min_u32_e32 v213, v36, v4
	v_min_u32_e32 v214, v24, v9
	v_min_u32_e32 v215, v26, v19
	v_min_u32_e32 v216, v10, v3
	v_max3_u32 v8, v8, v16, v18
	v_max3_u32 v16, v27, v39, v214
	v_max3_u32 v9, v22, v24, v9
	v_max3_u32 v18, v38, v29, v210
	v_max3_u32 v5, v82, v40, v5
	v_max3_u32 v22, v30, v68, v200
	v_max3_u32 v23, v185, v23, v25
	v_max3_u32 v11, v60, v11, v190
	v_max3_u32 v24, v189, v58, v33
	v_max3_u32 v20, v20, v45, v186
	v_max3_u32 v14, v199, v48, v14
	v_max3_u32 v7, v52, v7, v83
	v_max3_u32 v15, v203, v55, v15
	v_max3_u32 v4, v36, v4, v71
	v_max3_u32 v25, v213, v28, v69
	v_max3_u32 v27, v34, v57, v65
	v_max3_u32 v40, v66, v63, v50
	v_max3_u32 v31, v31, v70, v216
	v_max3_u32 v3, v72, v10, v3
	v_max3_u32 v10, v59, v61, v212
	v_max3_u32 v21, v183, v35, v21
	v_max3_u32 v35, v44, v47, v202
	v_max3_u32 v37, v187, v43, v37
	v_max3_u32 v12, v46, v12, v198
	v_max3_u32 v17, v191, v54, v17
	v_max3_u32 v6, v32, v6, v188
	v_max3_u32 v32, v201, v56, v53
	v_max3_u32 v13, v42, v13, v184
	v_max3_u32 v42, v211, v62, v51
	v_max3_u32 v19, v26, v19, v73
	v_max3_u32 v26, v215, v64, v67
	v_max3_u32 v2, v2, v41, v49
	v_max_u32_e32 v28, v8, v24
	v_min_u32_e32 v8, v8, v24
	v_max_u32_e32 v24, v16, v20
	v_min_u32_e32 v16, v16, v20
	v_max_u32_e32 v20, v9, v14
	v_min_u32_e32 v9, v9, v14
	v_max_u32_e32 v14, v18, v7
	v_min_u32_e32 v7, v18, v7
	v_max_u32_e32 v18, v5, v15
	v_min_u32_e32 v5, v5, v15
	v_max_u32_e32 v15, v22, v4
	v_min_u32_e32 v4, v22, v4
	v_max_u32_e32 v22, v23, v25
	v_min_u32_e32 v23, v23, v25
	v_max_u32_e32 v25, v11, v27
	v_min_u32_e32 v11, v11, v27
	v_max_u32_e32 v41, v40, v17
	v_min_u32_e32 v17, v40, v17
	v_max_u32_e32 v40, v31, v6
	v_min_u32_e32 v6, v31, v6
	v_max_u32_e32 v31, v3, v32
	v_min_u32_e32 v3, v3, v32
	v_max_u32_e32 v32, v10, v13
	v_min_u32_e32 v10, v10, v13
	v_max_u32_e32 v13, v21, v42
	v_min_u32_e32 v21, v21, v42
	v_max_u32_e32 v42, v35, v19
	v_min_u32_e32 v19, v35, v19
	v_max_u32_e32 v35, v37, v26
	v_min_u32_e32 v26, v37, v26
	v_max_u32_e32 v37, v12, v2
	v_min_u32_e32 v2, v12, v2
	v_max_u32_e32 v27, v28, v18
	v_min_u32_e32 v18, v28, v18
	v_max_u32_e32 v28, v24, v15
	v_min_u32_e32 v15, v24, v15
	v_max_u32_e32 v24, v20, v22
	v_min_u32_e32 v20, v20, v22
	v_max_u32_e32 v22, v14, v25
	v_min_u32_e32 v14, v14, v25
	v_max_u32_e32 v25, v8, v5
	v_min_u32_e32 v5, v8, v5
	v_max_u32_e32 v8, v16, v4
	v_min_u32_e32 v4, v16, v4
	v_max_u32_e32 v16, v9, v23
	v_min_u32_e32 v9, v9, v23
	v_max_u32_e32 v23, v7, v11
	v_min_u32_e32 v7, v7, v11
	v_max_u32_e32 v12, v41, v13
	v_min_u32_e32 v13, v41, v13
	v_max_u32_e32 v41, v40, v42
	v_min_u32_e32 v40, v40, v42
	v_max_u32_e32 v42, v31, v35
	v_min_u32_e32 v31, v31, v35
	v_max_u32_e32 v35, v32, v37
	v_min_u32_e32 v32, v32, v37
	v_max_u32_e32 v37, v17, v21
	v_min_u32_e32 v17, v17, v21
	v_max_u32_e32 v21, v6, v19
	v_min_u32_e32 v6, v6, v19
	v_max_u32_e32 v19, v3, v26
	v_min_u32_e32 v3, v3, v26
	v_max_u32_e32 v26, v10, v2
	v_min_u32_e32 v2, v10, v2
	v_max_u32_e32 v11, v27, v24
	v_min_u32_e32 v24, v27, v24
	v_max_u32_e32 v27, v28, v22
	v_min_u32_e32 v22, v28, v22
	v_max_u32_e32 v28, v18, v20
	v_min_u32_e32 v18, v18, v20
	v_max_u32_e32 v20, v15, v14
	v_min_u32_e32 v14, v15, v14
	v_max_u32_e32 v15, v25, v16
	v_min_u32_e32 v16, v25, v16
	v_max_u32_e32 v25, v8, v23
	v_min_u32_e32 v8, v8, v23
	v_max_u32_e32 v23, v5, v9
	v_min_u32_e32 v5, v5, v9
	v_max_u32_e32 v9, v4, v7
	v_min_u32_e32 v4, v4, v7
	v_max_u32_e32 v10, v12, v42
	v_min_u32_e32 v12, v12, v42
	v_max_u32_e32 v42, v41, v35
	v_min_u32_e32 v35, v41, v35
	v_max_u32_e32 v41, v13, v31
	v_min_u32_e32 v13, v13, v31
	v_max_u32_e32 v31, v40, v32
	v_min_u32_e32 v32, v40, v32
	v_max_u32_e32 v40, v37, v19
	v_min_u32_e32 v19, v37, v19
	v_max_u32_e32 v37, v21, v26
	v_min_u32_e32 v21, v21, v26
	v_max_u32_e32 v26, v17, v3
	v_min_u32_e32 v3, v17, v3
	v_max_u32_e32 v17, v6, v2
	v_min_u32_e32 v2, v6, v2
	v_min_u32_e32 v7, v11, v27
	v_min_u32_e32 v29, v24, v22
; DI unsigned f2ord(float f) { const unsigned u = __float_as_uint(f); return (u & 0x80000000u) ? ~u : (u | 0x80000000u); }
; DI float ord2f(unsigned o) { const unsigned u = (o & 0x80000000u) ? (o & 0x7fffffffu) : ~o; return __uint_as_float(u); }
; DI void peer_topk_phase(const bf16_t* __restrict__ qpk, const bf16_t* __restrict__ subk, int* __restrict__ eidx, float* __restrict__ gout) {
;     ...
;             merge_top16(g0, g1); merge_top16(g2, g3); merge_top16(g0, g2);
;             unsigned pb[16];
; #pragma unroll
;             for (int i = 0; i < 16; ++i) pb[i] = (unsigned)__shfl_xor((int)g0[i], 32);
;             merge_top16(g0, pb);
; #pragma unroll
;             for (int i = 0; i < 16; ++i) top[c][i] = g0[i];
;         }
;         unsigned ck[50];
; #pragma unroll
;         for (int a = 0; a < 16; ++a)
; #pragma unroll
;             for (int b = 0; b < 16 / (a + 1); ++b) {
;                 const float cv = ord2f(top[0][a] & ~127u) + ord2f(top[1][b] & ~127u);
;                 ck[combo_row_start(a) + b] = (f2ord(cv) & ~255u) | (unsigned)(((15 - a) << 4) | (15 - b));
;             }
	v_min_u32_e32 v30, v28, v20
	v_min_u32_e32 v33, v18, v14
	v_min_u32_e32 v34, v15, v25
	v_min_u32_e32 v36, v16, v8
	v_min_u32_e32 v38, v23, v9
	v_min_u32_e32 v39, v5, v4
	v_min_u32_e32 v6, v10, v42
	v_min_u32_e32 v43, v12, v35
	v_min_u32_e32 v44, v41, v31
	v_min_u32_e32 v45, v13, v32
	v_min_u32_e32 v46, v40, v37
	v_min_u32_e32 v47, v19, v21
	v_min_u32_e32 v48, v26, v17
	v_min_u32_e32 v49, v3, v2
	v_max3_u32 v11, v11, v27, v49
	v_max3_u32 v2, v7, v3, v2
	v_max3_u32 v3, v24, v22, v48
	v_max3_u32 v7, v29, v26, v17
	v_max3_u32 v17, v28, v20, v47
	v_max3_u32 v19, v30, v19, v21
	v_max3_u32 v14, v18, v14, v46
	v_max3_u32 v18, v33, v40, v37
	v_max3_u32 v15, v15, v25, v45
	v_max3_u32 v13, v34, v13, v32
	v_max3_u32 v8, v16, v8, v44
	v_max3_u32 v16, v36, v41, v31
	v_max3_u32 v9, v23, v9, v43
	v_max3_u32 v12, v38, v12, v35
	v_max3_u32 v4, v5, v4, v6
	v_max3_u32 v5, v39, v10, v42
	v_max_u32_e32 v6, v11, v15
	v_min_u32_e32 v10, v11, v15
	v_max_u32_e32 v11, v2, v13
	v_min_u32_e32 v2, v2, v13
	v_max_u32_e32 v13, v3, v8
	v_min_u32_e32 v3, v3, v8
	v_max_u32_e32 v8, v7, v16
	v_min_u32_e32 v7, v7, v16
	v_max_u32_e32 v15, v17, v9
	v_min_u32_e32 v9, v17, v9
	v_max_u32_e32 v16, v19, v12
	v_min_u32_e32 v12, v19, v12
	v_max_u32_e32 v17, v14, v4
	v_min_u32_e32 v4, v14, v4
	v_max_u32_e32 v14, v18, v5
	v_min_u32_e32 v5, v18, v5
	v_max_u32_e32 v18, v6, v15
	v_min_u32_e32 v6, v6, v15
	v_max_u32_e32 v15, v11, v16
	v_min_u32_e32 v11, v11, v16
	v_max_u32_e32 v16, v13, v17
	v_min_u32_e32 v13, v13, v17
	v_max_u32_e32 v17, v8, v14
	v_min_u32_e32 v8, v8, v14
	v_max_u32_e32 v14, v10, v9
	v_min_u32_e32 v9, v10, v9
	v_max_u32_e32 v10, v2, v12
	v_min_u32_e32 v2, v2, v12
	v_max_u32_e32 v12, v3, v4
	v_min_u32_e32 v3, v3, v4
	v_max_u32_e32 v4, v7, v5
	v_min_u32_e32 v5, v7, v5
	v_max_u32_e32 v7, v18, v16
	v_min_u32_e32 v16, v18, v16
	v_max_u32_e32 v18, v15, v17
	v_min_u32_e32 v15, v15, v17
	v_max_u32_e32 v17, v6, v13
	v_min_u32_e32 v6, v6, v13
	v_max_u32_e32 v13, v11, v8
	v_min_u32_e32 v8, v11, v8
	v_max_u32_e32 v11, v14, v12
	v_min_u32_e32 v12, v14, v12
	v_max_u32_e32 v14, v10, v4
	v_min_u32_e32 v4, v10, v4
	v_max_u32_e32 v10, v9, v3
	v_min_u32_e32 v3, v9, v3
	v_max_u32_e32 v9, v2, v5
	v_min_u32_e32 v2, v2, v5
	v_max_u32_e32 v5, v7, v18
	v_min_u32_e32 v7, v7, v18
	v_max_u32_e32 v18, v16, v15
	v_min_u32_e32 v15, v16, v15
	v_max_u32_e32 v16, v17, v13
	v_min_u32_e32 v13, v17, v13
	v_max_u32_e32 v17, v6, v8
	v_min_u32_e32 v6, v6, v8
	v_max_u32_e32 v8, v11, v14
	v_min_u32_e32 v11, v11, v14
	v_max_u32_e32 v14, v12, v4
	v_min_u32_e32 v4, v12, v4
	v_max_u32_e32 v12, v10, v9
	v_min_u32_e32 v9, v10, v9
	v_max_u32_e32 v10, v3, v2
	v_min_u32_e32 v2, v3, v2
	ds_bpermute_b32 v3, v173, v5
	ds_bpermute_b32 v19, v173, v7
	ds_bpermute_b32 v20, v173, v18
	ds_bpermute_b32 v21, v173, v15
	ds_bpermute_b32 v22, v173, v16
	ds_bpermute_b32 v23, v173, v13
	ds_bpermute_b32 v24, v173, v17
	ds_bpermute_b32 v25, v173, v6
	ds_bpermute_b32 v26, v173, v8
	ds_bpermute_b32 v27, v173, v11
	ds_bpermute_b32 v28, v173, v14
	ds_bpermute_b32 v29, v173, v4
	ds_bpermute_b32 v30, v173, v12
	ds_bpermute_b32 v31, v173, v9
	ds_bpermute_b32 v32, v173, v10
	ds_bpermute_b32 v33, v173, v2
	s_waitcnt lgkmcnt(4)
	v_max_u32_e32 v16, v16, v29
	s_waitcnt lgkmcnt(3)
	v_max_u32_e32 v15, v15, v30
	s_waitcnt lgkmcnt(2)
	v_max_u32_e32 v18, v18, v31
	s_waitcnt lgkmcnt(1)
	v_max_u32_e32 v7, v7, v32
	s_waitcnt lgkmcnt(0)
	v_max_u32_e32 v5, v5, v33
	v_max_u32_e32 v13, v13, v28
	v_max_u32_e32 v17, v17, v27
	v_max_u32_e32 v6, v6, v26
	v_max_u32_e32 v8, v8, v25
	v_max_u32_e32 v11, v11, v24
	v_max_u32_e32 v14, v14, v23
	v_max_u32_e32 v4, v4, v22
	v_max_u32_e32 v12, v12, v21
	v_max_u32_e32 v9, v9, v20
	v_max_u32_e32 v10, v10, v19
	v_max_u32_e32 v2, v2, v3
	v_max_u32_e32 v3, v5, v8
	v_min_u32_e32 v5, v5, v8
	v_max_u32_e32 v8, v7, v11
	v_min_u32_e32 v7, v7, v11
	v_max_u32_e32 v11, v18, v14
	v_min_u32_e32 v14, v18, v14
	v_max_u32_e32 v18, v15, v4
	v_min_u32_e32 v4, v15, v4
	v_max_u32_e32 v15, v16, v12
	v_min_u32_e32 v12, v16, v12
	v_max_u32_e32 v16, v13, v9
	v_min_u32_e32 v9, v13, v9
	v_max_u32_e32 v13, v17, v10
	v_min_u32_e32 v10, v17, v10
	v_max_u32_e32 v17, v6, v2
	v_min_u32_e32 v2, v6, v2
	v_max_u32_e32 v6, v3, v15
	v_min_u32_e32 v3, v3, v15
	v_max_u32_e32 v15, v8, v16
	v_min_u32_e32 v8, v8, v16
	v_max_u32_e32 v16, v11, v13
	v_min_u32_e32 v11, v11, v13
	v_max_u32_e32 v13, v18, v17
	v_min_u32_e32 v17, v18, v17
	v_max_u32_e32 v18, v5, v12
	v_min_u32_e32 v5, v5, v12
	v_max_u32_e32 v12, v7, v9
	v_min_u32_e32 v7, v7, v9
	v_max_u32_e32 v9, v14, v10
	v_min_u32_e32 v10, v14, v10
	v_max_u32_e32 v14, v4, v2
	v_min_u32_e32 v2, v4, v2
	v_max_u32_e32 v4, v6, v16
	v_min_u32_e32 v6, v6, v16
	v_max_u32_e32 v16, v15, v13
	v_min_u32_e32 v13, v15, v13
	v_max_u32_e32 v15, v3, v11
	v_min_u32_e32 v3, v3, v11
	v_max_u32_e32 v11, v8, v17
	v_min_u32_e32 v8, v8, v17
	v_max_u32_e32 v23, v18, v9
	v_min_u32_e32 v9, v18, v9
	v_max_u32_e32 v18, v15, v11
	v_min_u32_e32 v17, v15, v11
	v_max_u32_e32 v24, v12, v14
	v_min_u32_e32 v25, v12, v14
	v_max_u32_e32 v26, v5, v10
	v_min_u32_e32 v27, v5, v10
	v_max_u32_e32 v5, v7, v2
	v_min_u32_e32 v2, v7, v2
	v_max_u32_e32 v21, v6, v13
	v_min_u32_e32 v19, v6, v13
	v_and_b32_e32 v6, 0xffffff80, v18
	v_and_b32_e32 v7, 0xffffff80, v17
	v_max_u32_e32 v20, v4, v16
	v_min_u32_e32 v22, v4, v16
	v_max_u32_e32 v16, v3, v8
	v_min_u32_e32 v15, v3, v8
	v_max_u32_e32 v14, v23, v24
	v_min_u32_e32 v13, v23, v24
	v_max_u32_e32 v12, v9, v25
	v_min_u32_e32 v11, v9, v25
	v_max_u32_e32 v10, v26, v5
	v_min_u32_e32 v9, v26, v5
	v_max_u32_e32 v5, v27, v2
	v_min_u32_e32 v3, v27, v2
	v_cmp_gt_i32_e32 vcc, 0, v17
	v_cmp_gt_i32_e64 s[0:1], 0, v18
	v_and_b32_e32 v2, 0x7fffff80, v18
; DI unsigned f2ord(float f) { const unsigned u = __float_as_uint(f); return (u & 0x80000000u) ? ~u : (u | 0x80000000u); }
; DI float ord2f(unsigned o) { const unsigned u = (o & 0x80000000u) ? (o & 0x7fffffffu) : ~o; return __uint_as_float(u); }
; DI void peer_topk_phase(const bf16_t* __restrict__ qpk, const bf16_t* __restrict__ subk, int* __restrict__ eidx, float* __restrict__ gout) {
;     ...
;         unsigned ck[50];
; #pragma unroll
;         for (int a = 0; a < 16; ++a)
; #pragma unroll
;             for (int b = 0; b < 16 / (a + 1); ++b) {
;                 const float cv = ord2f(top[0][a] & ~127u) + ord2f(top[1][b] & ~127u);
;                 ck[combo_row_start(a) + b] = (f2ord(cv) & ~255u) | (unsigned)(((15 - a) << 4) | (15 - b));
;             }
	v_and_b32_e32 v4, 0x7fffff80, v17
	v_xor_b32_e32 v6, -1, v6
	v_xor_b32_e32 v8, -1, v7
	v_cndmask_b32_e64 v7, v6, v2, s[0:1]
	v_cndmask_b32_e32 v6, v8, v4, vcc
	v_cmp_gt_i32_e32 vcc, 0, v15
	v_and_b32_e32 v2, 0x7fffff80, v15
	v_bitop3_b32 v4, v15, s5, v15 bitop3:0xcf
	v_and_b32_e32 v8, 0xffffff80, v14
	v_and_b32_e32 v23, 0xffffff80, v13
	v_cndmask_b32_e32 v36, v4, v2, vcc
	v_cmp_gt_i32_e32 vcc, 0, v13
	v_cmp_gt_i32_e64 s[0:1], 0, v14
	v_and_b32_e32 v2, 0x7fffff80, v14
	v_and_b32_e32 v4, 0x7fffff80, v13
	v_xor_b32_e32 v8, -1, v8
	v_xor_b32_e32 v23, -1, v23
	v_cndmask_b32_e64 v27, v8, v2, s[0:1]
	v_cndmask_b32_e32 v26, v23, v4, vcc
	v_and_b32_e32 v8, 0xffffff80, v12
	v_and_b32_e32 v23, 0xffffff80, v11
	v_cmp_gt_i32_e32 vcc, 0, v11
	v_cmp_gt_i32_e64 s[0:1], 0, v12
	v_and_b32_e32 v2, 0x7fffff80, v12
	v_and_b32_e32 v4, 0x7fffff80, v11
	v_xor_b32_e32 v8, -1, v8
	v_xor_b32_e32 v23, -1, v23
	v_cndmask_b32_e64 v29, v8, v2, s[0:1]
	v_cndmask_b32_e32 v28, v23, v4, vcc
	v_and_b32_e32 v8, 0xffffff80, v10
	v_and_b32_e32 v23, 0xffffff80, v9
	v_cmp_gt_i32_e32 vcc, 0, v9
	v_cmp_gt_i32_e64 s[0:1], 0, v10
	v_and_b32_e32 v2, 0x7fffff80, v10
	v_and_b32_e32 v4, 0x7fffff80, v9
	v_xor_b32_e32 v8, -1, v8
	v_xor_b32_e32 v23, -1, v23
	v_cndmask_b32_e64 v31, v8, v2, s[0:1]
	v_cndmask_b32_e32 v30, v23, v4, vcc
	v_cmp_gt_i32_e32 vcc, 0, v5
	v_and_b32_e32 v2, 0x7fffff80, v5
	v_bitop3_b32 v4, v5, s5, v5 bitop3:0xcf
	v_and_b32_e32 v8, 0xffffff80, v3
	v_and_b32_e32 v23, 0xffffff80, v168
	v_cndmask_b32_e32 v33, v4, v2, vcc
	v_cmp_gt_i32_e32 vcc, 0, v168
	v_cmp_gt_i32_e64 s[0:1], 0, v3
	v_and_b32_e32 v2, 0x7fffff80, v3
	v_and_b32_e32 v4, 0x7fffff80, v168
	v_xor_b32_e32 v8, -1, v8
	v_xor_b32_e32 v23, -1, v23
	v_cndmask_b32_e64 v32, v8, v2, s[0:1]
	v_cndmask_b32_e32 v2, v23, v4, vcc
	v_pk_add_f32 v[24:25], v[2:3], v[6:7] op_sel_hi:[0,1]
	v_not_b32_e32 v4, v25
	v_or_b32_e32 v8, 0x80000000, v25
	v_cmp_gt_i32_e64 s[0:1], 0, v25
	v_cmp_gt_i32_e32 vcc, 0, v24
	v_pk_add_f32 v[34:35], v[2:3], v[26:27] op_sel_hi:[0,1]
	v_cndmask_b32_e64 v4, v8, v4, s[0:1]
	v_and_b32_e32 v4, 0xffffff00, v4
	v_or_b32_e32 v23, 0xfb, v4
	v_not_b32_e32 v4, v24
	v_or_b32_e32 v8, 0x80000000, v24
	v_cndmask_b32_e32 v4, v8, v4, vcc
	v_and_b32_e32 v4, 0xffffff00, v4
	v_or_b32_e32 v24, 0xfa, v4
	v_add_f32_e32 v4, v2, v36
	v_cmp_gt_i32_e32 vcc, 0, v4
	v_not_b32_e32 v8, v4
	v_or_b32_e32 v4, 0x80000000, v4
	v_cndmask_b32_e32 v4, v4, v8, vcc
	v_and_b32_e32 v4, 0xffffff00, v4
	v_or_b32_e32 v25, 0xf8, v4
	v_not_b32_e32 v4, v35
	v_or_b32_e32 v8, 0x80000000, v35
	v_cmp_gt_i32_e64 s[0:1], 0, v35
	v_cmp_gt_i32_e32 vcc, 0, v34
	v_and_b32_e32 v43, 0x7fffff80, v159
	v_cndmask_b32_e64 v4, v8, v4, s[0:1]
	v_and_b32_e32 v4, 0xffffff00, v4
	v_or_b32_e32 v26, 0xf7, v4
	v_not_b32_e32 v4, v34
	v_or_b32_e32 v8, 0x80000000, v34
	v_cndmask_b32_e32 v4, v8, v4, vcc
	v_and_b32_e32 v4, 0xffffff00, v4
	v_pk_add_f32 v[34:35], v[2:3], v[28:29] op_sel_hi:[0,1]
	v_or_b32_e32 v27, 0xf6, v4
	v_not_b32_e32 v4, v35
	v_or_b32_e32 v8, 0x80000000, v35
	v_cmp_gt_i32_e64 s[0:1], 0, v35
	v_cmp_gt_i32_e32 vcc, 0, v34
	v_and_b32_e32 v45, 0x7fffff80, v157
	v_cndmask_b32_e64 v4, v8, v4, s[0:1]
	v_and_b32_e32 v4, 0xffffff00, v4
	v_or_b32_e32 v28, 0xf5, v4
	v_not_b32_e32 v4, v34
	v_or_b32_e32 v8, 0x80000000, v34
	v_cndmask_b32_e32 v4, v8, v4, vcc
	v_and_b32_e32 v4, 0xffffff00, v4
	v_pk_add_f32 v[34:35], v[2:3], v[30:31] op_sel_hi:[0,1]
	v_or_b32_e32 v29, 0xf4, v4
	v_not_b32_e32 v4, v35
	v_or_b32_e32 v8, 0x80000000, v35
	v_cmp_gt_i32_e64 s[0:1], 0, v35
	v_cmp_gt_i32_e32 vcc, 0, v34
	v_and_b32_e32 v69, 0x7fffff80, v20
	v_cndmask_b32_e64 v4, v8, v4, s[0:1]
	v_and_b32_e32 v4, 0xffffff00, v4
	v_or_b32_e32 v30, 0xf3, v4
	v_not_b32_e32 v4, v34
	v_or_b32_e32 v8, 0x80000000, v34
	v_cndmask_b32_e32 v4, v8, v4, vcc
	v_and_b32_e32 v4, 0xffffff00, v4
	v_pk_add_f32 v[34:35], v[2:3], v[32:33] op_sel_hi:[0,1]
	v_or_b32_e32 v31, 0xf2, v4
	v_not_b32_e32 v4, v35
	v_or_b32_e32 v8, 0x80000000, v35
	v_cmp_gt_i32_e64 s[0:1], 0, v35
	v_cmp_gt_i32_e32 vcc, 0, v34
	v_and_b32_e32 v35, 0x7fffff80, v182
	v_cndmask_b32_e64 v4, v8, v4, s[0:1]
	v_and_b32_e32 v4, 0xffffff00, v4
	v_or_b32_e32 v32, 0xf1, v4
	v_not_b32_e32 v4, v34
	v_or_b32_e32 v8, 0x80000000, v34
	v_cndmask_b32_e32 v4, v8, v4, vcc
	v_and_b32_e32 v4, 0xffffff00, v4
	v_or_b32_e32 v33, 0xf0, v4
	v_and_b32_e32 v4, 0xffffff80, v16
	v_cmp_gt_i32_e32 vcc, 0, v16
	v_and_b32_e32 v34, 0x7fffff80, v16
	v_xor_b32_e32 v37, -1, v4
	v_and_b32_e32 v8, 0xffffff80, v182
	v_cndmask_b32_e32 v37, v37, v34, vcc
	v_xor_b32_e32 v4, -1, v8
	v_add_f32_e32 v8, v37, v2
	v_cmp_gt_i32_e64 s[0:1], 0, v182
	v_cmp_gt_i32_e32 vcc, 0, v8
	v_not_b32_e32 v34, v8
	v_or_b32_e32 v8, 0x80000000, v8
	v_cndmask_b32_e64 v4, v4, v35, s[0:1]
	v_cndmask_b32_e32 v8, v8, v34, vcc
	v_and_b32_e32 v8, 0xffffff00, v8
	v_pk_add_f32 v[38:39], v[4:5], v[6:7] op_sel_hi:[0,1]
	v_or_b32_e32 v34, 0xf9, v8
	v_not_b32_e32 v6, v39
	v_or_b32_e32 v8, 0x80000000, v39
	v_cmp_gt_i32_e64 s[0:1], 0, v39
	v_cmp_gt_i32_e32 vcc, 0, v38
	v_pk_add_f32 v[36:37], v[4:5], v[36:37] op_sel_hi:[0,1]
	v_cndmask_b32_e64 v6, v8, v6, s[0:1]
	v_and_b32_e32 v6, 0xffffff00, v6
	v_or_b32_e32 v47, 0xeb, v6
	v_not_b32_e32 v6, v38
	v_or_b32_e32 v8, 0x80000000, v38
	v_cndmask_b32_e32 v6, v8, v6, vcc
	v_and_b32_e32 v6, 0xffffff00, v6
	v_or_b32_e32 v48, 0xea, v6
	v_not_b32_e32 v6, v37
	v_or_b32_e32 v8, 0x80000000, v37
	v_cmp_gt_i32_e64 s[0:1], 0, v37
	v_cmp_gt_i32_e32 vcc, 0, v36
	v_and_b32_e32 v35, 0x7fffff80, v19
	v_cndmask_b32_e64 v6, v8, v6, s[0:1]
	v_and_b32_e32 v6, 0xffffff00, v6
	v_or_b32_e32 v49, 0xe9, v6
	v_not_b32_e32 v6, v36
	v_or_b32_e32 v8, 0x80000000, v36
	v_cndmask_b32_e32 v6, v8, v6, vcc
; DI unsigned f2ord(float f) { const unsigned u = __float_as_uint(f); return (u & 0x80000000u) ? ~u : (u | 0x80000000u); }
; DI float ord2f(unsigned o) { const unsigned u = (o & 0x80000000u) ? (o & 0x7fffffffu) : ~o; return __uint_as_float(u); }
; DI void peer_topk_phase(const bf16_t* __restrict__ qpk, const bf16_t* __restrict__ subk, int* __restrict__ eidx, float* __restrict__ gout) {
;     ...
;         for (int a = 0; a < 16; ++a)
; #pragma unroll
;             for (int b = 0; b < 16 / (a + 1); ++b) {
;                 const float cv = ord2f(top[0][a] & ~127u) + ord2f(top[1][b] & ~127u);
;                 ck[combo_row_start(a) + b] = (f2ord(cv) & ~255u) | (unsigned)(((15 - a) << 4) | (15 - b));
;             }
	v_and_b32_e32 v6, 0xffffff00, v6
	v_or_b32_e32 v50, 0xe8, v6
	v_and_b32_e32 v6, 0xffffff80, v19
	v_and_b32_e32 v8, 0xffffff80, v169
	v_cmp_gt_i32_e64 s[0:1], 0, v19
	v_xor_b32_e32 v6, -1, v6
	v_cmp_gt_i32_e32 vcc, 0, v169
	v_and_b32_e32 v36, 0x7fffff80, v169
	v_xor_b32_e32 v8, -1, v8
	v_cndmask_b32_e64 v37, v6, v35, s[0:1]
	v_cndmask_b32_e32 v6, v8, v36, vcc
	v_add_f32_e32 v8, v37, v2
	v_cmp_gt_i32_e32 vcc, 0, v8
	v_not_b32_e32 v35, v8
	v_or_b32_e32 v8, 0x80000000, v8
	v_cndmask_b32_e32 v8, v8, v35, vcc
	v_and_b32_e32 v8, 0xffffff00, v8
	v_or_b32_e32 v35, 0xfc, v8
	v_add_f32_e32 v8, v37, v4
	v_not_b32_e32 v36, v8
	v_or_b32_e32 v38, 0x80000000, v8
	v_cmp_gt_i32_e32 vcc, 0, v8
	v_and_b32_e32 v70, 0x7fffff80, v74
	s_nop 0
	v_cndmask_b32_e32 v8, v38, v36, vcc
	v_mov_b32_e32 v36, v7
	v_and_b32_e32 v8, 0xffffff00, v8
	v_pk_add_f32 v[38:39], v[6:7], v[36:37] op_sel_hi:[0,1]
	v_or_b32_e32 v51, 0xec, v8
	v_not_b32_e32 v7, v39
	v_or_b32_e32 v8, 0x80000000, v39
	v_cmp_gt_i32_e64 s[0:1], 0, v39
	v_cmp_gt_i32_e32 vcc, 0, v38
	v_and_b32_e32 v36, 0x7fffff80, v21
	v_cndmask_b32_e64 v7, v8, v7, s[0:1]
	v_and_b32_e32 v7, 0xffffff00, v7
	v_or_b32_e32 v52, 0xdc, v7
	v_not_b32_e32 v7, v38
	v_or_b32_e32 v8, 0x80000000, v38
	v_cndmask_b32_e32 v7, v8, v7, vcc
	v_and_b32_e32 v7, 0xffffff00, v7
	v_or_b32_e32 v53, 0xdb, v7
	v_and_b32_e32 v7, 0xffffff80, v21
	v_cmp_gt_i32_e64 s[0:1], 0, v21
	v_xor_b32_e32 v7, -1, v7
	v_and_b32_e32 v8, 0xffffff80, v167
	v_cndmask_b32_e64 v39, v7, v36, s[0:1]
	v_cmp_gt_i32_e32 vcc, 0, v167
	v_and_b32_e32 v38, 0x7fffff80, v167
	v_xor_b32_e32 v8, -1, v8
	v_add_f32_e32 v7, v39, v2
	v_cndmask_b32_e32 v8, v8, v38, vcc
	v_cmp_gt_i32_e32 vcc, 0, v7
	v_not_b32_e32 v36, v7
	v_or_b32_e32 v7, 0x80000000, v7
	v_cndmask_b32_e32 v7, v7, v36, vcc
	v_add_f32_e32 v36, v39, v4
	v_not_b32_e32 v38, v36
	v_or_b32_e32 v40, 0x80000000, v36
	v_cmp_gt_i32_e32 vcc, 0, v36
	v_and_b32_e32 v7, 0xffffff00, v7
	v_or_b32_e32 v7, 0xfd, v7
	v_cndmask_b32_e32 v36, v40, v38, vcc
	v_and_b32_e32 v36, 0xffffff00, v36
	v_or_b32_e32 v54, 0xed, v36
	v_add_f32_e32 v36, v39, v6
	v_not_b32_e32 v38, v36
	v_or_b32_e32 v40, 0x80000000, v36
	v_cmp_gt_i32_e32 vcc, 0, v36
	s_nop 1
	v_cndmask_b32_e32 v36, v40, v38, vcc
	v_and_b32_e32 v36, 0xffffff00, v36
	v_mov_b32_e32 v38, v37
	v_or_b32_e32 v55, 0xdd, v36
	v_pk_add_f32 v[36:37], v[8:9], v[38:39] op_sel_hi:[0,1]
	v_not_b32_e32 v38, v37
	v_or_b32_e32 v40, 0x80000000, v37
	v_cmp_gt_i32_e64 s[0:1], 0, v37
	v_cmp_gt_i32_e32 vcc, 0, v36
	s_nop 0
	v_cndmask_b32_e64 v37, v40, v38, s[0:1]
	v_not_b32_e32 v38, v36
	v_or_b32_e32 v36, 0x80000000, v36
	v_cndmask_b32_e32 v36, v36, v38, vcc
	v_and_b32_e32 v36, 0xffffff00, v36
	v_or_b32_e32 v56, 0xcc, v36
	v_cmp_gt_i32_e32 vcc, 0, v166
	v_and_b32_e32 v36, 0x7fffff80, v166
	v_bitop3_b32 v38, v166, s5, v166 bitop3:0xcf
	v_cndmask_b32_e32 v57, v38, v36, vcc
	v_add_f32_e32 v36, v39, v57
	v_not_b32_e32 v38, v36
	v_or_b32_e32 v39, 0x80000000, v36
	v_cmp_gt_i32_e32 vcc, 0, v36
	v_cmp_gt_i32_e64 s[0:1], 0, v164
	v_and_b32_e32 v40, 0x7fffff80, v164
	v_cndmask_b32_e32 v36, v39, v38, vcc
	v_and_b32_e32 v36, 0xffffff00, v36
	v_or_b32_e32 v58, 0xbd, v36
	v_cmp_gt_i32_e32 vcc, 0, v165
	v_and_b32_e32 v36, 0x7fffff80, v165
	v_bitop3_b32 v38, v165, s5, v165 bitop3:0xcf
	v_cndmask_b32_e32 v59, v38, v36, vcc
	v_and_b32_e32 v36, 0xffffff80, v22
	v_and_b32_e32 v38, 0xffffff80, v164
	v_cmp_gt_i32_e32 vcc, 0, v22
	v_and_b32_e32 v39, 0x7fffff80, v22
	v_xor_b32_e32 v36, -1, v36
	v_xor_b32_e32 v38, -1, v38
	v_cndmask_b32_e64 v60, v38, v40, s[0:1]
	v_cndmask_b32_e32 v38, v36, v39, vcc
	v_add_f32_e32 v36, v38, v2
	v_cmp_gt_i32_e32 vcc, 0, v36
	v_not_b32_e32 v39, v36
	v_or_b32_e32 v36, 0x80000000, v36
	v_cndmask_b32_e32 v36, v36, v39, vcc
	v_add_f32_e32 v39, v38, v4
	v_not_b32_e32 v40, v39
	v_or_b32_e32 v41, 0x80000000, v39
	v_cmp_gt_i32_e32 vcc, 0, v39
	v_cmp_gt_i32_e64 s[0:1], 0, v162
	v_and_b32_e32 v37, 0xffffff00, v37
	v_cndmask_b32_e32 v39, v41, v40, vcc
	v_and_b32_e32 v39, 0xffffff00, v39
	v_or_b32_e32 v61, 0xee, v39
	v_add_f32_e32 v39, v38, v6
	v_not_b32_e32 v40, v39
	v_or_b32_e32 v41, 0x80000000, v39
	v_cmp_gt_i32_e32 vcc, 0, v39
	v_or_b32_e32 v37, 0xcd, v37
	v_and_b32_e32 v36, 0xffffff00, v36
	v_cndmask_b32_e32 v39, v41, v40, vcc
	v_and_b32_e32 v39, 0xffffff00, v39
	v_or_b32_e32 v62, 0xde, v39
	v_add_f32_e32 v39, v38, v8
	v_not_b32_e32 v40, v39
	v_or_b32_e32 v41, 0x80000000, v39
	v_cmp_gt_i32_e32 vcc, 0, v39
	v_or_b32_e32 v36, 0xfe, v36
	s_nop 0
	v_cndmask_b32_e32 v39, v41, v40, vcc
	v_and_b32_e32 v39, 0xffffff00, v39
	v_or_b32_e32 v63, 0xce, v39
	v_add_f32_e32 v39, v38, v57
	v_not_b32_e32 v40, v39
	v_or_b32_e32 v41, 0x80000000, v39
	v_cmp_gt_i32_e32 vcc, 0, v39
	s_nop 1
	v_cndmask_b32_e32 v39, v41, v40, vcc
	v_and_b32_e32 v39, 0xffffff00, v39
	v_or_b32_e32 v64, 0xbe, v39
	v_add_f32_e32 v39, v38, v59
	v_not_b32_e32 v40, v39
	v_or_b32_e32 v41, 0x80000000, v39
	v_cmp_gt_i32_e32 vcc, 0, v39
	s_nop 1
	v_cndmask_b32_e32 v39, v41, v40, vcc
	v_and_b32_e32 v39, 0xffffff00, v39
	v_or_b32_e32 v65, 0xae, v39
	v_add_f32_e32 v39, v38, v60
	v_not_b32_e32 v40, v39
	v_or_b32_e32 v41, 0x80000000, v39
	v_cmp_gt_i32_e32 vcc, 0, v39
	s_nop 1
	v_cndmask_b32_e32 v39, v41, v40, vcc
	v_and_b32_e32 v39, 0xffffff00, v39
	v_or_b32_e32 v66, 0x9e, v39
	v_cmp_gt_i32_e32 vcc, 0, v163
	v_and_b32_e32 v39, 0x7fffff80, v163
	v_bitop3_b32 v40, v163, s5, v163 bitop3:0xcf
	v_cndmask_b32_e32 v67, v40, v39, vcc
	v_add_f32_e32 v38, v38, v67
	v_not_b32_e32 v39, v38
	v_or_b32_e32 v40, 0x80000000, v38
	v_cmp_gt_i32_e32 vcc, 0, v38
	v_and_b32_e32 v41, 0x7fffff80, v161
	s_nop 0
	v_cndmask_b32_e32 v38, v40, v39, vcc
	v_and_b32_e32 v38, 0xffffff00, v38
; DI unsigned f2ord(float f) { const unsigned u = __float_as_uint(f); return (u & 0x80000000u) ? ~u : (u | 0x80000000u); }
; DI float ord2f(unsigned o) { const unsigned u = (o & 0x80000000u) ? (o & 0x7fffffffu) : ~o; return __uint_as_float(u); }
; DI void peer_topk_phase(const bf16_t* __restrict__ qpk, const bf16_t* __restrict__ subk, int* __restrict__ eidx, float* __restrict__ gout) {
;     ...
; #pragma unroll
;         for (int a = 0; a < 16; ++a)
; #pragma unroll
;             for (int b = 0; b < 16 / (a + 1); ++b) {
;                 const float cv = ord2f(top[0][a] & ~127u) + ord2f(top[1][b] & ~127u);
;                 ck[combo_row_start(a) + b] = (f2ord(cv) & ~255u) | (unsigned)(((15 - a) << 4) | (15 - b));
;             }
;         unsigned c0[16], c1[16], c2[16], c3[16];
; #pragma unroll
;         for (int i = 0; i < 16; ++i) { c0[i] = ck[i]; c1[i] = ck[16 + i]; c2[i] = ck[32 + i]; c3[i] = (i < 2) ? ck[48 + i] : 0u; }
; #pragma unroll
;         for (int n = 0; n < 63; ++n) { cex(c1[SORT16[n][0]], c1[SORT16[n][1]]); cex(c2[SORT16[n][0]], c2[SORT16[n][1]]); }
	v_or_b32_e32 v68, 0x8e, v38
	v_and_b32_e32 v38, 0xffffff80, v162
	v_and_b32_e32 v39, 0xffffff80, v161
	v_cmp_gt_i32_e32 vcc, 0, v161
	v_and_b32_e32 v40, 0x7fffff80, v162
	v_xor_b32_e32 v38, -1, v38
	v_xor_b32_e32 v42, -1, v39
	v_cndmask_b32_e64 v39, v38, v40, s[0:1]
	v_cndmask_b32_e32 v38, v42, v41, vcc
	v_and_b32_e32 v40, 0xffffff80, v160
	v_and_b32_e32 v41, 0xffffff80, v159
	v_cmp_gt_i32_e32 vcc, 0, v159
	v_cmp_gt_i32_e64 s[0:1], 0, v160
	v_and_b32_e32 v42, 0x7fffff80, v160
	v_xor_b32_e32 v40, -1, v40
	v_xor_b32_e32 v44, -1, v41
	v_cndmask_b32_e64 v41, v40, v42, s[0:1]
	v_cndmask_b32_e32 v40, v44, v43, vcc
	v_and_b32_e32 v42, 0xffffff80, v158
	v_and_b32_e32 v43, 0xffffff80, v157
	v_cmp_gt_i32_e32 vcc, 0, v157
	v_cmp_gt_i32_e64 s[0:1], 0, v158
	v_and_b32_e32 v44, 0x7fffff80, v158
	v_xor_b32_e32 v42, -1, v42
	v_xor_b32_e32 v46, -1, v43
	v_cndmask_b32_e64 v43, v42, v44, s[0:1]
	v_cndmask_b32_e32 v42, v46, v45, vcc
	v_cmp_gt_i32_e32 vcc, 0, v79
	v_and_b32_e32 v44, 0x7fffff80, v79
	v_bitop3_b32 v45, v79, s5, v79 bitop3:0xcf
	v_cndmask_b32_e32 v45, v45, v44, vcc
	v_and_b32_e32 v44, 0xffffff80, v20
	v_and_b32_e32 v46, 0xffffff80, v74
	v_cmp_gt_i32_e32 vcc, 0, v20
	v_xor_b32_e32 v71, -1, v44
	v_xor_b32_e32 v44, -1, v46
	v_cndmask_b32_e32 v46, v71, v69, vcc
	v_cmp_gt_i32_e64 s[0:1], 0, v74
	v_add_f32_e32 v2, v46, v2
	v_not_b32_e32 v69, v2
	v_cndmask_b32_e64 v44, v44, v70, s[0:1]
	v_or_b32_e32 v70, 0x80000000, v2
	v_cmp_gt_i32_e32 vcc, 0, v2
	v_add_f32_e32 v4, v46, v4
	v_add_f32_e32 v6, v46, v6
	v_cndmask_b32_e32 v2, v70, v69, vcc
	v_not_b32_e32 v69, v4
	v_or_b32_e32 v70, 0x80000000, v4
	v_cmp_gt_i32_e32 vcc, 0, v4
	v_add_f32_e32 v8, v46, v8
	v_add_f32_e32 v57, v46, v57
	v_cndmask_b32_e32 v4, v70, v69, vcc
	v_not_b32_e32 v69, v6
	v_or_b32_e32 v70, 0x80000000, v6
	v_cmp_gt_i32_e32 vcc, 0, v6
	v_add_f32_e32 v59, v46, v59
	v_add_f32_e32 v60, v46, v60
	v_cndmask_b32_e32 v6, v70, v69, vcc
	v_not_b32_e32 v69, v8
	v_or_b32_e32 v70, 0x80000000, v8
	v_cmp_gt_i32_e32 vcc, 0, v8
	v_add_f32_e32 v67, v46, v67
	v_pk_add_f32 v[38:39], v[46:47], v[38:39] op_sel_hi:[0,1]
	v_cndmask_b32_e32 v8, v70, v69, vcc
	v_not_b32_e32 v69, v57
	v_or_b32_e32 v70, 0x80000000, v57
	v_cmp_gt_i32_e32 vcc, 0, v57
	v_cmp_gt_i32_e64 s[0:1], 0, v39
	v_and_b32_e32 v4, 0xffffff00, v4
	v_cndmask_b32_e32 v57, v70, v69, vcc
	v_not_b32_e32 v69, v59
	v_or_b32_e32 v70, 0x80000000, v59
	v_cmp_gt_i32_e32 vcc, 0, v59
	v_and_b32_e32 v57, 0xffffff00, v57
	v_or_b32_e32 v4, 0xef, v4
	v_cndmask_b32_e32 v59, v70, v69, vcc
	v_not_b32_e32 v69, v60
	v_or_b32_e32 v70, 0x80000000, v60
	v_cmp_gt_i32_e32 vcc, 0, v60
	v_or_b32_e32 v57, 0xbf, v57
	v_and_b32_e32 v59, 0xffffff00, v59
	v_cndmask_b32_e32 v60, v70, v69, vcc
	v_not_b32_e32 v69, v67
	v_or_b32_e32 v70, 0x80000000, v67
	v_cmp_gt_i32_e32 vcc, 0, v67
	v_and_b32_e32 v60, 0xffffff00, v60
	v_or_b32_e32 v59, 0xaf, v59
	v_cndmask_b32_e32 v67, v70, v69, vcc
	v_not_b32_e32 v69, v39
	v_or_b32_e32 v70, 0x80000000, v39
	v_cndmask_b32_e64 v39, v70, v69, s[0:1]
	v_and_b32_e32 v39, 0xffffff00, v39
	v_cmp_gt_i32_e32 vcc, 0, v38
	v_or_b32_e32 v69, 0x7f, v39
	v_not_b32_e32 v39, v38
	v_or_b32_e32 v38, 0x80000000, v38
	v_cndmask_b32_e32 v38, v38, v39, vcc
	v_and_b32_e32 v38, 0xffffff00, v38
	v_or_b32_e32 v70, 0x6f, v38
	v_pk_add_f32 v[38:39], v[46:47], v[40:41] op_sel_hi:[0,1]
	v_not_b32_e32 v40, v39
	v_or_b32_e32 v41, 0x80000000, v39
	v_cmp_gt_i32_e64 s[0:1], 0, v39
	v_cmp_gt_i32_e32 vcc, 0, v38
	v_or_b32_e32 v60, 0x9f, v60
	v_cndmask_b32_e64 v39, v41, v40, s[0:1]
	v_and_b32_e32 v39, 0xffffff00, v39
	v_or_b32_e32 v40, 0x5f, v39
	v_not_b32_e32 v39, v38
	v_or_b32_e32 v38, 0x80000000, v38
	v_cndmask_b32_e32 v38, v38, v39, vcc
	v_and_b32_e32 v38, 0xffffff00, v38
	v_or_b32_e32 v41, 0x4f, v38
	v_pk_add_f32 v[38:39], v[46:47], v[42:43] op_sel_hi:[0,1]
	v_not_b32_e32 v42, v39
	v_or_b32_e32 v43, 0x80000000, v39
	v_cmp_gt_i32_e64 s[0:1], 0, v39
	v_cmp_gt_i32_e32 vcc, 0, v38
	v_and_b32_e32 v6, 0xffffff00, v6
	v_cndmask_b32_e64 v39, v43, v42, s[0:1]
	v_and_or_b32 v42, v39, s54, 63
	v_not_b32_e32 v39, v38
	v_or_b32_e32 v38, 0x80000000, v38
	v_cndmask_b32_e32 v38, v38, v39, vcc
	v_and_or_b32 v43, v38, s54, 47
	v_pk_add_f32 v[38:39], v[46:47], v[44:45] op_sel_hi:[0,1]
	v_not_b32_e32 v44, v39
	v_or_b32_e32 v45, 0x80000000, v39
	v_cmp_gt_i32_e64 s[0:1], 0, v39
	v_cmp_gt_i32_e32 vcc, 0, v38
	v_min_u32_e32 v46, v56, v57
	v_cndmask_b32_e64 v39, v45, v44, s[0:1]
	v_not_b32_e32 v44, v38
	v_or_b32_e32 v38, 0x80000000, v38
	v_cndmask_b32_e32 v38, v38, v44, vcc
	v_max_u32_e32 v44, v4, v61
	v_min_u32_e32 v4, v4, v61
	v_max_u32_e32 v45, v56, v57
	v_max_u32_e32 v56, v54, v51
	v_min_u32_e32 v51, v54, v51
	v_max_u32_e32 v54, v64, v58
	v_min_u32_e32 v57, v64, v58
	v_max_u32_e32 v58, v44, v56
	v_min_u32_e32 v44, v44, v56
	v_max_u32_e32 v56, v45, v54
	v_min_u32_e32 v45, v45, v54
	v_max_u32_e32 v54, v4, v51
	v_min_u32_e32 v4, v4, v51
	v_max_u32_e32 v51, v46, v57
	v_min_u32_e32 v46, v46, v57
	v_max_u32_e32 v57, v54, v44
	v_min_u32_e32 v44, v54, v44
	v_max_u32_e32 v54, v51, v45
	v_min_u32_e32 v45, v51, v45
	v_max_u32_e32 v51, v47, v48
	v_min_u32_e32 v47, v47, v48
	v_max_u32_e32 v48, v59, v65
	v_min_u32_e32 v59, v59, v65
	v_max_u32_e32 v61, v49, v50
	v_min_u32_e32 v49, v49, v50
	v_max_u32_e32 v50, v60, v66
	v_min_u32_e32 v60, v60, v66
	v_max_u32_e32 v64, v51, v61
	v_min_u32_e32 v51, v51, v61
	v_max_u32_e32 v61, v48, v50
	v_min_u32_e32 v48, v48, v50
	v_max_u32_e32 v50, v47, v49
	v_min_u32_e32 v47, v47, v49
	v_max_u32_e32 v49, v59, v60
	v_min_u32_e32 v59, v59, v60
	v_max_u32_e32 v60, v50, v51
	v_min_u32_e32 v50, v50, v51
	v_max_u32_e32 v51, v49, v48
	v_min_u32_e32 v48, v49, v48
	v_max_u32_e32 v49, v58, v64
; DI void merge_top16(unsigned (&A)[16], const unsigned (&B)[16]) {
; #pragma unroll
;     for (int i = 0; i < 16; ++i) A[i] = max(A[i], B[15 - i]);
; #pragma unroll
;     for (int n = 0; n < 32; ++n) cex(A[BMERGE16[n][0]], A[BMERGE16[n][1]]);
; }
; DI void peer_topk_phase(const bf16_t* __restrict__ qpk, const bf16_t* __restrict__ subk, int* __restrict__ eidx, float* __restrict__ gout) {
;     ...
; #pragma unroll
;         for (int n = 0; n < 63; ++n) { cex(c1[SORT16[n][0]], c1[SORT16[n][1]]); cex(c2[SORT16[n][0]], c2[SORT16[n][1]]); }
;         merge_top16(c0, c1); merge_top16(c2, c3); merge_top16(c0, c2);
	v_min_u32_e32 v58, v58, v64
	v_max_u32_e32 v64, v56, v61
	v_min_u32_e32 v56, v56, v61
	v_max_u32_e32 v61, v44, v50
	v_min_u32_e32 v44, v44, v50
	v_max_u32_e32 v50, v45, v48
	v_and_b32_e32 v67, 0xffffff00, v67
	v_min_u32_e32 v45, v45, v48
	v_max_u32_e32 v48, v61, v58
	v_min_u32_e32 v58, v61, v58
	v_max_u32_e32 v61, v50, v56
	v_min_u32_e32 v50, v50, v56
	v_max_u32_e32 v56, v57, v60
	v_min_u32_e32 v57, v57, v60
	v_max_u32_e32 v60, v54, v51
	v_min_u32_e32 v51, v54, v51
	v_max_u32_e32 v54, v4, v47
	v_min_u32_e32 v4, v4, v47
	v_max_u32_e32 v47, v46, v59
	v_or_b32_e32 v6, 0xdf, v6
	v_or_b32_e32 v67, 0x8f, v67
	v_min_u32_e32 v46, v46, v59
	v_max_u32_e32 v59, v54, v57
	v_min_u32_e32 v54, v54, v57
	v_max_u32_e32 v57, v47, v51
	v_min_u32_e32 v47, v47, v51
	v_and_b32_e32 v8, 0xffffff00, v8
	v_max_u32_e32 v51, v56, v48
	v_min_u32_e32 v48, v56, v48
	v_max_u32_e32 v56, v60, v61
	v_min_u32_e32 v60, v60, v61
	v_max_u32_e32 v61, v59, v58
	v_min_u32_e32 v58, v59, v58
	v_max_u32_e32 v59, v57, v50
	v_min_u32_e32 v50, v57, v50
	v_max_u32_e32 v57, v54, v44
	v_min_u32_e32 v44, v54, v44
	v_max_u32_e32 v54, v47, v45
	v_min_u32_e32 v45, v47, v45
	v_max_u32_e32 v47, v6, v62
	v_min_u32_e32 v6, v6, v62
	v_max_u32_e32 v62, v67, v68
	v_min_u32_e32 v65, v67, v68
	v_max_u32_e32 v66, v55, v52
	v_min_u32_e32 v52, v55, v52
	v_max_u32_e32 v55, v69, v70
	v_min_u32_e32 v67, v69, v70
	v_or_b32_e32 v8, 0xcf, v8
	v_max_u32_e32 v68, v47, v66
	v_min_u32_e32 v47, v47, v66
	v_max_u32_e32 v66, v62, v55
	v_min_u32_e32 v55, v62, v55
	v_max_u32_e32 v62, v6, v52
	v_min_u32_e32 v6, v6, v52
	v_max_u32_e32 v52, v65, v67
	v_min_u32_e32 v65, v65, v67
	v_max_u32_e32 v67, v62, v47
	v_min_u32_e32 v47, v62, v47
	v_max_u32_e32 v62, v52, v55
	v_min_u32_e32 v52, v52, v55
	v_max_u32_e32 v55, v53, v8
	v_min_u32_e32 v8, v53, v8
	v_max_u32_e32 v53, v40, v41
	v_min_u32_e32 v40, v40, v41
	v_max_u32_e32 v41, v63, v37
	v_min_u32_e32 v37, v63, v37
	v_max_u32_e32 v63, v42, v43
	v_min_u32_e32 v42, v42, v43
	v_max_u32_e32 v43, v55, v41
	v_min_u32_e32 v41, v55, v41
	v_max_u32_e32 v55, v53, v63
	v_min_u32_e32 v53, v53, v63
	v_max_u32_e32 v63, v8, v37
	v_min_u32_e32 v8, v8, v37
	v_max_u32_e32 v37, v40, v42
	v_min_u32_e32 v40, v40, v42
	v_max_u32_e32 v42, v63, v41
	v_min_u32_e32 v41, v63, v41
	v_max_u32_e32 v63, v37, v53
	v_min_u32_e32 v37, v37, v53
	v_max_u32_e32 v53, v68, v43
	v_min_u32_e32 v43, v68, v43
	v_max_u32_e32 v68, v66, v55
	v_min_u32_e32 v55, v66, v55
	v_max_u32_e32 v66, v47, v41
	v_min_u32_e32 v41, v47, v41
	v_max_u32_e32 v47, v52, v37
	v_min_u32_e32 v37, v52, v37
	v_max_u32_e32 v52, v66, v43
	v_min_u32_e32 v43, v66, v43
	v_max_u32_e32 v66, v47, v55
	v_min_u32_e32 v47, v47, v55
	v_max_u32_e32 v55, v67, v42
	v_min_u32_e32 v42, v67, v42
	v_max_u32_e32 v67, v62, v63
	v_min_u32_e32 v62, v62, v63
	v_max_u32_e32 v63, v6, v8
	v_min_u32_e32 v6, v6, v8
	v_max_u32_e32 v8, v65, v40
	v_min_u32_e32 v40, v65, v40
	v_max_u32_e32 v65, v63, v42
	v_min_u32_e32 v42, v63, v42
	v_max_u32_e32 v63, v8, v62
	v_min_u32_e32 v8, v8, v62
	v_max_u32_e32 v62, v55, v52
	v_min_u32_e32 v52, v55, v52
	v_max_u32_e32 v55, v67, v66
	v_min_u32_e32 v66, v67, v66
	v_max_u32_e32 v67, v65, v43
	v_min_u32_e32 v43, v65, v43
	v_max_u32_e32 v65, v63, v47
	v_min_u32_e32 v47, v63, v47
	v_max_u32_e32 v63, v42, v41
	v_min_u32_e32 v41, v42, v41
	v_max_u32_e32 v42, v8, v37
	v_min_u32_e32 v8, v8, v37
	v_min_u32_e32 v37, v49, v53
	v_max_u32_e32 v69, v64, v68
	v_min_u32_e32 v64, v64, v68
	v_max_u32_e32 v68, v58, v43
	v_min_u32_e32 v43, v58, v43
	v_max_u32_e32 v58, v50, v47
	v_min_u32_e32 v47, v50, v47
	v_max_u32_e32 v50, v68, v37
	v_min_u32_e32 v37, v68, v37
	v_max_u32_e32 v68, v58, v64
	v_min_u32_e32 v58, v58, v64
	v_max_u32_e32 v64, v48, v52
	v_min_u32_e32 v48, v48, v52
	v_max_u32_e32 v52, v60, v66
	v_min_u32_e32 v60, v60, v66
	v_max_u32_e32 v66, v44, v41
	v_min_u32_e32 v41, v44, v41
	v_max_u32_e32 v44, v45, v8
	v_min_u32_e32 v8, v45, v8
	v_max_u32_e32 v45, v66, v48
	v_min_u32_e32 v48, v66, v48
	v_max_u32_e32 v66, v44, v60
	v_min_u32_e32 v44, v44, v60
	v_max_u32_e32 v60, v64, v50
	v_min_u32_e32 v50, v64, v50
	v_max_u32_e32 v64, v52, v68
	v_min_u32_e32 v52, v52, v68
	v_max_u32_e32 v68, v45, v37
	v_min_u32_e32 v37, v45, v37
	v_max_u32_e32 v45, v66, v58
	v_min_u32_e32 v58, v66, v58
	v_max_u32_e32 v66, v48, v43
	v_min_u32_e32 v43, v48, v43
	v_max_u32_e32 v48, v44, v47
	v_min_u32_e32 v44, v44, v47
	v_max_u32_e32 v47, v51, v62
	v_min_u32_e32 v51, v51, v62
	v_max_u32_e32 v62, v56, v55
	v_min_u32_e32 v55, v56, v55
	v_max_u32_e32 v56, v57, v63
	v_min_u32_e32 v57, v57, v63
	v_max_u32_e32 v63, v54, v42
	v_min_u32_e32 v42, v54, v42
	v_max_u32_e32 v54, v56, v51
	v_min_u32_e32 v51, v56, v51
	v_max_u32_e32 v56, v63, v55
	v_min_u32_e32 v55, v63, v55
	v_max_u32_e32 v63, v61, v67
	v_min_u32_e32 v61, v61, v67
	v_max_u32_e32 v67, v59, v65
	v_min_u32_e32 v59, v59, v65
	v_max_u32_e32 v65, v4, v6
	v_min_u32_e32 v4, v4, v6
	v_max_u32_e32 v6, v46, v40
	v_min_u32_e32 v40, v46, v40
	v_max_u32_e32 v46, v65, v61
	v_min_u32_e32 v61, v65, v61
	v_max_u32_e32 v65, v6, v59
	v_min_u32_e32 v6, v6, v59
	v_max_u32_e32 v59, v63, v54
	v_min_u32_e32 v54, v63, v54
	v_max_u32_e32 v63, v67, v56
	v_min_u32_e32 v56, v67, v56
	v_max_u32_e32 v67, v46, v51
	v_min_u32_e32 v46, v46, v51
	v_max_u32_e32 v51, v65, v55
	v_min_u32_e32 v55, v65, v55
	v_max_u32_e32 v65, v61, v57
	v_min_u32_e32 v57, v61, v57
	v_max_u32_e32 v61, v6, v42
	v_min_u32_e32 v6, v6, v42
	v_or_b32_e32 v2, 0xff, v2
	v_and_or_b32 v39, v39, s54, 31
	v_and_or_b32 v38, v38, s54, 15
	v_min_u32_e32 v42, v47, v60
	v_max_u32_e32 v70, v62, v64
	v_min_u32_e32 v62, v62, v64
	v_min_u32_e32 v64, v59, v50
	v_max_u32_e32 v71, v63, v52
	v_min_u32_e32 v52, v63, v52
; DI float ord2f(unsigned o) { const unsigned u = (o & 0x80000000u) ? (o & 0x7fffffffu) : ~o; return __uint_as_float(u); }
; DI void peer_topk_phase(const bf16_t* __restrict__ qpk, const bf16_t* __restrict__ subk, int* __restrict__ eidx, float* __restrict__ gout) {
;     ...
;         merge_top16(c0, c1); merge_top16(c2, c3); merge_top16(c0, c2);
;         float sv[16]; int se[16];
; #pragma unroll
;         for (int rd = 0; rd < 16; ++rd) {
;             const unsigned m = c0[rd];
;             const int asel = 15 - (int)((m >> 4) & 15u), bsel = 15 - (int)(m & 15u);
;             unsigned ka = top[0][0], kb = top[1][0];
; #pragma unroll
;             for (int i = 1; i < 16; ++i) { ka = (asel == i) ? top[0][i] : ka; kb = (bsel == i) ? top[1][i] : kb; }
;             sv[rd] = ord2f(ka & ~127u) + ord2f(kb & ~127u);
;             se[rd] = (127 - (int)(ka & 127u)) * 128 + (127 - (int)(kb & 127u));
;         }
	v_min_u32_e32 v63, v54, v68
	v_max_u32_e32 v72, v56, v45
	v_min_u32_e32 v45, v56, v45
	v_min_u32_e32 v56, v67, v37
	v_max_u32_e32 v73, v51, v58
	v_min_u32_e32 v51, v51, v58
	v_min_u32_e32 v58, v46, v66
	v_max_u32_e32 v82, v55, v48
	v_min_u32_e32 v48, v55, v48
	v_min_u32_e32 v55, v65, v43
	v_max_u32_e32 v83, v61, v44
	v_min_u32_e32 v44, v61, v44
	v_min_u32_e32 v61, v57, v41
	v_max_u32_e32 v183, v6, v8
	v_min_u32_e32 v6, v6, v8
	v_max_u32_e32 v2, v2, v4
	v_max_u32_e32 v4, v36, v61
	v_max3_u32 v7, v7, v57, v41
	v_max_u32_e32 v8, v35, v55
	v_max3_u32 v23, v23, v65, v43
	v_max_u32_e32 v24, v24, v58
	v_max3_u32 v34, v34, v46, v66
	v_max_u32_e32 v25, v25, v56
	v_max3_u32 v26, v26, v67, v37
	v_max_u32_e32 v27, v27, v63
	v_max3_u32 v28, v28, v54, v68
	v_max_u32_e32 v29, v29, v64
	v_max3_u32 v30, v30, v59, v50
	v_max_u32_e32 v31, v31, v42
	v_max3_u32 v32, v32, v47, v60
	v_max3_u32 v33, v33, v49, v53
	v_max_u32_e32 v6, v6, v38
	v_max_u32_e32 v38, v40, v39
	v_max_u32_e32 v35, v2, v26
	v_min_u32_e32 v2, v2, v26
	v_max_u32_e32 v26, v4, v27
	v_min_u32_e32 v4, v4, v27
	v_max_u32_e32 v27, v7, v28
	v_min_u32_e32 v7, v7, v28
	v_max_u32_e32 v28, v8, v29
	v_min_u32_e32 v8, v8, v29
	v_max_u32_e32 v29, v23, v30
	v_min_u32_e32 v23, v23, v30
	v_max_u32_e32 v30, v24, v31
	v_min_u32_e32 v24, v24, v31
	v_max_u32_e32 v31, v34, v32
	v_min_u32_e32 v32, v34, v32
	v_max_u32_e32 v34, v25, v33
	v_min_u32_e32 v25, v25, v33
	v_max_u32_e32 v39, v69, v51
	v_min_u32_e32 v40, v69, v51
	v_max_u32_e32 v49, v70, v82
	v_min_u32_e32 v50, v70, v82
	v_max_u32_e32 v51, v62, v48
	v_min_u32_e32 v48, v62, v48
	v_max_u32_e32 v53, v71, v83
	v_min_u32_e32 v54, v71, v83
	v_max_u32_e32 v55, v52, v44
	v_min_u32_e32 v44, v52, v44
	v_max_u32_e32 v52, v72, v183
	v_min_u32_e32 v56, v72, v183
	v_max_u32_e32 v57, v45, v6
	v_min_u32_e32 v6, v45, v6
	v_max_u32_e32 v45, v73, v38
	v_min_u32_e32 v38, v73, v38
	v_max_u32_e32 v33, v35, v29
	v_min_u32_e32 v29, v35, v29
	v_max_u32_e32 v35, v26, v30
	v_min_u32_e32 v26, v26, v30
	v_max_u32_e32 v30, v27, v31
	v_min_u32_e32 v27, v27, v31
	v_max_u32_e32 v31, v28, v34
	v_min_u32_e32 v28, v28, v34
	v_max_u32_e32 v34, v2, v23
	v_min_u32_e32 v2, v2, v23
	v_max_u32_e32 v23, v4, v24
	v_min_u32_e32 v4, v4, v24
	v_max_u32_e32 v24, v7, v32
	v_min_u32_e32 v7, v7, v32
	v_max_u32_e32 v32, v8, v25
	v_min_u32_e32 v8, v8, v25
	v_max_u32_e32 v58, v39, v55
	v_min_u32_e32 v39, v39, v55
	v_max_u32_e32 v55, v49, v52
	v_min_u32_e32 v49, v49, v52
	v_max_u32_e32 v52, v51, v57
	v_min_u32_e32 v51, v51, v57
	v_max_u32_e32 v57, v53, v45
	v_min_u32_e32 v45, v53, v45
	v_max_u32_e32 v53, v40, v44
	v_min_u32_e32 v40, v40, v44
	v_max_u32_e32 v44, v50, v56
	v_min_u32_e32 v50, v50, v56
	v_max_u32_e32 v56, v48, v6
	v_min_u32_e32 v6, v48, v6
	v_max_u32_e32 v48, v54, v38
	v_min_u32_e32 v38, v54, v38
	v_max_u32_e32 v25, v33, v30
	v_min_u32_e32 v30, v33, v30
	v_max_u32_e32 v33, v35, v31
	v_min_u32_e32 v31, v35, v31
	v_max_u32_e32 v35, v29, v27
	v_min_u32_e32 v27, v29, v27
	v_max_u32_e32 v29, v26, v28
	v_min_u32_e32 v26, v26, v28
	v_max_u32_e32 v28, v34, v24
	v_min_u32_e32 v24, v34, v24
	v_max_u32_e32 v34, v23, v32
	v_min_u32_e32 v23, v23, v32
	v_max_u32_e32 v32, v2, v7
	v_min_u32_e32 v2, v2, v7
	v_max_u32_e32 v7, v4, v8
	v_min_u32_e32 v4, v4, v8
	v_max_u32_e32 v54, v58, v52
	v_min_u32_e32 v52, v58, v52
	v_max_u32_e32 v58, v55, v57
	v_min_u32_e32 v55, v55, v57
	v_max_u32_e32 v57, v39, v51
	v_min_u32_e32 v39, v39, v51
	v_max_u32_e32 v51, v49, v45
	v_min_u32_e32 v45, v49, v45
	v_max_u32_e32 v49, v53, v56
	v_min_u32_e32 v53, v53, v56
	v_max_u32_e32 v56, v44, v48
	v_min_u32_e32 v44, v44, v48
	v_max_u32_e32 v48, v40, v6
	v_min_u32_e32 v6, v40, v6
	v_max_u32_e32 v40, v50, v38
	v_min_u32_e32 v38, v50, v38
	v_min_u32_e32 v8, v25, v33
	v_min_u32_e32 v36, v30, v31
	v_min_u32_e32 v37, v35, v29
	v_min_u32_e32 v41, v27, v26
	v_min_u32_e32 v42, v28, v34
	v_min_u32_e32 v43, v24, v23
	v_min_u32_e32 v46, v32, v7
	v_min_u32_e32 v47, v2, v4
	v_min_u32_e32 v50, v54, v58
	v_min_u32_e32 v59, v52, v55
	v_min_u32_e32 v60, v57, v51
	v_min_u32_e32 v61, v39, v45
	v_min_u32_e32 v62, v49, v56
	v_min_u32_e32 v63, v53, v44
	v_min_u32_e32 v64, v48, v40
	v_min_u32_e32 v65, v6, v38
	v_max3_u32 v25, v25, v33, v65
	v_max3_u32 v6, v8, v6, v38
	v_max3_u32 v8, v30, v31, v64
	v_max3_u32 v30, v36, v48, v40
	v_max3_u32 v29, v35, v29, v63
	v_max3_u32 v31, v37, v53, v44
	v_max3_u32 v26, v27, v26, v62
	v_max3_u32 v27, v41, v49, v56
	v_max3_u32 v28, v28, v34, v61
	v_max3_u32 v33, v42, v39, v45
	v_max3_u32 v23, v24, v23, v60
	v_max3_u32 v24, v43, v57, v51
	v_max3_u32 v7, v32, v7, v59
	v_max3_u32 v32, v46, v52, v55
	v_max3_u32 v2, v2, v4, v50
	v_max3_u32 v4, v47, v54, v58
	v_max_u32_e32 v34, v25, v28
	v_min_u32_e32 v25, v25, v28
	v_max_u32_e32 v28, v6, v33
	v_min_u32_e32 v6, v6, v33
	v_max_u32_e32 v33, v8, v23
	v_min_u32_e32 v8, v8, v23
	v_max_u32_e32 v23, v30, v24
	v_min_u32_e32 v24, v30, v24
	v_max_u32_e32 v30, v29, v7
	v_min_u32_e32 v7, v29, v7
	v_max_u32_e32 v29, v31, v32
	v_min_u32_e32 v31, v31, v32
	v_max_u32_e32 v32, v26, v2
	v_min_u32_e32 v2, v26, v2
	v_max_u32_e32 v26, v27, v4
	v_min_u32_e32 v4, v27, v4
	v_max_u32_e32 v27, v34, v30
	v_min_u32_e32 v30, v34, v30
	v_max_u32_e32 v34, v28, v29
	v_min_u32_e32 v28, v28, v29
	v_max_u32_e32 v29, v33, v32
	v_min_u32_e32 v32, v33, v32
	v_max_u32_e32 v33, v23, v26
	v_min_u32_e32 v23, v23, v26
	v_max_u32_e32 v26, v25, v7
	v_min_u32_e32 v7, v25, v7
	v_max_u32_e32 v25, v6, v31
	v_min_u32_e32 v6, v6, v31
	v_max_u32_e32 v31, v8, v2
	v_min_u32_e32 v2, v8, v2
	v_max_u32_e32 v8, v24, v4
	v_min_u32_e32 v4, v24, v4
	v_max_u32_e32 v24, v27, v29
	v_min_u32_e32 v27, v27, v29
	v_max_u32_e32 v29, v34, v33
	v_min_u32_e32 v33, v34, v33
	v_max_u32_e32 v34, v30, v32
	v_min_u32_e32 v30, v30, v32
	v_max_u32_e32 v32, v28, v23
	v_min_u32_e32 v23, v28, v23
	v_max_u32_e32 v28, v26, v31
	v_min_u32_e32 v26, v26, v31
	v_max_u32_e32 v31, v25, v8
	v_min_u32_e32 v8, v25, v8
	v_max_u32_e32 v25, v7, v2
	v_min_u32_e32 v7, v7, v2
	v_max_u32_e32 v35, v6, v4
	v_min_u32_e32 v4, v6, v4
	v_min_u32_e32 v6, v24, v29
	v_max_u32_e32 v2, v24, v29
	v_max_u32_e32 v29, v34, v32
	v_min_u32_e32 v32, v34, v32
	v_max_u32_e32 v38, v28, v31
	v_min_u32_e32 v39, v28, v31
	v_max_u32_e32 v34, v7, v4
	v_min_u32_e32 v31, v7, v4
	v_max_u32_e32 v42, v26, v8
	v_min_u32_e32 v41, v26, v8
	v_max_u32_e32 v24, v27, v33
	v_min_u32_e32 v27, v27, v33
	v_max_u32_e32 v33, v30, v23
	v_min_u32_e32 v36, v30, v23
	v_max_u32_e32 v40, v25, v35
	v_min_u32_e32 v37, v25, v35
	v_lshrrev_b32_e32 v48, 6, v174
	v_lshlrev_b32_e32 v48, 13, v48
	v_lshl_or_b32 v48, v172, 2, v48
	v_mov_b32_e32 v49, 0xf00
	ds_write_b32 v48, v74
	ds_write_b32 v48, v79 offset:256
	ds_write_b32 v48, v157 offset:512
	ds_write_b32 v48, v158 offset:768
	ds_write_b32 v48, v159 offset:1024
	ds_write_b32 v48, v160 offset:1280
	ds_write_b32 v48, v161 offset:1536
	ds_write_b32 v48, v162 offset:1792
	s_waitcnt lgkmcnt(7)
; DI float ord2f(unsigned o) { const unsigned u = (o & 0x80000000u) ? (o & 0x7fffffffu) : ~o; return __uint_as_float(u); }
; DI void peer_topk_phase(const bf16_t* __restrict__ qpk, const bf16_t* __restrict__ subk, int* __restrict__ eidx, float* __restrict__ gout) {
;     ...
;         for (int rd = 0; rd < 16; ++rd) {
;             const unsigned m = c0[rd];
;             const int asel = 15 - (int)((m >> 4) & 15u), bsel = 15 - (int)(m & 15u);
;             unsigned ka = top[0][0], kb = top[1][0];
; #pragma unroll
;             for (int i = 1; i < 16; ++i) { ka = (asel == i) ? top[0][i] : ka; kb = (bsel == i) ? top[1][i] : kb; }
;             sv[rd] = ord2f(ka & ~127u) + ord2f(kb & ~127u);
;             se[rd] = (127 - (int)(ka & 127u)) * 128 + (127 - (int)(kb & 127u));
;         }
;         float den = 0.f;
;         const float mx0 = sv[0];
; #pragma unroll
;         for (int i = 0; i < 16; ++i) { sv[i] = __expf(sv[i] - mx0); den += sv[i]; }
;         const float inv = 1.0f / den;
;         const size_t ob = (size_t)(t0 + r) * 128 + hh * 16;
;         if (h == 0) {
; #pragma unroll
;             for (int i = 0; i < 4; ++i) { int4 v = make_int4(se[4 * i], se[4 * i + 1], se[4 * i + 2], se[4 * i + 3]); *(int4*)(eidx + ob + 4 * i) = v; }
;         } else {
; #pragma unroll
;             for (int i = 0; i < 4; ++i) { f32x4 v = {sv[4 * i] * inv, sv[4 * i + 1] * inv, sv[4 * i + 2] * inv, sv[4 * i + 3] * inv}; *(f32x4*)(gout + ob + 4 * i) = v; }
	ds_write_b32 v48, v163 offset:2048
	ds_write_b32 v48, v164 offset:2304
	ds_write_b32 v48, v165 offset:2560
	ds_write_b32 v48, v166 offset:2816
	ds_write_b32 v48, v167 offset:3072
	ds_write_b32 v48, v169 offset:3328
	ds_write_b32 v48, v182 offset:3584
	ds_write_b32 v48, v168 offset:3840
	s_waitcnt lgkmcnt(7)
	ds_write_b32 v48, v3 offset:4096
	ds_write_b32 v48, v5 offset:4352
	ds_write_b32 v48, v9 offset:4608
	ds_write_b32 v48, v10 offset:4864
	ds_write_b32 v48, v11 offset:5120
	ds_write_b32 v48, v12 offset:5376
	ds_write_b32 v48, v13 offset:5632
	ds_write_b32 v48, v14 offset:5888
	s_waitcnt lgkmcnt(7)
	ds_write_b32 v48, v15 offset:6144
	ds_write_b32 v48, v16 offset:6400
	ds_write_b32 v48, v17 offset:6656
	ds_write_b32 v48, v18 offset:6912
	ds_write_b32 v48, v19 offset:7168
	ds_write_b32 v48, v21 offset:7424
	ds_write_b32 v48, v22 offset:7680
	ds_write_b32 v48, v20 offset:7936
	s_waitcnt lgkmcnt(7)
	s_waitcnt lgkmcnt(0)
	v_lshlrev_b32_e32 v4, 8, v6
	v_and_or_b32 v4, v4, v49, v48
	ds_read_b32 v4, v4 offset:4096
	v_lshlrev_b32_e32 v6, 4, v6
	v_and_or_b32 v6, v6, v49, v48
	ds_read_b32 v6, v6
	v_lshlrev_b32_e32 v8, 4, v24
	v_and_or_b32 v8, v8, v49, v48
	ds_read_b32 v8, v8
	v_lshlrev_b32_e32 v7, 8, v24
	v_and_or_b32 v7, v7, v49, v48
	ds_read_b32 v7, v7 offset:4096
	v_lshlrev_b32_e32 v24, 4, v27
	v_and_or_b32 v24, v24, v49, v48
	ds_read_b32 v24, v24
	v_lshlrev_b32_e32 v23, 8, v27
	v_and_or_b32 v23, v23, v49, v48
	ds_read_b32 v23, v23 offset:4096
	v_lshlrev_b32_e32 v26, 4, v29
	v_and_or_b32 v26, v26, v49, v48
	ds_read_b32 v26, v26
	v_lshlrev_b32_e32 v25, 8, v29
	v_and_or_b32 v25, v25, v49, v48
	ds_read_b32 v25, v25 offset:4096
	s_waitcnt lgkmcnt(7)
	v_lshlrev_b32_e32 v28, 4, v32
	v_and_or_b32 v28, v28, v49, v48
	ds_read_b32 v28, v28
	v_lshlrev_b32_e32 v27, 8, v32
	v_and_or_b32 v27, v27, v49, v48
	ds_read_b32 v27, v27 offset:4096
	v_lshlrev_b32_e32 v30, 4, v33
	v_and_or_b32 v30, v30, v49, v48
	ds_read_b32 v30, v30
	v_lshlrev_b32_e32 v29, 8, v33
	v_and_or_b32 v29, v29, v49, v48
	ds_read_b32 v29, v29 offset:4096
	v_lshlrev_b32_e32 v33, 4, v36
	v_and_or_b32 v33, v33, v49, v48
	ds_read_b32 v33, v33
	v_lshlrev_b32_e32 v32, 8, v36
	v_and_or_b32 v32, v32, v49, v48
	ds_read_b32 v32, v32 offset:4096
	v_lshlrev_b32_e32 v36, 4, v38
	v_and_or_b32 v36, v36, v49, v48
	ds_read_b32 v36, v36
	v_lshlrev_b32_e32 v35, 8, v38
	v_and_or_b32 v35, v35, v49, v48
	ds_read_b32 v35, v35 offset:4096
	s_waitcnt lgkmcnt(7)
	v_lshlrev_b32_e32 v38, 8, v39
	v_and_or_b32 v38, v38, v49, v48
	ds_read_b32 v38, v38 offset:4096
	v_lshlrev_b32_e32 v39, 4, v39
	v_and_or_b32 v39, v39, v49, v48
	ds_read_b32 v39, v39
	v_lshlrev_b32_e32 v43, 4, v42
	v_and_or_b32 v43, v43, v49, v48
	ds_read_b32 v43, v43
	v_lshlrev_b32_e32 v42, 8, v42
	v_and_or_b32 v42, v42, v49, v48
	ds_read_b32 v42, v42 offset:4096
	v_lshlrev_b32_e32 v44, 4, v41
	v_and_or_b32 v44, v44, v49, v48
	ds_read_b32 v44, v44
	v_lshlrev_b32_e32 v41, 8, v41
	v_and_or_b32 v41, v41, v49, v48
	ds_read_b32 v41, v41 offset:4096
	v_lshlrev_b32_e32 v45, 4, v40
	v_and_or_b32 v45, v45, v49, v48
	ds_read_b32 v45, v45
	v_lshlrev_b32_e32 v40, 8, v40
	v_and_or_b32 v40, v40, v49, v48
	ds_read_b32 v40, v40 offset:4096
	s_waitcnt lgkmcnt(7)
	v_lshlrev_b32_e32 v46, 4, v37
	v_and_or_b32 v46, v46, v49, v48
	ds_read_b32 v46, v46
	v_lshlrev_b32_e32 v37, 8, v37
	v_and_or_b32 v37, v37, v49, v48
	ds_read_b32 v37, v37 offset:4096
	v_lshlrev_b32_e32 v47, 4, v34
	v_and_or_b32 v47, v47, v49, v48
	ds_read_b32 v47, v47
	v_lshlrev_b32_e32 v34, 8, v34
	v_and_or_b32 v34, v34, v49, v48
	ds_read_b32 v34, v34 offset:4096
	v_lshlrev_b32_e32 v10, 4, v2
	v_and_or_b32 v10, v10, v49, v48
	ds_read_b32 v10, v10
	v_lshlrev_b32_e32 v11, 8, v2
	v_and_or_b32 v11, v11, v49, v48
	ds_read_b32 v11, v11 offset:4096
	v_lshlrev_b32_e32 v5, 4, v31
	v_and_or_b32 v5, v5, v49, v48
	ds_read_b32 v5, v5
	v_lshlrev_b32_e32 v9, 8, v31
	v_and_or_b32 v9, v9, v49, v48
	ds_read_b32 v9, v9 offset:4096
	s_waitcnt lgkmcnt(7)
	s_waitcnt lgkmcnt(0)
	v_lshlrev_b64 v[2:3], 7, v[80:81]
	v_lshl_or_b32 v2, v156, 4, v2
	s_and_saveexec_b64 s[0:1], s[10:11]
	s_xor_b64 s[0:1], exec, s[0:1]
	s_cbranch_execz .LBB0_468
	v_and_b32_e32 v12, 0x7fffff80, v47
	v_bitop3_b32 v13, v47, s5, v47 bitop3:0xcf
	v_cmp_gt_i32_e32 vcc, 0, v47
	v_bitop3_b32 v14, v34, s5, v34 bitop3:0xcf
	v_bitop3_b32 v21, v32, s5, v32 bitop3:0xcf
	v_cndmask_b32_e32 v12, v13, v12, vcc
	v_and_b32_e32 v13, 0x7fffff80, v34
	v_cmp_gt_i32_e32 vcc, 0, v34
	v_bitop3_b32 v22, v29, s5, v29 bitop3:0xcf
	s_nop 0
	v_cndmask_b32_e32 v13, v14, v13, vcc
	v_add_f32_e32 v20, v13, v12
	v_and_b32_e32 v12, 0x7fffff80, v46
	v_bitop3_b32 v13, v46, s5, v46 bitop3:0xcf
	v_cmp_gt_i32_e32 vcc, 0, v46
	v_bitop3_b32 v14, v37, s5, v37 bitop3:0xcf
	s_nop 0
	v_cndmask_b32_e32 v12, v13, v12, vcc
	v_and_b32_e32 v13, 0x7fffff80, v37
	v_cmp_gt_i32_e32 vcc, 0, v37
	s_nop 1
	v_cndmask_b32_e32 v13, v14, v13, vcc
	v_add_f32_e32 v19, v13, v12
	v_and_b32_e32 v12, 0x7fffff80, v45
	v_bitop3_b32 v13, v45, s5, v45 bitop3:0xcf
	v_cmp_gt_i32_e32 vcc, 0, v45
	v_bitop3_b32 v14, v40, s5, v40 bitop3:0xcf
	s_nop 0
	v_cndmask_b32_e32 v12, v13, v12, vcc
	v_and_b32_e32 v13, 0x7fffff80, v40
	v_cmp_gt_i32_e32 vcc, 0, v40
	s_nop 1
	v_cndmask_b32_e32 v13, v14, v13, vcc
	v_add_f32_e32 v18, v13, v12
	v_and_b32_e32 v12, 0x7fffff80, v44
	v_bitop3_b32 v13, v44, s5, v44 bitop3:0xcf
	v_cmp_gt_i32_e32 vcc, 0, v44
	v_bitop3_b32 v14, v41, s5, v41 bitop3:0xcf
	s_nop 0
	v_cndmask_b32_e32 v12, v13, v12, vcc
	v_and_b32_e32 v13, 0x7fffff80, v41
	v_cmp_gt_i32_e32 vcc, 0, v41
	s_nop 1
	v_cndmask_b32_e32 v13, v14, v13, vcc
	v_add_f32_e32 v17, v13, v12
	v_and_b32_e32 v12, 0x7fffff80, v43
	v_bitop3_b32 v13, v43, s5, v43 bitop3:0xcf
; DI float ord2f(unsigned o) { const unsigned u = (o & 0x80000000u) ? (o & 0x7fffffffu) : ~o; return __uint_as_float(u); }
; DI void peer_topk_phase(const bf16_t* __restrict__ qpk, const bf16_t* __restrict__ subk, int* __restrict__ eidx, float* __restrict__ gout) {
;     ...
;             sv[rd] = ord2f(ka & ~127u) + ord2f(kb & ~127u);
;             se[rd] = (127 - (int)(ka & 127u)) * 128 + (127 - (int)(kb & 127u));
;         }
;         float den = 0.f;
;         const float mx0 = sv[0];
; #pragma unroll
;         for (int i = 0; i < 16; ++i) { sv[i] = __expf(sv[i] - mx0); den += sv[i]; }
;         const float inv = 1.0f / den;
;         const size_t ob = (size_t)(t0 + r) * 128 + hh * 16;
;         if (h == 0) {
; #pragma unroll
;             for (int i = 0; i < 4; ++i) { int4 v = make_int4(se[4 * i], se[4 * i + 1], se[4 * i + 2], se[4 * i + 3]); *(int4*)(eidx + ob + 4 * i) = v; }
;         } else {
; #pragma unroll
;             for (int i = 0; i < 4; ++i) { f32x4 v = {sv[4 * i] * inv, sv[4 * i + 1] * inv, sv[4 * i + 2] * inv, sv[4 * i + 3] * inv}; *(f32x4*)(gout + ob + 4 * i) = v; }
	v_cmp_gt_i32_e32 vcc, 0, v43
	v_bitop3_b32 v14, v42, s5, v42 bitop3:0xcf
	s_nop 0
	v_cndmask_b32_e32 v12, v13, v12, vcc
	v_and_b32_e32 v13, 0x7fffff80, v42
	v_cmp_gt_i32_e32 vcc, 0, v42
	s_nop 1
	v_cndmask_b32_e32 v13, v14, v13, vcc
	v_add_f32_e32 v16, v13, v12
	v_and_b32_e32 v12, 0x7fffff80, v39
	v_bitop3_b32 v13, v39, s5, v39 bitop3:0xcf
	v_cmp_gt_i32_e32 vcc, 0, v39
	v_bitop3_b32 v14, v38, s5, v38 bitop3:0xcf
	s_nop 0
	v_cndmask_b32_e32 v12, v13, v12, vcc
	v_and_b32_e32 v13, 0x7fffff80, v38
	v_cmp_gt_i32_e32 vcc, 0, v38
	s_nop 1
	v_cndmask_b32_e32 v13, v14, v13, vcc
	v_add_f32_e32 v15, v13, v12
	v_and_b32_e32 v12, 0x7fffff80, v36
	v_bitop3_b32 v13, v36, s5, v36 bitop3:0xcf
	v_cmp_gt_i32_e32 vcc, 0, v36
	v_bitop3_b32 v14, v35, s5, v35 bitop3:0xcf
	s_nop 0
	v_cndmask_b32_e32 v12, v13, v12, vcc
	v_and_b32_e32 v13, 0x7fffff80, v35
	v_cmp_gt_i32_e32 vcc, 0, v35
	s_nop 1
	v_cndmask_b32_e32 v13, v14, v13, vcc
	v_add_f32_e32 v14, v13, v12
	v_and_b32_e32 v12, 0x7fffff80, v33
	v_bitop3_b32 v13, v33, s5, v33 bitop3:0xcf
	v_cmp_gt_i32_e32 vcc, 0, v33
	s_nop 1
	v_cndmask_b32_e32 v12, v13, v12, vcc
	v_and_b32_e32 v13, 0x7fffff80, v32
	v_cmp_gt_i32_e32 vcc, 0, v32
	s_nop 1
	v_cndmask_b32_e32 v13, v21, v13, vcc
	v_add_f32_e32 v13, v13, v12
	v_and_b32_e32 v12, 0x7fffff80, v30
	v_bitop3_b32 v21, v30, s5, v30 bitop3:0xcf
	v_cmp_gt_i32_e32 vcc, 0, v30
	s_nop 1
	v_cndmask_b32_e32 v12, v21, v12, vcc
	v_and_b32_e32 v21, 0x7fffff80, v29
	v_cmp_gt_i32_e32 vcc, 0, v29
	v_and_b32_e32 v29, 0xffffff80, v9
	s_nop 0
	v_cndmask_b32_e32 v21, v22, v21, vcc
	v_add_f32_e32 v12, v21, v12
	v_and_b32_e32 v21, 0x7fffff80, v28
	v_bitop3_b32 v22, v28, s5, v28 bitop3:0xcf
	v_cmp_gt_i32_e32 vcc, 0, v28
	v_bitop3_b32 v28, v27, s5, v27 bitop3:0xcf
	s_nop 0
	v_cndmask_b32_e32 v21, v22, v21, vcc
	v_and_b32_e32 v22, 0x7fffff80, v27
	v_cmp_gt_i32_e32 vcc, 0, v27
	v_bitop3_b32 v27, v26, s5, v26 bitop3:0xcf
	s_nop 0
	v_cndmask_b32_e32 v22, v28, v22, vcc
	v_add_f32_e32 v21, v22, v21
	v_and_b32_e32 v22, 0x7fffff80, v26
	v_cmp_gt_i32_e32 vcc, 0, v26
	v_and_b32_e32 v26, 0x7fffff80, v25
	v_and_b32_e32 v28, 0xffffff80, v11
	v_cndmask_b32_e32 v22, v27, v22, vcc
	v_bitop3_b32 v27, v25, s5, v25 bitop3:0xcf
	v_cmp_gt_i32_e32 vcc, 0, v25
	s_nop 1
	v_cndmask_b32_e32 v25, v27, v26, vcc
	v_add_f32_e32 v22, v25, v22
	v_and_b32_e32 v25, 0x7fffff80, v24
	v_bitop3_b32 v26, v24, s5, v24 bitop3:0xcf
	v_cmp_gt_i32_e32 vcc, 0, v24
	v_and_b32_e32 v27, 0x7fffff80, v9
	s_nop 0
	v_cndmask_b32_e32 v24, v26, v25, vcc
	v_and_b32_e32 v25, 0x7fffff80, v23
	v_bitop3_b32 v26, v23, s5, v23 bitop3:0xcf
	v_cmp_gt_i32_e32 vcc, 0, v23
	s_nop 1
	v_cndmask_b32_e32 v23, v26, v25, vcc
	v_add_f32_e32 v23, v23, v24
	v_and_b32_e32 v24, 0x7fffff80, v8
	v_bitop3_b32 v25, v8, s5, v8 bitop3:0xcf
	v_cmp_gt_i32_e32 vcc, 0, v8
	v_and_b32_e32 v26, 0x7fffff80, v11
	s_nop 0
	v_cndmask_b32_e32 v8, v25, v24, vcc
	v_and_b32_e32 v24, 0x7fffff80, v7
	v_bitop3_b32 v25, v7, s5, v7 bitop3:0xcf
	v_cmp_gt_i32_e32 vcc, 0, v7
	s_nop 1
	v_cndmask_b32_e32 v7, v25, v24, vcc
	v_add_f32_e32 v8, v7, v8
	v_and_b32_e32 v7, 0x7fffff80, v6
	v_bitop3_b32 v24, v6, s5, v6 bitop3:0xcf
	v_cmp_gt_i32_e32 vcc, 0, v6
	v_and_b32_e32 v25, 0xffffff80, v5
	v_xor_b32_e32 v25, -1, v25
	v_cndmask_b32_e32 v6, v24, v7, vcc
	v_and_b32_e32 v7, 0x7fffff80, v4
	v_bitop3_b32 v24, v4, s5, v4 bitop3:0xcf
	v_cmp_gt_i32_e32 vcc, 0, v4
	s_nop 1
	v_cndmask_b32_e32 v4, v24, v7, vcc
	v_and_b32_e32 v7, 0xffffff80, v10
	v_add_f32_e32 v24, v4, v6
	v_and_b32_e32 v4, 0x7fffff80, v10
	v_xor_b32_e32 v7, -1, v7
	v_cmp_gt_i32_e32 vcc, 0, v10
	v_and_b32_e32 v6, 0x7fffff80, v5
	v_xor_b32_e32 v10, -1, v29
	v_cndmask_b32_e32 v7, v7, v4, vcc
	v_cmp_gt_i32_e32 vcc, 0, v5
	v_xor_b32_e32 v4, -1, v28
	s_nop 0
	v_cndmask_b32_e32 v6, v25, v6, vcc
	v_cmp_gt_i32_e32 vcc, 0, v11
	s_nop 1
	v_cndmask_b32_e32 v5, v4, v26, vcc
	v_cmp_gt_i32_e32 vcc, 0, v9
	s_nop 1
	v_cndmask_b32_e32 v4, v10, v27, vcc
	v_pk_add_f32 v[4:5], v[4:5], v[6:7]
	s_nop 0
	v_sub_f32_e32 v6, v5, v5
	v_mul_f32_e32 v6, 0x3fb8aa3b, v6
	v_sub_f32_e32 v7, v24, v5
	v_exp_f32_e32 v6, v6
	v_mul_f32_e32 v7, 0x3fb8aa3b, v7
	v_sub_f32_e32 v8, v8, v5
	v_exp_f32_e32 v7, v7
	v_mul_f32_e32 v8, 0x3fb8aa3b, v8
	v_sub_f32_e32 v9, v23, v5
	v_exp_f32_e32 v8, v8
	v_mul_f32_e32 v9, 0x3fb8aa3b, v9
	v_exp_f32_e32 v9, v9
	v_add_f32_e32 v10, 0, v6
	v_add_f32_e32 v10, v7, v10
	v_add_f32_e32 v10, v8, v10
	v_add_f32_e32 v23, v9, v10
	v_sub_f32_e32 v10, v22, v5
	v_mul_f32_e32 v10, 0x3fb8aa3b, v10
	v_sub_f32_e32 v11, v21, v5
	v_exp_f32_e32 v10, v10
	v_mul_f32_e32 v11, 0x3fb8aa3b, v11
	v_sub_f32_e32 v12, v12, v5
	v_exp_f32_e32 v11, v11
	v_mul_f32_e32 v12, 0x3fb8aa3b, v12
	v_sub_f32_e32 v13, v13, v5
	v_exp_f32_e32 v12, v12
	v_mul_f32_e32 v13, 0x3fb8aa3b, v13
	v_sub_f32_e32 v14, v14, v5
	v_exp_f32_e32 v13, v13
	v_mul_f32_e32 v14, 0x3fb8aa3b, v14
	v_sub_f32_e32 v15, v15, v5
	v_add_f32_e32 v21, v10, v23
	v_exp_f32_e32 v14, v14
	v_mul_f32_e32 v15, 0x3fb8aa3b, v15
	v_sub_f32_e32 v16, v16, v5
	v_add_f32_e32 v21, v11, v21
	v_exp_f32_e32 v15, v15
	v_mul_f32_e32 v16, 0x3fb8aa3b, v16
	v_sub_f32_e32 v17, v17, v5
	v_add_f32_e32 v21, v12, v21
	v_exp_f32_e32 v16, v16
	v_mul_f32_e32 v17, 0x3fb8aa3b, v17
	v_sub_f32_e32 v18, v18, v5
	v_add_f32_e32 v21, v13, v21
	v_exp_f32_e32 v17, v17
	v_mul_f32_e32 v18, 0x3fb8aa3b, v18
	v_sub_f32_e32 v19, v19, v5
	v_add_f32_e32 v21, v14, v21
	v_exp_f32_e32 v18, v18
	v_mul_f32_e32 v19, 0x3fb8aa3b, v19
	v_sub_f32_e32 v20, v20, v5
	v_add_f32_e32 v21, v15, v21
	v_exp_f32_e32 v19, v19
	v_mul_f32_e32 v20, 0x3fb8aa3b, v20
	v_sub_f32_e32 v4, v4, v5
	v_add_f32_e32 v21, v16, v21
	v_exp_f32_e32 v20, v20
	v_mul_f32_e32 v4, 0x3fb8aa3b, v4
	v_add_f32_e32 v22, v17, v21
	v_exp_f32_e32 v21, v4
	v_add_f32_e32 v4, v18, v22
	v_add_f32_e32 v4, v19, v4
	v_add_f32_e32 v4, v20, v4
	v_add_f32_e32 v4, v21, v4
	v_div_scale_f32 v5, s[12:13], v4, v4, 1.0
	v_rcp_f32_e32 v22, v5
	v_readlane_b32 s12, v253, 18
	v_readlane_b32 s13, v253, 19
	v_fma_f32 v23, -v5, v22, 1.0
	v_fmac_f32_e32 v22, v23, v22
	v_div_scale_f32 v23, vcc, 1.0, v4, 1.0
	v_mul_f32_e32 v24, v23, v22
	v_fma_f32 v25, -v5, v24, v23
	v_fmac_f32_e32 v24, v25, v22
	v_fma_f32 v5, -v5, v24, v23
	v_div_fmas_f32 v5, v5, v22, v24
	v_div_fixup_f32 v22, v5, v4, 1.0
	v_lshl_add_u64 v[24:25], v[2:3], 2, s[12:13]
	v_pk_mul_f32 v[4:5], v[8:9], v[22:23] op_sel_hi:[1,0]
	v_pk_mul_f32 v[2:3], v[6:7], v[22:23] op_sel_hi:[1,0]
	global_store_dwordx4 v[24:25], v[2:5], off
	s_nop 1
	v_pk_mul_f32 v[4:5], v[12:13], v[22:23] op_sel_hi:[1,0]
	v_pk_mul_f32 v[2:3], v[10:11], v[22:23] op_sel_hi:[1,0]
	global_store_dwordx4 v[24:25], v[2:5], off offset:16
	s_nop 1
	v_pk_mul_f32 v[4:5], v[16:17], v[22:23] op_sel_hi:[1,0]
	v_pk_mul_f32 v[2:3], v[14:15], v[22:23] op_sel_hi:[1,0]
	global_store_dwordx4 v[24:25], v[2:5], off offset:32
	s_nop 1
	v_pk_mul_f32 v[4:5], v[20:21], v[22:23] op_sel_hi:[1,0]
	v_pk_mul_f32 v[2:3], v[18:19], v[22:23] op_sel_hi:[1,0]
	global_store_dwordx4 v[24:25], v[2:5], off offset:48
